# GEMM K-loops: inverted priority flips (s_setprio 1 in load segments, 0 in MFMA segments) + side_gemm1 coalesced
# baseline (speedup 1.0000x reference)
; #define PG8_STAGE(bufoff, gbase, voff) do { _Pragma("unroll") for (int _i = 0; _i < 2; ++_i) \
;         __builtin_amdgcn_global_load_lds((const unsigned*)((const char*)(gbase) + (voff)[_i]), (PG8_LAS unsigned*)(lds + (bufoff) + ldsw + _i * 8192), 16, 0, 0); } while (0)
; #define PG8_LDA(dst, b, h) do { _Pragma("unroll") for (int m = 0; m < 4; ++m) _Pragma("unroll") for (int k = 0; k < 2; ++k) dst[m][k] = *(const PG8_LAS bf16x8*)(lds + PG8_SA(b, h) + aoff + m * 2048 + k * 1024); } while (0)
; #define PG8_LDB(dst, b, h) do { _Pragma("unroll") for (int n = 0; n < 2; ++n) _Pragma("unroll") for (int k = 0; k < 2; ++k) dst[n][k] = *(const PG8_LAS bf16x8*)(lds + PG8_SB(b, h) + boff + n * 2048 + k * 1024); } while (0)
; #define PG8_WAIT_V(n) asm volatile("s_waitcnt vmcnt(" #n ")" ::: "memory")
; #define PG8_WAIT_L(n) asm volatile("s_waitcnt lgkmcnt(" #n ")" ::: "memory")
; #define PG8_BAR __builtin_amdgcn_s_barrier()
; template <class Epi, class Sched, bool ALIGN_EPI = false, bool SP2 = false>
; __device__ __forceinline__ void gemm_phase(PG8_LAS unsigned char* lds, const Gemm g, const Sched& S, const Epi& E) {
;     ...
;         const bool has_next = S.next(ui + 1, nxt);
;         const char* nA = has_next ? (const char*)g.A + (size_t)nxt.pm * tstep : cA; const char* nB = has_next ? (const char*)g.Bt + (size_t)nxt.pn * tstep : cB;
;         for (int t = 0; t < nt; t += 2) {
;             const bool last = (t == nt - 2);
;             const char* a1 = cA + (size_t)(t + 1) * kstep;
;             const char* a2 = last ? nA : cA + (size_t)(t + 2) * kstep; const char* b2 = last ? nB : cB + (size_t)(t + 2) * kstep;
;             const char* a3 = a2 + kstep; const char* b3 = b2 + kstep;
;             if (last && has_next) S.a_ready(nxt);
;             if constexpr (SP2) {
;             PG8_LDB(B0, 0, 0); PG8_LDB(B1, 0, 1); PG8_SCHED; PG8_LDA(At, 0, 0); PG8_STAGE(PG8_SA(1, 1), a1 + hstep, voffA);
;             PG8_WAIT_V(8); PG8_WAIT_L(0); PG8_BAR; PG8_MMA(0, 0, At, B0); PG8_MMA(0, 1, At, B1); PG8_BAR; PG8_SCHED;
;     ...
; #pragma unroll
;         for (int a = 0; a < 2; ++a)
; #pragma unroll
;             for (int b = 0; b < 2; ++b)
; #pragma unroll
;                 for (int m = 0; m < 4; ++m)
; #pragma unroll
;                     for (int n = 0; n < 2; ++n) acc[a][b][m][n] = (f32x4){0.f, 0.f, 0.f, 0.f};
;         cur = nxt; cA = nA; cB = nB; ++ui;
.LBB0_85:
	s_ashr_i32 s29, s28, 31
	s_lshl_b64 s[26:27], s[28:29], 20
	s_add_u32 s30, s22, s26
	s_addc_u32 s31, s23, s27
	s_and_b64 s[26:27], s[36:37], exec
	s_cselect_b32 s29, s31, s41
	s_cselect_b32 s50, s30, s40
	s_ashr_i32 s19, s18, 31
	s_lshl_b64 s[26:27], s[18:19], 20
	v_readlane_b32 s34, v254, 40
	v_readlane_b32 s35, v254, 41
	s_add_u32 s34, s34, s26
	s_addc_u32 s35, s35, s27
	s_and_b64 s[26:27], s[36:37], exec
	s_cselect_b32 s19, s35, s39
	s_cselect_b32 s51, s34, s38
	s_add_u32 s52, s38, 0x100
	s_addc_u32 s53, s39, 0
	s_add_u32 s38, s40, 0x80080
	v_mov_b32_e32 v4, 0
	s_addc_u32 s39, s41, 0
	s_mov_b32 s54, -2
	v_mov_b32_e32 v5, v4
	v_mov_b32_e32 v6, v4
	v_mov_b32_e32 v7, v4
	v_mov_b32_e32 v8, v4
	v_mov_b32_e32 v9, v4
	v_mov_b32_e32 v10, v4
	v_mov_b32_e32 v11, v4
	v_mov_b32_e32 v16, v4
	v_mov_b32_e32 v17, v4
	v_mov_b32_e32 v18, v4
	v_mov_b32_e32 v19, v4
	v_mov_b32_e32 v24, v4
	v_mov_b32_e32 v25, v4
	v_mov_b32_e32 v26, v4
	v_mov_b32_e32 v27, v4
	s_waitcnt vmcnt(0)
	v_mov_b32_e32 v32, v4
	v_mov_b32_e32 v33, v4
	v_mov_b32_e32 v34, v4
	v_mov_b32_e32 v35, v4
	v_mov_b32_e32 v40, v4
	v_mov_b32_e32 v41, v4
	v_mov_b32_e32 v42, v4
	v_mov_b32_e32 v43, v4
	v_mov_b32_e32 v48, v4
	v_mov_b32_e32 v49, v4
	v_mov_b32_e32 v50, v4
	v_mov_b32_e32 v51, v4
	v_mov_b32_e32 v56, v4
	v_mov_b32_e32 v57, v4
	v_mov_b32_e32 v58, v4
	v_mov_b32_e32 v59, v4
	v_mov_b32_e32 v12, v4
	v_mov_b32_e32 v13, v4
	v_mov_b32_e32 v14, v4
	v_mov_b32_e32 v15, v4
	v_mov_b32_e32 v20, v4
	v_mov_b32_e32 v21, v4
	v_mov_b32_e32 v22, v4
	v_mov_b32_e32 v23, v4
	v_mov_b32_e32 v28, v4
	v_mov_b32_e32 v29, v4
	v_mov_b32_e32 v30, v4
	v_mov_b32_e32 v31, v4
	v_mov_b32_e32 v36, v4
	v_mov_b32_e32 v37, v4
	v_mov_b32_e32 v38, v4
	v_mov_b32_e32 v39, v4
	v_mov_b32_e32 v44, v4
	v_mov_b32_e32 v45, v4
	v_mov_b32_e32 v46, v4
	v_mov_b32_e32 v47, v4
	v_mov_b32_e32 v52, v4
	v_mov_b32_e32 v53, v4
	v_mov_b32_e32 v54, v4
	v_mov_b32_e32 v55, v4
	v_mov_b32_e32 v60, v4
	v_mov_b32_e32 v61, v4
	v_mov_b32_e32 v62, v4
	v_mov_b32_e32 v63, v4
	v_mov_b32_e32 v64, v4
	v_mov_b32_e32 v65, v4
	v_mov_b32_e32 v66, v4
	v_mov_b32_e32 v67, v4
	v_mov_b32_e32 v68, v4
	v_mov_b32_e32 v69, v4
	v_mov_b32_e32 v70, v4
	v_mov_b32_e32 v71, v4
	v_mov_b32_e32 v72, v4
	v_mov_b32_e32 v73, v4
	v_mov_b32_e32 v74, v4
	v_mov_b32_e32 v75, v4
	v_mov_b32_e32 v84, v4
	v_mov_b32_e32 v85, v4
	v_mov_b32_e32 v86, v4
	v_mov_b32_e32 v87, v4
	v_mov_b32_e32 v88, v4
	v_mov_b32_e32 v89, v4
	v_mov_b32_e32 v90, v4
	v_mov_b32_e32 v91, v4
	v_mov_b32_e32 v100, v4
	v_mov_b32_e32 v101, v4
	v_mov_b32_e32 v102, v4
	v_mov_b32_e32 v103, v4
	v_mov_b32_e32 v104, v4
	v_mov_b32_e32 v105, v4
	v_mov_b32_e32 v106, v4
	v_mov_b32_e32 v107, v4
	v_mov_b32_e32 v116, v4
	v_mov_b32_e32 v117, v4
	v_mov_b32_e32 v118, v4
	v_mov_b32_e32 v119, v4
	v_mov_b32_e32 v120, v4
	v_mov_b32_e32 v121, v4
	v_mov_b32_e32 v122, v4
	v_mov_b32_e32 v123, v4
	v_mov_b32_e32 v76, v4
	v_mov_b32_e32 v77, v4
	v_mov_b32_e32 v78, v4
	v_mov_b32_e32 v79, v4
	v_mov_b32_e32 v80, v4
	v_mov_b32_e32 v81, v4
	v_mov_b32_e32 v82, v4
	v_mov_b32_e32 v83, v4
	v_mov_b32_e32 v92, v4
	v_mov_b32_e32 v93, v4
	v_mov_b32_e32 v94, v4
	v_mov_b32_e32 v95, v4
	v_mov_b32_e32 v96, v4
	v_mov_b32_e32 v97, v4
	v_mov_b32_e32 v98, v4
	v_mov_b32_e32 v99, v4
	v_mov_b32_e32 v108, v4
	v_mov_b32_e32 v109, v4
	v_mov_b32_e32 v110, v4
	v_mov_b32_e32 v111, v4
	v_mov_b32_e32 v112, v4
	v_mov_b32_e32 v113, v4
	v_mov_b32_e32 v114, v4
	v_mov_b32_e32 v115, v4
	v_mov_b32_e32 v124, v4
	v_mov_b32_e32 v125, v4
	v_mov_b32_e32 v126, v4
	v_mov_b32_e32 v127, v4
	v_mov_b32_e32 v128, v4
	v_mov_b32_e32 v129, v4
	v_mov_b32_e32 v130, v4
	v_mov_b32_e32 v131, v4
	s_setprio 1
.LBB0_86:
	s_add_u32 s26, s38, 0xfff80080
	s_addc_u32 s27, s39, -1
	s_add_i32 s55, 0, 0x10000
	s_cmp_eq_u32 s54, 28
	s_cselect_b32 s27, s29, s27
	s_cselect_b32 s26, s50, s26
	v_add_u32_e32 v142, s55, v147
	s_cselect_b32 s41, s19, s53
	s_cselect_b32 s40, s51, s52
	s_add_i32 s58, 0, 0x14000
	ds_read_b128 v[148:151], v142
	ds_read_b128 v[156:159], v142 offset:1024
	ds_read_b128 v[160:163], v142 offset:2048
	ds_read_b128 v[164:167], v142 offset:3072
	v_add_u32_e32 v142, s58, v147
	ds_read_b128 v[168:171], v142
	ds_read_b128 v[184:187], v142 offset:1024
	ds_read_b128 v[188:191], v142 offset:2048
	ds_read_b128 v[192:195], v142 offset:3072
	v_lshl_add_u64 v[144:145], s[38:39], 0, v[140:141]
	s_add_i32 m0, s25, 0xc000
	ds_read_b128 v[196:199], v155
	ds_read_b128 v[200:203], v155 offset:1024
	ds_read_b128 v[204:207], v155 offset:2048
	ds_read_b128 v[208:211], v155 offset:3072
	ds_read_b128 v[212:215], v155 offset:4096
	ds_read_b128 v[216:219], v155 offset:5120
	ds_read_b128 v[220:223], v155 offset:6144
	ds_read_b128 v[224:227], v155 offset:7168
	global_load_lds_dwordx4 v[144:145], off
	v_lshl_add_u64 v[144:145], s[38:39], 0, v[138:139]
	s_add_i32 m0, s25, 0xe000
	s_nop 0
	global_load_lds_dwordx4 v[144:145], off
	s_waitcnt vmcnt(8)
	s_waitcnt lgkmcnt(0)
	s_barrier
; #define PG8_STAGE(bufoff, gbase, voff) do { _Pragma("unroll") for (int _i = 0; _i < 2; ++_i) \
;         __builtin_amdgcn_global_load_lds((const unsigned*)((const char*)(gbase) + (voff)[_i]), (PG8_LAS unsigned*)(lds + (bufoff) + ldsw + _i * 8192), 16, 0, 0); } while (0)
; #define PG8_LDA(dst, b, h) do { _Pragma("unroll") for (int m = 0; m < 4; ++m) _Pragma("unroll") for (int k = 0; k < 2; ++k) dst[m][k] = *(const PG8_LAS bf16x8*)(lds + PG8_SA(b, h) + aoff + m * 2048 + k * 1024); } while (0)
; #define PG8_MMA(ai, bj, At, Bt) do { __builtin_amdgcn_s_setprio(1); _Pragma("unroll") for (int m = 0; m < 4; ++m) _Pragma("unroll") for (int n = 0; n < 2; ++n) _Pragma("unroll") for (int k = 0; k < 2; ++k) \
;         acc[ai][bj][m][n] = __builtin_amdgcn_mfma_f32_16x16x32_bf16(Bt[n][k], At[m][k], acc[ai][bj][m][n], 0, 0, 0); __builtin_amdgcn_s_setprio(0); } while (0)
; #define PG8_WAIT_V(n) asm volatile("s_waitcnt vmcnt(" #n ")" ::: "memory")
; #define PG8_WAIT_L(n) asm volatile("s_waitcnt lgkmcnt(" #n ")" ::: "memory")
; #define PG8_BAR __builtin_amdgcn_s_barrier()
; #define PG8_SCHED __builtin_amdgcn_sched_barrier(0)
; template <class Epi, class Sched, bool ALIGN_EPI = false, bool SP2 = false>
; __device__ __forceinline__ void gemm_phase(PG8_LAS unsigned char* lds, const Gemm g, const Sched& S, const Epi& E) {
;     ...
;             PG8_WAIT_V(8); PG8_WAIT_L(0); PG8_BAR; PG8_MMA(0, 0, At, B0); PG8_MMA(0, 1, At, B1); PG8_BAR; PG8_SCHED;
;             PG8_LDA(At, 0, 1); PG8_STAGE(PG8_SB(0, 0), b2, voffB); PG8_STAGE(PG8_SB(0, 1), b2 + hstep, voffB); PG8_STAGE(PG8_SA(0, 0), a2, voffA);
;             PG8_WAIT_V(8); PG8_WAIT_L(0); PG8_BAR; PG8_MMA(1, 0, At, B0); PG8_MMA(1, 1, At, B1); PG8_BAR; PG8_SCHED;
	s_setprio 0
	s_waitcnt lgkmcnt(0)
	v_mfma_f32_16x16x32_bf16 v[128:131], v[148:151], v[196:199], v[128:131]
	v_mfma_f32_16x16x32_bf16 v[124:127], v[160:163], v[196:199], v[124:127]
	v_mfma_f32_16x16x32_bf16 v[112:115], v[148:151], v[204:207], v[112:115]
	v_mfma_f32_16x16x32_bf16 v[108:111], v[160:163], v[204:207], v[108:111]
	v_mfma_f32_16x16x32_bf16 v[96:99], v[148:151], v[212:215], v[96:99]
	v_mfma_f32_16x16x32_bf16 v[92:95], v[160:163], v[212:215], v[92:95]
	v_mfma_f32_16x16x32_bf16 v[80:83], v[148:151], v[220:223], v[80:83]
	v_mfma_f32_16x16x32_bf16 v[76:79], v[160:163], v[220:223], v[76:79]
	v_mfma_f32_16x16x32_bf16 v[128:131], v[156:159], v[200:203], v[128:131]
	v_mfma_f32_16x16x32_bf16 v[124:127], v[164:167], v[200:203], v[124:127]
	v_mfma_f32_16x16x32_bf16 v[112:115], v[156:159], v[208:211], v[112:115]
	v_mfma_f32_16x16x32_bf16 v[108:111], v[164:167], v[208:211], v[108:111]
	v_mfma_f32_16x16x32_bf16 v[96:99], v[156:159], v[216:219], v[96:99]
	v_mfma_f32_16x16x32_bf16 v[92:95], v[164:167], v[216:219], v[92:95]
	v_mfma_f32_16x16x32_bf16 v[80:83], v[156:159], v[224:227], v[80:83]
	v_mfma_f32_16x16x32_bf16 v[76:79], v[164:167], v[224:227], v[76:79]
	v_mfma_f32_16x16x32_bf16 v[120:123], v[168:171], v[196:199], v[120:123]
	v_mfma_f32_16x16x32_bf16 v[116:119], v[188:191], v[196:199], v[116:119]
	v_mfma_f32_16x16x32_bf16 v[104:107], v[168:171], v[204:207], v[104:107]
	v_mfma_f32_16x16x32_bf16 v[100:103], v[188:191], v[204:207], v[100:103]
	v_mfma_f32_16x16x32_bf16 v[88:91], v[168:171], v[212:215], v[88:91]
	v_mfma_f32_16x16x32_bf16 v[84:87], v[188:191], v[212:215], v[84:87]
	v_mfma_f32_16x16x32_bf16 v[72:75], v[168:171], v[220:223], v[72:75]
	v_mfma_f32_16x16x32_bf16 v[68:71], v[188:191], v[220:223], v[68:71]
	v_mfma_f32_16x16x32_bf16 v[120:123], v[184:187], v[200:203], v[120:123]
	v_mfma_f32_16x16x32_bf16 v[116:119], v[192:195], v[200:203], v[116:119]
	v_mfma_f32_16x16x32_bf16 v[104:107], v[184:187], v[208:211], v[104:107]
	v_mfma_f32_16x16x32_bf16 v[100:103], v[192:195], v[208:211], v[100:103]
	v_mfma_f32_16x16x32_bf16 v[88:91], v[184:187], v[216:219], v[88:91]
	v_mfma_f32_16x16x32_bf16 v[84:87], v[192:195], v[216:219], v[84:87]
	v_mfma_f32_16x16x32_bf16 v[72:75], v[184:187], v[224:227], v[72:75]
	v_mfma_f32_16x16x32_bf16 v[68:71], v[192:195], v[224:227], v[68:71]
	s_barrier
	s_setprio 1
	s_add_i32 s55, s55, s24
	v_lshl_add_u64 v[144:145], s[40:41], 0, v[174:175]
	s_mov_b32 m0, s55
	ds_read_b128 v[196:199], v155 offset:16384
	ds_read_b128 v[200:203], v155 offset:17408
	ds_read_b128 v[204:207], v155 offset:18432
	ds_read_b128 v[208:211], v155 offset:19456
	ds_read_b128 v[212:215], v155 offset:20480
	ds_read_b128 v[216:219], v155 offset:21504
	ds_read_b128 v[220:223], v155 offset:22528
	ds_read_b128 v[224:227], v155 offset:23552
	global_load_lds_dwordx4 v[144:145], off
	s_add_i32 m0, s55, 0x2000
	s_add_u32 s56, s40, 0x80000
	v_lshl_add_u64 v[228:229], s[40:41], 0, v[132:133]
	s_addc_u32 s57, s41, 0
	s_add_i32 s55, s58, s24
	global_load_lds_dwordx4 v[228:229], off
	v_lshl_add_u64 v[230:231], s[56:57], 0, v[174:175]
	s_mov_b32 m0, s55
	v_lshl_add_u64 v[232:233], s[26:27], 0, v[134:135]
	global_load_lds_dwordx4 v[230:231], off
	v_lshl_add_u64 v[230:231], s[56:57], 0, v[132:133]
	s_add_i32 m0, s55, 0x2000
	s_nop 0
	global_load_lds_dwordx4 v[230:231], off
	v_lshl_add_u64 v[230:231], s[26:27], 0, v[136:137]
	s_mov_b32 m0, s25
	s_nop 0
	global_load_lds_dwordx4 v[230:231], off
	s_mov_b32 m0, s42
	s_nop 0
	global_load_lds_dwordx4 v[232:233], off
	s_waitcnt vmcnt(8)
	s_waitcnt lgkmcnt(0)
	s_barrier
	s_setprio 0
	s_waitcnt lgkmcnt(0)
	v_mfma_f32_16x16x32_bf16 v[64:67], v[148:151], v[196:199], v[64:67]
	v_mfma_f32_16x16x32_bf16 v[60:63], v[160:163], v[196:199], v[60:63]
	v_mfma_f32_16x16x32_bf16 v[52:55], v[148:151], v[204:207], v[52:55]
	v_mfma_f32_16x16x32_bf16 v[44:47], v[160:163], v[204:207], v[44:47]
	v_mfma_f32_16x16x32_bf16 v[36:39], v[148:151], v[212:215], v[36:39]
	v_mfma_f32_16x16x32_bf16 v[28:31], v[160:163], v[212:215], v[28:31]
	v_mfma_f32_16x16x32_bf16 v[20:23], v[148:151], v[220:223], v[20:23]
	v_mfma_f32_16x16x32_bf16 v[12:15], v[160:163], v[220:223], v[12:15]
	v_mfma_f32_16x16x32_bf16 v[64:67], v[156:159], v[200:203], v[64:67]
	v_mfma_f32_16x16x32_bf16 v[60:63], v[164:167], v[200:203], v[60:63]
	v_mfma_f32_16x16x32_bf16 v[52:55], v[156:159], v[208:211], v[52:55]
	v_mfma_f32_16x16x32_bf16 v[44:47], v[164:167], v[208:211], v[44:47]
	v_mfma_f32_16x16x32_bf16 v[36:39], v[156:159], v[216:219], v[36:39]
	v_mfma_f32_16x16x32_bf16 v[28:31], v[164:167], v[216:219], v[28:31]
	v_mfma_f32_16x16x32_bf16 v[20:23], v[156:159], v[224:227], v[20:23]
	v_mfma_f32_16x16x32_bf16 v[12:15], v[164:167], v[224:227], v[12:15]
	v_mfma_f32_16x16x32_bf16 v[56:59], v[168:171], v[196:199], v[56:59]
	v_mfma_f32_16x16x32_bf16 v[48:51], v[188:191], v[196:199], v[48:51]
	v_mfma_f32_16x16x32_bf16 v[40:43], v[168:171], v[204:207], v[40:43]
	v_mfma_f32_16x16x32_bf16 v[32:35], v[188:191], v[204:207], v[32:35]
	v_mfma_f32_16x16x32_bf16 v[24:27], v[168:171], v[212:215], v[24:27]
	v_mfma_f32_16x16x32_bf16 v[16:19], v[188:191], v[212:215], v[16:19]
	v_mfma_f32_16x16x32_bf16 v[8:11], v[168:171], v[220:223], v[8:11]
	v_mfma_f32_16x16x32_bf16 v[4:7], v[188:191], v[220:223], v[4:7]
	v_mfma_f32_16x16x32_bf16 v[56:59], v[184:187], v[200:203], v[56:59]
	v_mfma_f32_16x16x32_bf16 v[48:51], v[192:195], v[200:203], v[48:51]
	v_mfma_f32_16x16x32_bf16 v[40:43], v[184:187], v[208:211], v[40:43]
	v_mfma_f32_16x16x32_bf16 v[32:35], v[192:195], v[208:211], v[32:35]
	v_mfma_f32_16x16x32_bf16 v[24:27], v[184:187], v[216:219], v[24:27]
	v_mfma_f32_16x16x32_bf16 v[16:19], v[192:195], v[216:219], v[16:19]
	v_mfma_f32_16x16x32_bf16 v[8:11], v[184:187], v[224:227], v[8:11]
	v_mfma_f32_16x16x32_bf16 v[4:7], v[192:195], v[224:227], v[4:7]
	s_barrier
; #define PG8_STAGE(bufoff, gbase, voff) do { _Pragma("unroll") for (int _i = 0; _i < 2; ++_i) \
;         __builtin_amdgcn_global_load_lds((const unsigned*)((const char*)(gbase) + (voff)[_i]), (PG8_LAS unsigned*)(lds + (bufoff) + ldsw + _i * 8192), 16, 0, 0); } while (0)
; #define PG8_LDA(dst, b, h) do { _Pragma("unroll") for (int m = 0; m < 4; ++m) _Pragma("unroll") for (int k = 0; k < 2; ++k) dst[m][k] = *(const PG8_LAS bf16x8*)(lds + PG8_SA(b, h) + aoff + m * 2048 + k * 1024); } while (0)
; #define PG8_LDB(dst, b, h) do { _Pragma("unroll") for (int n = 0; n < 2; ++n) _Pragma("unroll") for (int k = 0; k < 2; ++k) dst[n][k] = *(const PG8_LAS bf16x8*)(lds + PG8_SB(b, h) + boff + n * 2048 + k * 1024); } while (0)
; #define PG8_MMA(ai, bj, At, Bt) do { __builtin_amdgcn_s_setprio(1); _Pragma("unroll") for (int m = 0; m < 4; ++m) _Pragma("unroll") for (int n = 0; n < 2; ++n) _Pragma("unroll") for (int k = 0; k < 2; ++k) \
;         acc[ai][bj][m][n] = __builtin_amdgcn_mfma_f32_16x16x32_bf16(Bt[n][k], At[m][k], acc[ai][bj][m][n], 0, 0, 0); __builtin_amdgcn_s_setprio(0); } while (0)
; #define PG8_WAIT_V(n) asm volatile("s_waitcnt vmcnt(" #n ")" ::: "memory")
; #define PG8_WAIT_L(n) asm volatile("s_waitcnt lgkmcnt(" #n ")" ::: "memory")
; #define PG8_BAR __builtin_amdgcn_s_barrier()
; #define PG8_SCHED __builtin_amdgcn_sched_barrier(0)
; template <class Epi, class Sched, bool ALIGN_EPI = false, bool SP2 = false>
; __device__ __forceinline__ void gemm_phase(PG8_LAS unsigned char* lds, const Gemm g, const Sched& S, const Epi& E) {
;     ...
;             PG8_WAIT_V(8); PG8_WAIT_L(0); PG8_BAR; PG8_MMA(1, 0, At, B0); PG8_MMA(1, 1, At, B1); PG8_BAR; PG8_SCHED;
;             PG8_LDB(B0, 1, 0); PG8_LDB(B1, 1, 1); PG8_SCHED; PG8_LDA(At, 1, 0); PG8_STAGE(PG8_SA(0, 1), a2 + hstep, voffA);
;             PG8_WAIT_V(8); PG8_WAIT_L(0); PG8_BAR; PG8_MMA(0, 0, At, B0); PG8_MMA(0, 1, At, B1); PG8_BAR; PG8_SCHED;
	s_setprio 1
	s_add_i32 s55, 0, 0x18000
	v_add_u32_e32 v142, s55, v147
	s_add_i32 s56, 0, 0x1c000
	ds_read_b128 v[148:151], v142
	ds_read_b128 v[156:159], v142 offset:1024
	ds_read_b128 v[160:163], v142 offset:2048
	ds_read_b128 v[164:167], v142 offset:3072
	v_add_u32_e32 v142, s56, v147
	ds_read_b128 v[168:171], v142
	ds_read_b128 v[184:187], v142 offset:1024
	ds_read_b128 v[188:191], v142 offset:2048
	ds_read_b128 v[192:195], v142 offset:3072
	s_add_u32 s26, s26, 0x80000
	s_addc_u32 s27, s27, 0
	s_mov_b32 m0, s43
	v_lshl_add_u64 v[234:235], s[26:27], 0, v[136:137]
	ds_read_b128 v[196:199], v155 offset:32768
	ds_read_b128 v[200:203], v155 offset:33792
	ds_read_b128 v[204:207], v155 offset:34816
	ds_read_b128 v[208:211], v155 offset:35840
	ds_read_b128 v[212:215], v155 offset:36864
	ds_read_b128 v[216:219], v155 offset:37888
	ds_read_b128 v[220:223], v155 offset:38912
	ds_read_b128 v[224:227], v155 offset:39936
	global_load_lds_dwordx4 v[234:235], off
	v_lshl_add_u64 v[234:235], s[26:27], 0, v[134:135]
	s_mov_b32 m0, s44
	s_nop 0
	global_load_lds_dwordx4 v[234:235], off
	s_waitcnt vmcnt(8)
	s_waitcnt lgkmcnt(0)
	s_barrier
	s_setprio 0
	s_waitcnt lgkmcnt(0)
	v_mfma_f32_16x16x32_bf16 v[128:131], v[148:151], v[196:199], v[128:131]
	v_mfma_f32_16x16x32_bf16 v[124:127], v[160:163], v[196:199], v[124:127]
	v_mfma_f32_16x16x32_bf16 v[112:115], v[148:151], v[204:207], v[112:115]
	v_mfma_f32_16x16x32_bf16 v[108:111], v[160:163], v[204:207], v[108:111]
	v_mfma_f32_16x16x32_bf16 v[96:99], v[148:151], v[212:215], v[96:99]
	v_mfma_f32_16x16x32_bf16 v[92:95], v[160:163], v[212:215], v[92:95]
	v_mfma_f32_16x16x32_bf16 v[80:83], v[148:151], v[220:223], v[80:83]
	v_mfma_f32_16x16x32_bf16 v[76:79], v[160:163], v[220:223], v[76:79]
	v_mfma_f32_16x16x32_bf16 v[128:131], v[156:159], v[200:203], v[128:131]
	v_mfma_f32_16x16x32_bf16 v[124:127], v[164:167], v[200:203], v[124:127]
	v_mfma_f32_16x16x32_bf16 v[112:115], v[156:159], v[208:211], v[112:115]
	v_mfma_f32_16x16x32_bf16 v[108:111], v[164:167], v[208:211], v[108:111]
	v_mfma_f32_16x16x32_bf16 v[96:99], v[156:159], v[216:219], v[96:99]
	v_mfma_f32_16x16x32_bf16 v[92:95], v[164:167], v[216:219], v[92:95]
	v_mfma_f32_16x16x32_bf16 v[80:83], v[156:159], v[224:227], v[80:83]
	v_mfma_f32_16x16x32_bf16 v[76:79], v[164:167], v[224:227], v[76:79]
	v_mfma_f32_16x16x32_bf16 v[120:123], v[168:171], v[196:199], v[120:123]
	v_mfma_f32_16x16x32_bf16 v[116:119], v[188:191], v[196:199], v[116:119]
	v_mfma_f32_16x16x32_bf16 v[104:107], v[168:171], v[204:207], v[104:107]
	v_mfma_f32_16x16x32_bf16 v[100:103], v[188:191], v[204:207], v[100:103]
	v_mfma_f32_16x16x32_bf16 v[88:91], v[168:171], v[212:215], v[88:91]
	v_mfma_f32_16x16x32_bf16 v[84:87], v[188:191], v[212:215], v[84:87]
	v_mfma_f32_16x16x32_bf16 v[72:75], v[168:171], v[220:223], v[72:75]
	v_mfma_f32_16x16x32_bf16 v[68:71], v[188:191], v[220:223], v[68:71]
	v_mfma_f32_16x16x32_bf16 v[120:123], v[184:187], v[200:203], v[120:123]
	v_mfma_f32_16x16x32_bf16 v[116:119], v[192:195], v[200:203], v[116:119]
	v_mfma_f32_16x16x32_bf16 v[104:107], v[184:187], v[208:211], v[104:107]
	v_mfma_f32_16x16x32_bf16 v[100:103], v[192:195], v[208:211], v[100:103]
	v_mfma_f32_16x16x32_bf16 v[88:91], v[184:187], v[216:219], v[88:91]
	v_mfma_f32_16x16x32_bf16 v[84:87], v[192:195], v[216:219], v[84:87]
	v_mfma_f32_16x16x32_bf16 v[72:75], v[184:187], v[224:227], v[72:75]
	v_mfma_f32_16x16x32_bf16 v[68:71], v[192:195], v[224:227], v[68:71]
	s_barrier
; #define PG8_STAGE(bufoff, gbase, voff) do { _Pragma("unroll") for (int _i = 0; _i < 2; ++_i) \
;         __builtin_amdgcn_global_load_lds((const unsigned*)((const char*)(gbase) + (voff)[_i]), (PG8_LAS unsigned*)(lds + (bufoff) + ldsw + _i * 8192), 16, 0, 0); } while (0)
; #define PG8_LDA(dst, b, h) do { _Pragma("unroll") for (int m = 0; m < 4; ++m) _Pragma("unroll") for (int k = 0; k < 2; ++k) dst[m][k] = *(const PG8_LAS bf16x8*)(lds + PG8_SA(b, h) + aoff + m * 2048 + k * 1024); } while (0)
; #define PG8_MMA(ai, bj, At, Bt) do { __builtin_amdgcn_s_setprio(1); _Pragma("unroll") for (int m = 0; m < 4; ++m) _Pragma("unroll") for (int n = 0; n < 2; ++n) _Pragma("unroll") for (int k = 0; k < 2; ++k) \
;         acc[ai][bj][m][n] = __builtin_amdgcn_mfma_f32_16x16x32_bf16(Bt[n][k], At[m][k], acc[ai][bj][m][n], 0, 0, 0); __builtin_amdgcn_s_setprio(0); } while (0)
; #define PG8_WAIT_V(n) asm volatile("s_waitcnt vmcnt(" #n ")" ::: "memory")
; #define PG8_WAIT_L(n) asm volatile("s_waitcnt lgkmcnt(" #n ")" ::: "memory")
; #define PG8_BAR __builtin_amdgcn_s_barrier()
; #define PG8_SCHED __builtin_amdgcn_sched_barrier(0)
; template <class Epi, class Sched, bool ALIGN_EPI = false, bool SP2 = false>
; __device__ __forceinline__ void gemm_phase(PG8_LAS unsigned char* lds, const Gemm g, const Sched& S, const Epi& E) {
;     ...
;         for (int t = 0; t < nt; t += 2) {
;             const bool last = (t == nt - 2);
;             const char* a1 = cA + (size_t)(t + 1) * kstep;
;             const char* a2 = last ? nA : cA + (size_t)(t + 2) * kstep; const char* b2 = last ? nB : cB + (size_t)(t + 2) * kstep;
;             const char* a3 = a2 + kstep; const char* b3 = b2 + kstep;
;     ...
;             PG8_WAIT_V(8); PG8_WAIT_L(0); PG8_BAR; PG8_MMA(0, 0, At, B0); PG8_MMA(0, 1, At, B1); PG8_BAR; PG8_SCHED;
;             PG8_LDA(At, 1, 1); PG8_STAGE(PG8_SB(1, 0), b3, voffB); PG8_STAGE(PG8_SB(1, 1), b3 + hstep, voffB); PG8_STAGE(PG8_SA(1, 0), a3, voffA);
;             PG8_WAIT_V(8); PG8_WAIT_L(0); PG8_BAR; PG8_MMA(1, 0, At, B0); PG8_MMA(1, 1, At, B1); PG8_BAR; PG8_SCHED;
	s_setprio 1
	s_add_i32 s26, s55, s24
	v_lshl_add_u64 v[144:145], v[144:145], 0, s[10:11]
	s_mov_b32 m0, s26
	ds_read_b128 v[196:199], v155 offset:49152
	ds_read_b128 v[200:203], v155 offset:50176
	ds_read_b128 v[204:207], v155 offset:51200
	ds_read_b128 v[208:211], v155 offset:52224
	ds_read_b128 v[212:215], v155 offset:53248
	ds_read_b128 v[216:219], v155 offset:54272
	ds_read_b128 v[220:223], v155 offset:55296
	ds_read_b128 v[224:227], v155 offset:56320
	global_load_lds_dwordx4 v[144:145], off
	s_add_i32 m0, s26, 0x2000
	s_add_u32 s26, s40, 0x80080
	v_lshl_add_u64 v[144:145], v[228:229], 0, s[10:11]
	s_addc_u32 s27, s41, 0
	s_add_i32 s40, s56, s24
	global_load_lds_dwordx4 v[144:145], off
	v_lshl_add_u64 v[144:145], s[26:27], 0, v[174:175]
	s_mov_b32 m0, s40
	s_nop 0
	global_load_lds_dwordx4 v[144:145], off
	v_lshl_add_u64 v[144:145], s[26:27], 0, v[132:133]
	s_add_i32 m0, s40, 0x2000
	s_nop 0
	global_load_lds_dwordx4 v[144:145], off
	v_lshl_add_u64 v[144:145], v[230:231], 0, s[10:11]
	s_mov_b32 m0, s20
	s_nop 0
	global_load_lds_dwordx4 v[144:145], off
	v_lshl_add_u64 v[144:145], v[232:233], 0, s[10:11]
	s_mov_b32 m0, s45
	s_nop 0
	global_load_lds_dwordx4 v[144:145], off
	s_waitcnt vmcnt(8)
	s_waitcnt lgkmcnt(0)
	s_barrier
	s_setprio 0
	s_waitcnt lgkmcnt(0)
	v_mfma_f32_16x16x32_bf16 v[64:67], v[148:151], v[196:199], v[64:67]
	v_mfma_f32_16x16x32_bf16 v[60:63], v[160:163], v[196:199], v[60:63]
	v_mfma_f32_16x16x32_bf16 v[52:55], v[148:151], v[204:207], v[52:55]
	v_mfma_f32_16x16x32_bf16 v[44:47], v[160:163], v[204:207], v[44:47]
	v_mfma_f32_16x16x32_bf16 v[36:39], v[148:151], v[212:215], v[36:39]
	v_mfma_f32_16x16x32_bf16 v[28:31], v[160:163], v[212:215], v[28:31]
	v_mfma_f32_16x16x32_bf16 v[20:23], v[148:151], v[220:223], v[20:23]
	v_mfma_f32_16x16x32_bf16 v[12:15], v[160:163], v[220:223], v[12:15]
	v_mfma_f32_16x16x32_bf16 v[64:67], v[156:159], v[200:203], v[64:67]
	v_mfma_f32_16x16x32_bf16 v[60:63], v[164:167], v[200:203], v[60:63]
	v_mfma_f32_16x16x32_bf16 v[52:55], v[156:159], v[208:211], v[52:55]
	v_mfma_f32_16x16x32_bf16 v[44:47], v[164:167], v[208:211], v[44:47]
	v_mfma_f32_16x16x32_bf16 v[36:39], v[156:159], v[216:219], v[36:39]
	v_mfma_f32_16x16x32_bf16 v[28:31], v[164:167], v[216:219], v[28:31]
	v_mfma_f32_16x16x32_bf16 v[20:23], v[156:159], v[224:227], v[20:23]
	v_mfma_f32_16x16x32_bf16 v[12:15], v[164:167], v[224:227], v[12:15]
	v_mfma_f32_16x16x32_bf16 v[56:59], v[168:171], v[196:199], v[56:59]
	v_mfma_f32_16x16x32_bf16 v[48:51], v[188:191], v[196:199], v[48:51]
	v_mfma_f32_16x16x32_bf16 v[40:43], v[168:171], v[204:207], v[40:43]
	v_mfma_f32_16x16x32_bf16 v[32:35], v[188:191], v[204:207], v[32:35]
	v_mfma_f32_16x16x32_bf16 v[24:27], v[168:171], v[212:215], v[24:27]
	v_mfma_f32_16x16x32_bf16 v[16:19], v[188:191], v[212:215], v[16:19]
	v_mfma_f32_16x16x32_bf16 v[8:11], v[168:171], v[220:223], v[8:11]
	v_mfma_f32_16x16x32_bf16 v[4:7], v[188:191], v[220:223], v[4:7]
	v_mfma_f32_16x16x32_bf16 v[56:59], v[184:187], v[200:203], v[56:59]
	v_mfma_f32_16x16x32_bf16 v[48:51], v[192:195], v[200:203], v[48:51]
	v_mfma_f32_16x16x32_bf16 v[40:43], v[184:187], v[208:211], v[40:43]
	v_mfma_f32_16x16x32_bf16 v[32:35], v[192:195], v[208:211], v[32:35]
	v_mfma_f32_16x16x32_bf16 v[24:27], v[184:187], v[216:219], v[24:27]
	v_mfma_f32_16x16x32_bf16 v[16:19], v[192:195], v[216:219], v[16:19]
	v_mfma_f32_16x16x32_bf16 v[8:11], v[184:187], v[224:227], v[8:11]
	v_mfma_f32_16x16x32_bf16 v[4:7], v[192:195], v[224:227], v[4:7]
	s_barrier
	s_setprio 1
	s_add_i32 s54, s54, 2
	s_add_u32 s52, s52, 0x100
	s_addc_u32 s53, s53, 0
	s_add_u32 s38, s38, 0x100
	s_addc_u32 s39, s39, 0
	s_cmp_gt_u32 s54, 29
	s_cbranch_scc0 .LBB0_86
	s_and_b64 vcc, exec, s[16:17]
	s_cbranch_vccz .LBB0_89
	s_barrier

; #define PG8_STAGE(bufoff, gbase, voff) do { _Pragma("unroll") for (int _i = 0; _i < 2; ++_i) \
;         __builtin_amdgcn_global_load_lds((const unsigned*)((const char*)(gbase) + (voff)[_i]), (PG8_LAS unsigned*)(lds + (bufoff) + ldsw + _i * 8192), 16, 0, 0); } while (0)
; #define PG8_LDA(dst, b, h) do { _Pragma("unroll") for (int m = 0; m < 4; ++m) _Pragma("unroll") for (int k = 0; k < 2; ++k) dst[m][k] = *(const PG8_LAS bf16x8*)(lds + PG8_SA(b, h) + aoff + m * 2048 + k * 1024); } while (0)
; #define PG8_LDB(dst, b, h) do { _Pragma("unroll") for (int n = 0; n < 2; ++n) _Pragma("unroll") for (int k = 0; k < 2; ++k) dst[n][k] = *(const PG8_LAS bf16x8*)(lds + PG8_SB(b, h) + boff + n * 2048 + k * 1024); } while (0)
; #define PG8_WAIT_V(n) asm volatile("s_waitcnt vmcnt(" #n ")" ::: "memory")
; #define PG8_WAIT_L(n) asm volatile("s_waitcnt lgkmcnt(" #n ")" ::: "memory")
; #define PG8_BAR __builtin_amdgcn_s_barrier()
; template <class Epi, class Sched, bool ALIGN_EPI = false, bool SP2 = false>
; __device__ __forceinline__ void gemm_phase(PG8_LAS unsigned char* lds, const Gemm g, const Sched& S, const Epi& E) {
;     ...
;         const bool has_next = S.next(ui + 1, nxt);
;         const char* nA = has_next ? (const char*)g.A + (size_t)nxt.pm * tstep : cA; const char* nB = has_next ? (const char*)g.Bt + (size_t)nxt.pn * tstep : cB;
;         for (int t = 0; t < nt; t += 2) {
;             const bool last = (t == nt - 2);
;             const char* a1 = cA + (size_t)(t + 1) * kstep;
;             const char* a2 = last ? nA : cA + (size_t)(t + 2) * kstep; const char* b2 = last ? nB : cB + (size_t)(t + 2) * kstep;
;             const char* a3 = a2 + kstep; const char* b3 = b2 + kstep;
;             if (last && has_next) S.a_ready(nxt);
;             if constexpr (SP2) {
;             PG8_LDB(B0, 0, 0); PG8_LDB(B1, 0, 1); PG8_SCHED; PG8_LDA(At, 0, 0); PG8_STAGE(PG8_SA(1, 1), a1 + hstep, voffA);
;             PG8_WAIT_V(8); PG8_WAIT_L(0); PG8_BAR; PG8_MMA(0, 0, At, B0); PG8_MMA(0, 1, At, B1); PG8_BAR; PG8_SCHED;
;     ...
; #pragma unroll
;         for (int a = 0; a < 2; ++a)
; #pragma unroll
;             for (int b = 0; b < 2; ++b)
; #pragma unroll
;                 for (int m = 0; m < 4; ++m)
; #pragma unroll
;                     for (int n = 0; n < 2; ++n) acc[a][b][m][n] = (f32x4){0.f, 0.f, 0.f, 0.f};
;         cur = nxt; cA = nA; cB = nB; ++ui;
.LBB0_406:
	s_ashr_i32 s51, s50, 31
	s_lshl_b64 s[16:17], s[50:51], 20
	s_add_u32 s52, s19, s16
	s_addc_u32 s53, s20, s17
	s_and_b64 s[16:17], s[40:41], exec
	s_cselect_b32 s23, s53, s15
	s_cselect_b32 s24, s52, s14
	s_ashr_i32 s49, s48, 31
	s_lshl_b64 s[16:17], s[48:49], 20
	s_add_u32 s54, s26, s16
	s_addc_u32 s55, s27, s17
	s_and_b64 s[16:17], s[40:41], exec
	s_cselect_b32 s25, s55, s1
	s_cselect_b32 s49, s54, s0
	s_add_u32 s51, s0, 0x100
	s_addc_u32 s57, s1, 0
	s_add_u32 s0, s14, 0x80080
	v_mov_b32_e32 v4, 0
	s_addc_u32 s1, s15, 0
	s_mov_b32 s58, -2
	v_mov_b32_e32 v5, v4
	v_mov_b32_e32 v6, v4
	v_mov_b32_e32 v7, v4
	v_mov_b32_e32 v8, v4
	v_mov_b32_e32 v9, v4
	v_mov_b32_e32 v10, v4
	v_mov_b32_e32 v11, v4
	v_mov_b32_e32 v12, v4
	v_mov_b32_e32 v13, v4
	v_mov_b32_e32 v14, v4
	v_mov_b32_e32 v15, v4
	v_mov_b32_e32 v16, v4
	v_mov_b32_e32 v17, v4
	v_mov_b32_e32 v18, v4
	v_mov_b32_e32 v19, v4
	v_mov_b32_e32 v20, v4
	v_mov_b32_e32 v21, v4
	v_mov_b32_e32 v22, v4
	v_mov_b32_e32 v23, v4
	v_mov_b32_e32 v24, v4
	v_mov_b32_e32 v25, v4
	v_mov_b32_e32 v26, v4
	v_mov_b32_e32 v27, v4
	s_waitcnt vmcnt(0)
	v_mov_b32_e32 v28, v4
	v_mov_b32_e32 v29, v4
	v_mov_b32_e32 v30, v4
	v_mov_b32_e32 v31, v4
	v_mov_b32_e32 v32, v4
	v_mov_b32_e32 v33, v4
	v_mov_b32_e32 v34, v4
	v_mov_b32_e32 v35, v4
	v_mov_b32_e32 v68, v4
	v_mov_b32_e32 v69, v4
	v_mov_b32_e32 v70, v4
	v_mov_b32_e32 v71, v4
	v_mov_b32_e32 v72, v4
	v_mov_b32_e32 v73, v4
	v_mov_b32_e32 v74, v4
	v_mov_b32_e32 v75, v4
	v_mov_b32_e32 v76, v4
	v_mov_b32_e32 v77, v4
	v_mov_b32_e32 v78, v4
	v_mov_b32_e32 v79, v4
	v_mov_b32_e32 v80, v4
	v_mov_b32_e32 v81, v4
	v_mov_b32_e32 v82, v4
	v_mov_b32_e32 v83, v4
	v_mov_b32_e32 v84, v4
	v_mov_b32_e32 v85, v4
	v_mov_b32_e32 v86, v4
	v_mov_b32_e32 v87, v4
	v_mov_b32_e32 v88, v4
	v_mov_b32_e32 v89, v4
	v_mov_b32_e32 v90, v4
	v_mov_b32_e32 v91, v4
	v_mov_b32_e32 v92, v4
	v_mov_b32_e32 v93, v4
	v_mov_b32_e32 v94, v4
	v_mov_b32_e32 v95, v4
	v_mov_b32_e32 v96, v4
	v_mov_b32_e32 v97, v4
	v_mov_b32_e32 v98, v4
	v_mov_b32_e32 v99, v4
	v_mov_b32_e32 v36, v4
	v_mov_b32_e32 v37, v4
	v_mov_b32_e32 v38, v4
	v_mov_b32_e32 v39, v4
	v_mov_b32_e32 v40, v4
	v_mov_b32_e32 v41, v4
	v_mov_b32_e32 v42, v4
	v_mov_b32_e32 v43, v4
	v_mov_b32_e32 v44, v4
	v_mov_b32_e32 v45, v4
	v_mov_b32_e32 v46, v4
	v_mov_b32_e32 v47, v4
	v_mov_b32_e32 v48, v4
	v_mov_b32_e32 v49, v4
	v_mov_b32_e32 v50, v4
	v_mov_b32_e32 v51, v4
	v_mov_b32_e32 v52, v4
	v_mov_b32_e32 v53, v4
	v_mov_b32_e32 v54, v4
	v_mov_b32_e32 v55, v4
	v_mov_b32_e32 v56, v4
	v_mov_b32_e32 v57, v4
	v_mov_b32_e32 v58, v4
	v_mov_b32_e32 v59, v4
	v_mov_b32_e32 v60, v4
	v_mov_b32_e32 v61, v4
	v_mov_b32_e32 v62, v4
	v_mov_b32_e32 v63, v4
	v_mov_b32_e32 v64, v4
	v_mov_b32_e32 v65, v4
	v_mov_b32_e32 v66, v4
	v_mov_b32_e32 v67, v4
	v_mov_b32_e32 v108, v4
	v_mov_b32_e32 v109, v4
	v_mov_b32_e32 v110, v4
	v_mov_b32_e32 v111, v4
	v_mov_b32_e32 v112, v4
	v_mov_b32_e32 v113, v4
	v_mov_b32_e32 v114, v4
	v_mov_b32_e32 v115, v4
	v_mov_b32_e32 v116, v4
	v_mov_b32_e32 v117, v4
	v_mov_b32_e32 v118, v4
	v_mov_b32_e32 v119, v4
	v_mov_b32_e32 v120, v4
	v_mov_b32_e32 v121, v4
	v_mov_b32_e32 v122, v4
	v_mov_b32_e32 v123, v4
	v_mov_b32_e32 v124, v4
	v_mov_b32_e32 v125, v4
	v_mov_b32_e32 v126, v4
	v_mov_b32_e32 v127, v4
	v_mov_b32_e32 v128, v4
	v_mov_b32_e32 v129, v4
	v_mov_b32_e32 v130, v4
	v_mov_b32_e32 v131, v4
	v_mov_b32_e32 v132, v4
	v_mov_b32_e32 v133, v4
	v_mov_b32_e32 v134, v4
	v_mov_b32_e32 v135, v4
	v_mov_b32_e32 v136, v4
	v_mov_b32_e32 v137, v4
	v_mov_b32_e32 v138, v4
	v_mov_b32_e32 v139, v4
	s_setprio 1
.LBB0_407:
	s_add_u32 s14, s0, 0xfff80080
	s_addc_u32 s15, s1, -1
	s_add_i32 s59, 0, 0x10000
	s_cmp_eq_u32 s58, 28
	s_cselect_b32 s17, s23, s15
	s_cselect_b32 s16, s24, s14
	s_cselect_b32 s15, s25, s57
	s_cselect_b32 s14, s49, s51
	s_add_i32 s62, 0, 0x14000
	v_add_u32_e32 v154, s59, v171
	v_add_u32_e32 v185, s62, v171
	ds_read_b128 v[100:103], v154
	ds_read_b128 v[104:107], v154 offset:1024
	ds_read_b128 v[140:143], v154 offset:2048
	ds_read_b128 v[154:157], v154 offset:3072
	ds_read_b128 v[158:161], v185
	ds_read_b128 v[162:165], v185 offset:1024
	ds_read_b128 v[166:169], v185 offset:2048
	ds_read_b128 v[186:189], v185 offset:3072
	v_lshl_add_u64 v[222:223], s[0:1], 0, v[152:153]
	s_add_i32 m0, s29, 0xc000
	ds_read_b128 v[190:193], v184
	ds_read_b128 v[194:197], v184 offset:1024
	ds_read_b128 v[198:201], v184 offset:2048
	ds_read_b128 v[202:205], v184 offset:3072
	ds_read_b128 v[206:209], v184 offset:4096
	ds_read_b128 v[210:213], v184 offset:5120
	ds_read_b128 v[214:217], v184 offset:6144
	ds_read_b128 v[218:221], v184 offset:7168
	global_load_lds_dwordx4 v[222:223], off
	v_lshl_add_u64 v[222:223], s[0:1], 0, v[150:151]
	s_add_i32 m0, s29, 0xe000
	s_nop 0
	global_load_lds_dwordx4 v[222:223], off
	s_waitcnt vmcnt(8)
	s_waitcnt lgkmcnt(0)
	s_barrier
; #define PG8_STAGE(bufoff, gbase, voff) do { _Pragma("unroll") for (int _i = 0; _i < 2; ++_i) \
;         __builtin_amdgcn_global_load_lds((const unsigned*)((const char*)(gbase) + (voff)[_i]), (PG8_LAS unsigned*)(lds + (bufoff) + ldsw + _i * 8192), 16, 0, 0); } while (0)
; #define PG8_LDA(dst, b, h) do { _Pragma("unroll") for (int m = 0; m < 4; ++m) _Pragma("unroll") for (int k = 0; k < 2; ++k) dst[m][k] = *(const PG8_LAS bf16x8*)(lds + PG8_SA(b, h) + aoff + m * 2048 + k * 1024); } while (0)
; #define PG8_MMA(ai, bj, At, Bt) do { __builtin_amdgcn_s_setprio(1); _Pragma("unroll") for (int m = 0; m < 4; ++m) _Pragma("unroll") for (int n = 0; n < 2; ++n) _Pragma("unroll") for (int k = 0; k < 2; ++k) \
;         acc[ai][bj][m][n] = __builtin_amdgcn_mfma_f32_16x16x32_bf16(Bt[n][k], At[m][k], acc[ai][bj][m][n], 0, 0, 0); __builtin_amdgcn_s_setprio(0); } while (0)
; #define PG8_WAIT_V(n) asm volatile("s_waitcnt vmcnt(" #n ")" ::: "memory")
; #define PG8_WAIT_L(n) asm volatile("s_waitcnt lgkmcnt(" #n ")" ::: "memory")
; #define PG8_BAR __builtin_amdgcn_s_barrier()
; #define PG8_SCHED __builtin_amdgcn_sched_barrier(0)
; template <class Epi, class Sched, bool ALIGN_EPI = false, bool SP2 = false>
; __device__ __forceinline__ void gemm_phase(PG8_LAS unsigned char* lds, const Gemm g, const Sched& S, const Epi& E) {
;     ...
;             PG8_WAIT_V(8); PG8_WAIT_L(0); PG8_BAR; PG8_MMA(0, 0, At, B0); PG8_MMA(0, 1, At, B1); PG8_BAR; PG8_SCHED;
;             PG8_LDA(At, 0, 1); PG8_STAGE(PG8_SB(0, 0), b2, voffB); PG8_STAGE(PG8_SB(0, 1), b2 + hstep, voffB); PG8_STAGE(PG8_SA(0, 0), a2, voffA);
;             PG8_WAIT_V(8); PG8_WAIT_L(0); PG8_BAR; PG8_MMA(1, 0, At, B0); PG8_MMA(1, 1, At, B1); PG8_BAR; PG8_SCHED;
	s_setprio 0
	s_waitcnt lgkmcnt(0)
	v_mfma_f32_16x16x32_bf16 v[136:139], v[100:103], v[190:193], v[136:139]
	v_mfma_f32_16x16x32_bf16 v[132:135], v[140:143], v[190:193], v[132:135]
	v_mfma_f32_16x16x32_bf16 v[128:131], v[100:103], v[198:201], v[128:131]
	v_mfma_f32_16x16x32_bf16 v[124:127], v[140:143], v[198:201], v[124:127]
	v_mfma_f32_16x16x32_bf16 v[120:123], v[100:103], v[206:209], v[120:123]
	v_mfma_f32_16x16x32_bf16 v[116:119], v[140:143], v[206:209], v[116:119]
	v_mfma_f32_16x16x32_bf16 v[112:115], v[100:103], v[214:217], v[112:115]
	v_mfma_f32_16x16x32_bf16 v[108:111], v[140:143], v[214:217], v[108:111]
	v_mfma_f32_16x16x32_bf16 v[136:139], v[104:107], v[194:197], v[136:139]
	v_mfma_f32_16x16x32_bf16 v[132:135], v[154:157], v[194:197], v[132:135]
	v_mfma_f32_16x16x32_bf16 v[128:131], v[104:107], v[202:205], v[128:131]
	v_mfma_f32_16x16x32_bf16 v[124:127], v[154:157], v[202:205], v[124:127]
	v_mfma_f32_16x16x32_bf16 v[120:123], v[104:107], v[210:213], v[120:123]
	v_mfma_f32_16x16x32_bf16 v[116:119], v[154:157], v[210:213], v[116:119]
	v_mfma_f32_16x16x32_bf16 v[112:115], v[104:107], v[218:221], v[112:115]
	v_mfma_f32_16x16x32_bf16 v[108:111], v[154:157], v[218:221], v[108:111]
	v_mfma_f32_16x16x32_bf16 v[64:67], v[158:161], v[190:193], v[64:67]
	v_mfma_f32_16x16x32_bf16 v[60:63], v[166:169], v[190:193], v[60:63]
	v_mfma_f32_16x16x32_bf16 v[56:59], v[158:161], v[198:201], v[56:59]
	v_mfma_f32_16x16x32_bf16 v[52:55], v[166:169], v[198:201], v[52:55]
	v_mfma_f32_16x16x32_bf16 v[48:51], v[158:161], v[206:209], v[48:51]
	v_mfma_f32_16x16x32_bf16 v[44:47], v[166:169], v[206:209], v[44:47]
	v_mfma_f32_16x16x32_bf16 v[40:43], v[158:161], v[214:217], v[40:43]
	v_mfma_f32_16x16x32_bf16 v[36:39], v[166:169], v[214:217], v[36:39]
	v_mfma_f32_16x16x32_bf16 v[64:67], v[162:165], v[194:197], v[64:67]
	v_mfma_f32_16x16x32_bf16 v[60:63], v[186:189], v[194:197], v[60:63]
	v_mfma_f32_16x16x32_bf16 v[56:59], v[162:165], v[202:205], v[56:59]
	v_mfma_f32_16x16x32_bf16 v[52:55], v[186:189], v[202:205], v[52:55]
	v_mfma_f32_16x16x32_bf16 v[48:51], v[162:165], v[210:213], v[48:51]
	v_mfma_f32_16x16x32_bf16 v[44:47], v[186:189], v[210:213], v[44:47]
	v_mfma_f32_16x16x32_bf16 v[40:43], v[162:165], v[218:221], v[40:43]
	v_mfma_f32_16x16x32_bf16 v[36:39], v[186:189], v[218:221], v[36:39]
	s_barrier
	s_setprio 1
	s_add_i32 s59, s59, s28
	v_lshl_add_u64 v[222:223], s[14:15], 0, v[174:175]
	s_mov_b32 m0, s59
	ds_read_b128 v[190:193], v184 offset:16384
	ds_read_b128 v[194:197], v184 offset:17408
	ds_read_b128 v[198:201], v184 offset:18432
	ds_read_b128 v[202:205], v184 offset:19456
	ds_read_b128 v[206:209], v184 offset:20480
	ds_read_b128 v[210:213], v184 offset:21504
	ds_read_b128 v[214:217], v184 offset:22528
	ds_read_b128 v[218:221], v184 offset:23552
	global_load_lds_dwordx4 v[222:223], off
	s_add_i32 m0, s59, 0x2000
	s_add_u32 s60, s14, 0x80000
	v_lshl_add_u64 v[224:225], s[14:15], 0, v[144:145]
	s_addc_u32 s61, s15, 0
	s_add_i32 s59, s62, s28
	global_load_lds_dwordx4 v[224:225], off
	v_lshl_add_u64 v[226:227], s[60:61], 0, v[174:175]
	s_mov_b32 m0, s59
	v_lshl_add_u64 v[228:229], s[16:17], 0, v[146:147]
	global_load_lds_dwordx4 v[226:227], off
	v_lshl_add_u64 v[226:227], s[60:61], 0, v[144:145]
	s_add_i32 m0, s59, 0x2000
	s_nop 0
	global_load_lds_dwordx4 v[226:227], off
	v_lshl_add_u64 v[226:227], s[16:17], 0, v[148:149]
	s_mov_b32 m0, s29
	s_nop 0
	global_load_lds_dwordx4 v[226:227], off
	s_mov_b32 m0, s30
	s_nop 0
	global_load_lds_dwordx4 v[228:229], off
	s_waitcnt vmcnt(8)
	s_waitcnt lgkmcnt(0)
	s_barrier
	s_setprio 0
	s_waitcnt lgkmcnt(0)
	v_mfma_f32_16x16x32_bf16 v[96:99], v[100:103], v[190:193], v[96:99]
	v_mfma_f32_16x16x32_bf16 v[92:95], v[140:143], v[190:193], v[92:95]
	v_mfma_f32_16x16x32_bf16 v[88:91], v[100:103], v[198:201], v[88:91]
	v_mfma_f32_16x16x32_bf16 v[84:87], v[140:143], v[198:201], v[84:87]
	v_mfma_f32_16x16x32_bf16 v[80:83], v[100:103], v[206:209], v[80:83]
	v_mfma_f32_16x16x32_bf16 v[76:79], v[140:143], v[206:209], v[76:79]
	v_mfma_f32_16x16x32_bf16 v[72:75], v[100:103], v[214:217], v[72:75]
	v_mfma_f32_16x16x32_bf16 v[68:71], v[140:143], v[214:217], v[68:71]
	v_mfma_f32_16x16x32_bf16 v[96:99], v[104:107], v[194:197], v[96:99]
	v_mfma_f32_16x16x32_bf16 v[92:95], v[154:157], v[194:197], v[92:95]
	v_mfma_f32_16x16x32_bf16 v[88:91], v[104:107], v[202:205], v[88:91]
	v_mfma_f32_16x16x32_bf16 v[84:87], v[154:157], v[202:205], v[84:87]
	v_mfma_f32_16x16x32_bf16 v[80:83], v[104:107], v[210:213], v[80:83]
	v_mfma_f32_16x16x32_bf16 v[76:79], v[154:157], v[210:213], v[76:79]
	v_mfma_f32_16x16x32_bf16 v[72:75], v[104:107], v[218:221], v[72:75]
	v_mfma_f32_16x16x32_bf16 v[68:71], v[154:157], v[218:221], v[68:71]
	v_mfma_f32_16x16x32_bf16 v[32:35], v[158:161], v[190:193], v[32:35]
	v_mfma_f32_16x16x32_bf16 v[28:31], v[166:169], v[190:193], v[28:31]
	v_mfma_f32_16x16x32_bf16 v[24:27], v[158:161], v[198:201], v[24:27]
	v_mfma_f32_16x16x32_bf16 v[20:23], v[166:169], v[198:201], v[20:23]
	v_mfma_f32_16x16x32_bf16 v[16:19], v[158:161], v[206:209], v[16:19]
	v_mfma_f32_16x16x32_bf16 v[12:15], v[166:169], v[206:209], v[12:15]
	v_mfma_f32_16x16x32_bf16 v[8:11], v[158:161], v[214:217], v[8:11]
	v_mfma_f32_16x16x32_bf16 v[4:7], v[166:169], v[214:217], v[4:7]
	v_mfma_f32_16x16x32_bf16 v[32:35], v[162:165], v[194:197], v[32:35]
	v_mfma_f32_16x16x32_bf16 v[28:31], v[186:189], v[194:197], v[28:31]
	v_mfma_f32_16x16x32_bf16 v[24:27], v[162:165], v[202:205], v[24:27]
	v_mfma_f32_16x16x32_bf16 v[20:23], v[186:189], v[202:205], v[20:23]
	v_mfma_f32_16x16x32_bf16 v[16:19], v[162:165], v[210:213], v[16:19]
	v_mfma_f32_16x16x32_bf16 v[12:15], v[186:189], v[210:213], v[12:15]
	v_mfma_f32_16x16x32_bf16 v[8:11], v[162:165], v[218:221], v[8:11]
	v_mfma_f32_16x16x32_bf16 v[4:7], v[186:189], v[218:221], v[4:7]
	s_barrier
; #define PG8_STAGE(bufoff, gbase, voff) do { _Pragma("unroll") for (int _i = 0; _i < 2; ++_i) \
;         __builtin_amdgcn_global_load_lds((const unsigned*)((const char*)(gbase) + (voff)[_i]), (PG8_LAS unsigned*)(lds + (bufoff) + ldsw + _i * 8192), 16, 0, 0); } while (0)
; #define PG8_LDA(dst, b, h) do { _Pragma("unroll") for (int m = 0; m < 4; ++m) _Pragma("unroll") for (int k = 0; k < 2; ++k) dst[m][k] = *(const PG8_LAS bf16x8*)(lds + PG8_SA(b, h) + aoff + m * 2048 + k * 1024); } while (0)
; #define PG8_LDB(dst, b, h) do { _Pragma("unroll") for (int n = 0; n < 2; ++n) _Pragma("unroll") for (int k = 0; k < 2; ++k) dst[n][k] = *(const PG8_LAS bf16x8*)(lds + PG8_SB(b, h) + boff + n * 2048 + k * 1024); } while (0)
; #define PG8_MMA(ai, bj, At, Bt) do { __builtin_amdgcn_s_setprio(1); _Pragma("unroll") for (int m = 0; m < 4; ++m) _Pragma("unroll") for (int n = 0; n < 2; ++n) _Pragma("unroll") for (int k = 0; k < 2; ++k) \
;         acc[ai][bj][m][n] = __builtin_amdgcn_mfma_f32_16x16x32_bf16(Bt[n][k], At[m][k], acc[ai][bj][m][n], 0, 0, 0); __builtin_amdgcn_s_setprio(0); } while (0)
; #define PG8_WAIT_V(n) asm volatile("s_waitcnt vmcnt(" #n ")" ::: "memory")
; #define PG8_WAIT_L(n) asm volatile("s_waitcnt lgkmcnt(" #n ")" ::: "memory")
; #define PG8_BAR __builtin_amdgcn_s_barrier()
; #define PG8_SCHED __builtin_amdgcn_sched_barrier(0)
; template <class Epi, class Sched, bool ALIGN_EPI = false, bool SP2 = false>
; __device__ __forceinline__ void gemm_phase(PG8_LAS unsigned char* lds, const Gemm g, const Sched& S, const Epi& E) {
;     ...
;             PG8_WAIT_V(8); PG8_WAIT_L(0); PG8_BAR; PG8_MMA(1, 0, At, B0); PG8_MMA(1, 1, At, B1); PG8_BAR; PG8_SCHED;
;             PG8_LDB(B0, 1, 0); PG8_LDB(B1, 1, 1); PG8_SCHED; PG8_LDA(At, 1, 0); PG8_STAGE(PG8_SA(0, 1), a2 + hstep, voffA);
;             PG8_WAIT_V(8); PG8_WAIT_L(0); PG8_BAR; PG8_MMA(0, 0, At, B0); PG8_MMA(0, 1, At, B1); PG8_BAR; PG8_SCHED;
	s_setprio 1
	s_add_i32 s59, 0, 0x18000
	s_add_i32 s60, 0, 0x1c000
	v_add_u32_e32 v154, s59, v171
	v_add_u32_e32 v185, s60, v171
	ds_read_b128 v[100:103], v154
	ds_read_b128 v[104:107], v154 offset:1024
	ds_read_b128 v[140:143], v154 offset:2048
	ds_read_b128 v[154:157], v154 offset:3072
	ds_read_b128 v[158:161], v185
	ds_read_b128 v[162:165], v185 offset:1024
	ds_read_b128 v[166:169], v185 offset:2048
	ds_read_b128 v[186:189], v185 offset:3072
	s_add_u32 s16, s16, 0x80000
	s_addc_u32 s17, s17, 0
	s_mov_b32 m0, s31
	v_lshl_add_u64 v[230:231], s[16:17], 0, v[148:149]
	ds_read_b128 v[190:193], v184 offset:32768
	ds_read_b128 v[194:197], v184 offset:33792
	ds_read_b128 v[198:201], v184 offset:34816
	ds_read_b128 v[202:205], v184 offset:35840
	ds_read_b128 v[206:209], v184 offset:36864
	ds_read_b128 v[210:213], v184 offset:37888
	ds_read_b128 v[214:217], v184 offset:38912
	ds_read_b128 v[218:221], v184 offset:39936
	global_load_lds_dwordx4 v[230:231], off
	v_lshl_add_u64 v[230:231], s[16:17], 0, v[146:147]
	s_mov_b32 m0, s34
	s_nop 0
	global_load_lds_dwordx4 v[230:231], off
	s_waitcnt vmcnt(8)
	s_waitcnt lgkmcnt(0)
	s_barrier
	s_setprio 0
	s_waitcnt lgkmcnt(0)
	v_mfma_f32_16x16x32_bf16 v[136:139], v[100:103], v[190:193], v[136:139]
	v_mfma_f32_16x16x32_bf16 v[132:135], v[140:143], v[190:193], v[132:135]
	v_mfma_f32_16x16x32_bf16 v[128:131], v[100:103], v[198:201], v[128:131]
	v_mfma_f32_16x16x32_bf16 v[124:127], v[140:143], v[198:201], v[124:127]
	v_mfma_f32_16x16x32_bf16 v[120:123], v[100:103], v[206:209], v[120:123]
	v_mfma_f32_16x16x32_bf16 v[116:119], v[140:143], v[206:209], v[116:119]
	v_mfma_f32_16x16x32_bf16 v[112:115], v[100:103], v[214:217], v[112:115]
	v_mfma_f32_16x16x32_bf16 v[108:111], v[140:143], v[214:217], v[108:111]
	v_mfma_f32_16x16x32_bf16 v[136:139], v[104:107], v[194:197], v[136:139]
	v_mfma_f32_16x16x32_bf16 v[132:135], v[154:157], v[194:197], v[132:135]
	v_mfma_f32_16x16x32_bf16 v[128:131], v[104:107], v[202:205], v[128:131]
	v_mfma_f32_16x16x32_bf16 v[124:127], v[154:157], v[202:205], v[124:127]
	v_mfma_f32_16x16x32_bf16 v[120:123], v[104:107], v[210:213], v[120:123]
	v_mfma_f32_16x16x32_bf16 v[116:119], v[154:157], v[210:213], v[116:119]
	v_mfma_f32_16x16x32_bf16 v[112:115], v[104:107], v[218:221], v[112:115]
	v_mfma_f32_16x16x32_bf16 v[108:111], v[154:157], v[218:221], v[108:111]
	v_mfma_f32_16x16x32_bf16 v[64:67], v[158:161], v[190:193], v[64:67]
	v_mfma_f32_16x16x32_bf16 v[60:63], v[166:169], v[190:193], v[60:63]
	v_mfma_f32_16x16x32_bf16 v[56:59], v[158:161], v[198:201], v[56:59]
	v_mfma_f32_16x16x32_bf16 v[52:55], v[166:169], v[198:201], v[52:55]
	v_mfma_f32_16x16x32_bf16 v[48:51], v[158:161], v[206:209], v[48:51]
	v_mfma_f32_16x16x32_bf16 v[44:47], v[166:169], v[206:209], v[44:47]
	v_mfma_f32_16x16x32_bf16 v[40:43], v[158:161], v[214:217], v[40:43]
	v_mfma_f32_16x16x32_bf16 v[36:39], v[166:169], v[214:217], v[36:39]
	v_mfma_f32_16x16x32_bf16 v[64:67], v[162:165], v[194:197], v[64:67]
	v_mfma_f32_16x16x32_bf16 v[60:63], v[186:189], v[194:197], v[60:63]
	v_mfma_f32_16x16x32_bf16 v[56:59], v[162:165], v[202:205], v[56:59]
	v_mfma_f32_16x16x32_bf16 v[52:55], v[186:189], v[202:205], v[52:55]
	v_mfma_f32_16x16x32_bf16 v[48:51], v[162:165], v[210:213], v[48:51]
	v_mfma_f32_16x16x32_bf16 v[44:47], v[186:189], v[210:213], v[44:47]
	v_mfma_f32_16x16x32_bf16 v[40:43], v[162:165], v[218:221], v[40:43]
	v_mfma_f32_16x16x32_bf16 v[36:39], v[186:189], v[218:221], v[36:39]
	s_barrier
; #define PG8_STAGE(bufoff, gbase, voff) do { _Pragma("unroll") for (int _i = 0; _i < 2; ++_i) \
;         __builtin_amdgcn_global_load_lds((const unsigned*)((const char*)(gbase) + (voff)[_i]), (PG8_LAS unsigned*)(lds + (bufoff) + ldsw + _i * 8192), 16, 0, 0); } while (0)
; #define PG8_LDA(dst, b, h) do { _Pragma("unroll") for (int m = 0; m < 4; ++m) _Pragma("unroll") for (int k = 0; k < 2; ++k) dst[m][k] = *(const PG8_LAS bf16x8*)(lds + PG8_SA(b, h) + aoff + m * 2048 + k * 1024); } while (0)
; #define PG8_MMA(ai, bj, At, Bt) do { __builtin_amdgcn_s_setprio(1); _Pragma("unroll") for (int m = 0; m < 4; ++m) _Pragma("unroll") for (int n = 0; n < 2; ++n) _Pragma("unroll") for (int k = 0; k < 2; ++k) \
;         acc[ai][bj][m][n] = __builtin_amdgcn_mfma_f32_16x16x32_bf16(Bt[n][k], At[m][k], acc[ai][bj][m][n], 0, 0, 0); __builtin_amdgcn_s_setprio(0); } while (0)
; #define PG8_WAIT_V(n) asm volatile("s_waitcnt vmcnt(" #n ")" ::: "memory")
; #define PG8_WAIT_L(n) asm volatile("s_waitcnt lgkmcnt(" #n ")" ::: "memory")
; #define PG8_BAR __builtin_amdgcn_s_barrier()
; #define PG8_SCHED __builtin_amdgcn_sched_barrier(0)
; template <class Epi, class Sched, bool ALIGN_EPI = false, bool SP2 = false>
; __device__ __forceinline__ void gemm_phase(PG8_LAS unsigned char* lds, const Gemm g, const Sched& S, const Epi& E) {
;     ...
;         for (int t = 0; t < nt; t += 2) {
;             const bool last = (t == nt - 2);
;             const char* a1 = cA + (size_t)(t + 1) * kstep;
;             const char* a2 = last ? nA : cA + (size_t)(t + 2) * kstep; const char* b2 = last ? nB : cB + (size_t)(t + 2) * kstep;
;             const char* a3 = a2 + kstep; const char* b3 = b2 + kstep;
;     ...
;             PG8_WAIT_V(8); PG8_WAIT_L(0); PG8_BAR; PG8_MMA(0, 0, At, B0); PG8_MMA(0, 1, At, B1); PG8_BAR; PG8_SCHED;
;             PG8_LDA(At, 1, 1); PG8_STAGE(PG8_SB(1, 0), b3, voffB); PG8_STAGE(PG8_SB(1, 1), b3 + hstep, voffB); PG8_STAGE(PG8_SA(1, 0), a3, voffA);
;             PG8_WAIT_V(8); PG8_WAIT_L(0); PG8_BAR; PG8_MMA(1, 0, At, B0); PG8_MMA(1, 1, At, B1); PG8_BAR; PG8_SCHED;
	s_setprio 1
	s_add_i32 s16, s59, s28
	v_lshl_add_u64 v[222:223], v[222:223], 0, s[10:11]
	s_mov_b32 m0, s16
	ds_read_b128 v[190:193], v184 offset:49152
	ds_read_b128 v[194:197], v184 offset:50176
	ds_read_b128 v[198:201], v184 offset:51200
	ds_read_b128 v[202:205], v184 offset:52224
	ds_read_b128 v[206:209], v184 offset:53248
	ds_read_b128 v[210:213], v184 offset:54272
	ds_read_b128 v[214:217], v184 offset:55296
	ds_read_b128 v[218:221], v184 offset:56320
	global_load_lds_dwordx4 v[222:223], off
	s_add_i32 m0, s16, 0x2000
	s_add_u32 s14, s14, 0x80080
	v_lshl_add_u64 v[222:223], v[224:225], 0, s[10:11]
	s_addc_u32 s15, s15, 0
	s_add_i32 s16, s60, s28
	global_load_lds_dwordx4 v[222:223], off
	v_lshl_add_u64 v[222:223], s[14:15], 0, v[174:175]
	s_mov_b32 m0, s16
	s_nop 0
	global_load_lds_dwordx4 v[222:223], off
	v_lshl_add_u64 v[222:223], s[14:15], 0, v[144:145]
	s_add_i32 m0, s16, 0x2000
	s_nop 0
	global_load_lds_dwordx4 v[222:223], off
	v_lshl_add_u64 v[222:223], v[226:227], 0, s[10:11]
	s_mov_b32 m0, s35
	s_nop 0
	global_load_lds_dwordx4 v[222:223], off
	v_lshl_add_u64 v[222:223], v[228:229], 0, s[10:11]
	s_mov_b32 m0, s38
	s_nop 0
	global_load_lds_dwordx4 v[222:223], off
	s_waitcnt vmcnt(8)
	s_waitcnt lgkmcnt(0)
	s_barrier
	s_setprio 0
	s_waitcnt lgkmcnt(0)
	v_mfma_f32_16x16x32_bf16 v[96:99], v[100:103], v[190:193], v[96:99]
	v_mfma_f32_16x16x32_bf16 v[92:95], v[140:143], v[190:193], v[92:95]
	v_mfma_f32_16x16x32_bf16 v[88:91], v[100:103], v[198:201], v[88:91]
	v_mfma_f32_16x16x32_bf16 v[84:87], v[140:143], v[198:201], v[84:87]
	v_mfma_f32_16x16x32_bf16 v[80:83], v[100:103], v[206:209], v[80:83]
	v_mfma_f32_16x16x32_bf16 v[76:79], v[140:143], v[206:209], v[76:79]
	v_mfma_f32_16x16x32_bf16 v[72:75], v[100:103], v[214:217], v[72:75]
	v_mfma_f32_16x16x32_bf16 v[68:71], v[140:143], v[214:217], v[68:71]
	v_mfma_f32_16x16x32_bf16 v[96:99], v[104:107], v[194:197], v[96:99]
	v_mfma_f32_16x16x32_bf16 v[92:95], v[154:157], v[194:197], v[92:95]
	v_mfma_f32_16x16x32_bf16 v[88:91], v[104:107], v[202:205], v[88:91]
	v_mfma_f32_16x16x32_bf16 v[84:87], v[154:157], v[202:205], v[84:87]
	v_mfma_f32_16x16x32_bf16 v[80:83], v[104:107], v[210:213], v[80:83]
	v_mfma_f32_16x16x32_bf16 v[76:79], v[154:157], v[210:213], v[76:79]
	v_mfma_f32_16x16x32_bf16 v[72:75], v[104:107], v[218:221], v[72:75]
	v_mfma_f32_16x16x32_bf16 v[68:71], v[154:157], v[218:221], v[68:71]
	v_mfma_f32_16x16x32_bf16 v[32:35], v[158:161], v[190:193], v[32:35]
	v_mfma_f32_16x16x32_bf16 v[28:31], v[166:169], v[190:193], v[28:31]
	v_mfma_f32_16x16x32_bf16 v[24:27], v[158:161], v[198:201], v[24:27]
	v_mfma_f32_16x16x32_bf16 v[20:23], v[166:169], v[198:201], v[20:23]
	v_mfma_f32_16x16x32_bf16 v[16:19], v[158:161], v[206:209], v[16:19]
	v_mfma_f32_16x16x32_bf16 v[12:15], v[166:169], v[206:209], v[12:15]
	v_mfma_f32_16x16x32_bf16 v[8:11], v[158:161], v[214:217], v[8:11]
	v_mfma_f32_16x16x32_bf16 v[4:7], v[166:169], v[214:217], v[4:7]
	v_mfma_f32_16x16x32_bf16 v[32:35], v[162:165], v[194:197], v[32:35]
	v_mfma_f32_16x16x32_bf16 v[28:31], v[186:189], v[194:197], v[28:31]
	v_mfma_f32_16x16x32_bf16 v[24:27], v[162:165], v[202:205], v[24:27]
	v_mfma_f32_16x16x32_bf16 v[20:23], v[186:189], v[202:205], v[20:23]
	v_mfma_f32_16x16x32_bf16 v[16:19], v[162:165], v[210:213], v[16:19]
	v_mfma_f32_16x16x32_bf16 v[12:15], v[186:189], v[210:213], v[12:15]
	v_mfma_f32_16x16x32_bf16 v[8:11], v[162:165], v[218:221], v[8:11]
	v_mfma_f32_16x16x32_bf16 v[4:7], v[186:189], v[218:221], v[4:7]
	s_barrier
	s_setprio 1
	s_add_i32 s58, s58, 2
	s_add_u32 s51, s51, 0x100
	s_addc_u32 s57, s57, 0
	s_add_u32 s0, s0, 0x100
	s_addc_u32 s1, s1, 0
	s_cmp_gt_u32 s58, 29
	s_cbranch_scc0 .LBB0_407
	s_and_b64 vcc, exec, s[46:47]
	s_cbranch_vccz .LBB0_410
	s_barrier

; #define PG8_STAGE(bufoff, gbase, voff) do { _Pragma("unroll") for (int _i = 0; _i < 2; ++_i) \
;         __builtin_amdgcn_global_load_lds((const unsigned*)((const char*)(gbase) + (voff)[_i]), (PG8_LAS unsigned*)(lds + (bufoff) + ldsw + _i * 8192), 16, 0, 0); } while (0)
; #define PG8_LDA(dst, b, h) do { _Pragma("unroll") for (int m = 0; m < 4; ++m) _Pragma("unroll") for (int k = 0; k < 2; ++k) dst[m][k] = *(const PG8_LAS bf16x8*)(lds + PG8_SA(b, h) + aoff + m * 2048 + k * 1024); } while (0)
; #define PG8_LDB(dst, b, h) do { _Pragma("unroll") for (int n = 0; n < 2; ++n) _Pragma("unroll") for (int k = 0; k < 2; ++k) dst[n][k] = *(const PG8_LAS bf16x8*)(lds + PG8_SB(b, h) + boff + n * 2048 + k * 1024); } while (0)
; #define PG8_WAIT_V(n) asm volatile("s_waitcnt vmcnt(" #n ")" ::: "memory")
; #define PG8_WAIT_L(n) asm volatile("s_waitcnt lgkmcnt(" #n ")" ::: "memory")
; #define PG8_BAR __builtin_amdgcn_s_barrier()
; template <class Epi, class Sched, bool ALIGN_EPI = false, bool SP2 = false>
; __device__ __forceinline__ void gemm_phase(PG8_LAS unsigned char* lds, const Gemm g, const Sched& S, const Epi& E) {
;     ...
;         const bool has_next = S.next(ui + 1, nxt);
;         const char* nA = has_next ? (const char*)g.A + (size_t)nxt.pm * tstep : cA; const char* nB = has_next ? (const char*)g.Bt + (size_t)nxt.pn * tstep : cB;
;         for (int t = 0; t < nt; t += 2) {
;             const bool last = (t == nt - 2);
;             const char* a1 = cA + (size_t)(t + 1) * kstep;
;             const char* a2 = last ? nA : cA + (size_t)(t + 2) * kstep; const char* b2 = last ? nB : cB + (size_t)(t + 2) * kstep;
;             const char* a3 = a2 + kstep; const char* b3 = b2 + kstep;
;             if (last && has_next) S.a_ready(nxt);
;             if constexpr (SP2) {
;             PG8_LDB(B0, 0, 0); PG8_LDB(B1, 0, 1); PG8_SCHED; PG8_LDA(At, 0, 0); PG8_STAGE(PG8_SA(1, 1), a1 + hstep, voffA);
;             PG8_WAIT_V(8); PG8_WAIT_L(0); PG8_BAR; PG8_MMA(0, 0, At, B0); PG8_MMA(0, 1, At, B1); PG8_BAR; PG8_SCHED;
;     ...
; #pragma unroll
;         for (int a = 0; a < 2; ++a)
; #pragma unroll
;             for (int b = 0; b < 2; ++b)
; #pragma unroll
;                 for (int m = 0; m < 4; ++m)
; #pragma unroll
;                     for (int n = 0; n < 2; ++n) acc[a][b][m][n] = (f32x4){0.f, 0.f, 0.f, 0.f};
;         cur = nxt; cA = nA; cB = nB; ++ui;
.LBB0_484:
	s_ashr_i32 s53, s52, 31
	s_lshl_b64 s[16:17], s[52:53], 21
	s_add_u32 s54, s19, s16
	s_addc_u32 s55, s20, s17
	s_and_b64 s[16:17], s[40:41], exec
	s_cselect_b32 s23, s55, s15
	s_cselect_b32 s24, s54, s14
	s_ashr_i32 s51, s50, 31
	s_lshl_b64 s[16:17], s[50:51], 21
	s_add_u32 s56, s26, s16
	s_addc_u32 s57, s27, s17
	s_and_b64 s[16:17], s[40:41], exec
	s_cselect_b32 s25, s57, s1
	s_cselect_b32 s51, s56, s0
	s_add_u32 s53, s0, 0x100
	s_addc_u32 s59, s1, 0
	s_add_u32 s0, s14, 0x100080
	v_mov_b32_e32 v4, 0
	s_addc_u32 s1, s15, 0
	s_mov_b32 s60, -2
	v_mov_b32_e32 v5, v4
	v_mov_b32_e32 v6, v4
	v_mov_b32_e32 v7, v4
	v_mov_b32_e32 v8, v4
	v_mov_b32_e32 v9, v4
	v_mov_b32_e32 v10, v4
	v_mov_b32_e32 v11, v4
	v_mov_b32_e32 v12, v4
	v_mov_b32_e32 v13, v4
	v_mov_b32_e32 v14, v4
	v_mov_b32_e32 v15, v4
	v_mov_b32_e32 v16, v4
	v_mov_b32_e32 v17, v4
	v_mov_b32_e32 v18, v4
	v_mov_b32_e32 v19, v4
	v_mov_b32_e32 v20, v4
	v_mov_b32_e32 v21, v4
	v_mov_b32_e32 v22, v4
	v_mov_b32_e32 v23, v4
	v_mov_b32_e32 v24, v4
	v_mov_b32_e32 v25, v4
	v_mov_b32_e32 v26, v4
	v_mov_b32_e32 v27, v4
	s_waitcnt vmcnt(0)
	v_mov_b32_e32 v28, v4
	v_mov_b32_e32 v29, v4
	v_mov_b32_e32 v30, v4
	v_mov_b32_e32 v31, v4
	v_mov_b32_e32 v32, v4
	v_mov_b32_e32 v33, v4
	v_mov_b32_e32 v34, v4
	v_mov_b32_e32 v35, v4
	v_mov_b32_e32 v68, v4
	v_mov_b32_e32 v69, v4
	v_mov_b32_e32 v70, v4
	v_mov_b32_e32 v71, v4
	v_mov_b32_e32 v72, v4
	v_mov_b32_e32 v73, v4
	v_mov_b32_e32 v74, v4
	v_mov_b32_e32 v75, v4
	v_mov_b32_e32 v76, v4
	v_mov_b32_e32 v77, v4
	v_mov_b32_e32 v78, v4
	v_mov_b32_e32 v79, v4
	v_mov_b32_e32 v80, v4
	v_mov_b32_e32 v81, v4
	v_mov_b32_e32 v82, v4
	v_mov_b32_e32 v83, v4
	v_mov_b32_e32 v84, v4
	v_mov_b32_e32 v85, v4
	v_mov_b32_e32 v86, v4
	v_mov_b32_e32 v87, v4
	v_mov_b32_e32 v88, v4
	v_mov_b32_e32 v89, v4
	v_mov_b32_e32 v90, v4
	v_mov_b32_e32 v91, v4
	v_mov_b32_e32 v92, v4
	v_mov_b32_e32 v93, v4
	v_mov_b32_e32 v94, v4
	v_mov_b32_e32 v95, v4
	v_mov_b32_e32 v96, v4
	v_mov_b32_e32 v97, v4
	v_mov_b32_e32 v98, v4
	v_mov_b32_e32 v99, v4
	v_mov_b32_e32 v36, v4
	v_mov_b32_e32 v37, v4
	v_mov_b32_e32 v38, v4
	v_mov_b32_e32 v39, v4
	v_mov_b32_e32 v40, v4
	v_mov_b32_e32 v41, v4
	v_mov_b32_e32 v42, v4
	v_mov_b32_e32 v43, v4
	v_mov_b32_e32 v44, v4
	v_mov_b32_e32 v45, v4
	v_mov_b32_e32 v46, v4
	v_mov_b32_e32 v47, v4
	v_mov_b32_e32 v48, v4
	v_mov_b32_e32 v49, v4
	v_mov_b32_e32 v50, v4
	v_mov_b32_e32 v51, v4
	v_mov_b32_e32 v52, v4
	v_mov_b32_e32 v53, v4
	v_mov_b32_e32 v54, v4
	v_mov_b32_e32 v55, v4
	v_mov_b32_e32 v56, v4
	v_mov_b32_e32 v57, v4
	v_mov_b32_e32 v58, v4
	v_mov_b32_e32 v59, v4
	v_mov_b32_e32 v60, v4
	v_mov_b32_e32 v61, v4
	v_mov_b32_e32 v62, v4
	v_mov_b32_e32 v63, v4
	v_mov_b32_e32 v64, v4
	v_mov_b32_e32 v65, v4
	v_mov_b32_e32 v66, v4
	v_mov_b32_e32 v67, v4
	v_mov_b32_e32 v108, v4
	v_mov_b32_e32 v109, v4
	v_mov_b32_e32 v110, v4
	v_mov_b32_e32 v111, v4
	v_mov_b32_e32 v112, v4
	v_mov_b32_e32 v113, v4
	v_mov_b32_e32 v114, v4
	v_mov_b32_e32 v115, v4
	v_mov_b32_e32 v116, v4
	v_mov_b32_e32 v117, v4
	v_mov_b32_e32 v118, v4
	v_mov_b32_e32 v119, v4
	v_mov_b32_e32 v120, v4
	v_mov_b32_e32 v121, v4
	v_mov_b32_e32 v122, v4
	v_mov_b32_e32 v123, v4
	v_mov_b32_e32 v124, v4
	v_mov_b32_e32 v125, v4
	v_mov_b32_e32 v126, v4
	v_mov_b32_e32 v127, v4
	v_mov_b32_e32 v128, v4
	v_mov_b32_e32 v129, v4
	v_mov_b32_e32 v130, v4
	v_mov_b32_e32 v131, v4
	v_mov_b32_e32 v132, v4
	v_mov_b32_e32 v133, v4
	v_mov_b32_e32 v134, v4
	v_mov_b32_e32 v135, v4
	v_mov_b32_e32 v136, v4
	v_mov_b32_e32 v137, v4
	v_mov_b32_e32 v138, v4
	v_mov_b32_e32 v139, v4
	s_setprio 1
.LBB0_485:
	s_add_u32 s14, s0, 0xfff00080
	s_addc_u32 s15, s1, -1
	s_add_i32 s61, 0, 0x10000
	s_cmp_eq_u32 s60, 60
	s_cselect_b32 s17, s23, s15
	s_cselect_b32 s16, s24, s14
	s_cselect_b32 s15, s25, s59
	s_cselect_b32 s14, s51, s53
	s_add_i32 s64, 0, 0x14000
	v_add_u32_e32 v144, s61, v188
	v_add_u32_e32 v170, s64, v188
	ds_read_b128 v[100:103], v144
	ds_read_b128 v[104:107], v144 offset:1024
	ds_read_b128 v[140:143], v144 offset:2048
	ds_read_b128 v[144:147], v144 offset:3072
	ds_read_b128 v[158:161], v170
	ds_read_b128 v[162:165], v170 offset:1024
	ds_read_b128 v[166:169], v170 offset:2048
	ds_read_b128 v[184:187], v170 offset:3072
	v_lshl_add_u64 v[170:171], s[0:1], 0, v[156:157]
	s_add_i32 m0, s29, 0xc000
	ds_read_b128 v[192:195], v190
	ds_read_b128 v[196:199], v190 offset:1024
	ds_read_b128 v[200:203], v190 offset:2048
	ds_read_b128 v[204:207], v190 offset:3072
	ds_read_b128 v[208:211], v190 offset:4096
	ds_read_b128 v[212:215], v190 offset:5120
	ds_read_b128 v[216:219], v190 offset:6144
	ds_read_b128 v[220:223], v190 offset:7168
	global_load_lds_dwordx4 v[170:171], off
	v_lshl_add_u64 v[170:171], s[0:1], 0, v[154:155]
	s_add_i32 m0, s29, 0xe000
	s_nop 0
	global_load_lds_dwordx4 v[170:171], off
	s_waitcnt vmcnt(8)
	s_waitcnt lgkmcnt(0)
	s_barrier
; #define PG8_STAGE(bufoff, gbase, voff) do { _Pragma("unroll") for (int _i = 0; _i < 2; ++_i) \
;         __builtin_amdgcn_global_load_lds((const unsigned*)((const char*)(gbase) + (voff)[_i]), (PG8_LAS unsigned*)(lds + (bufoff) + ldsw + _i * 8192), 16, 0, 0); } while (0)
; #define PG8_LDA(dst, b, h) do { _Pragma("unroll") for (int m = 0; m < 4; ++m) _Pragma("unroll") for (int k = 0; k < 2; ++k) dst[m][k] = *(const PG8_LAS bf16x8*)(lds + PG8_SA(b, h) + aoff + m * 2048 + k * 1024); } while (0)
; #define PG8_MMA(ai, bj, At, Bt) do { __builtin_amdgcn_s_setprio(1); _Pragma("unroll") for (int m = 0; m < 4; ++m) _Pragma("unroll") for (int n = 0; n < 2; ++n) _Pragma("unroll") for (int k = 0; k < 2; ++k) \
;         acc[ai][bj][m][n] = __builtin_amdgcn_mfma_f32_16x16x32_bf16(Bt[n][k], At[m][k], acc[ai][bj][m][n], 0, 0, 0); __builtin_amdgcn_s_setprio(0); } while (0)
; #define PG8_WAIT_V(n) asm volatile("s_waitcnt vmcnt(" #n ")" ::: "memory")
; #define PG8_WAIT_L(n) asm volatile("s_waitcnt lgkmcnt(" #n ")" ::: "memory")
; #define PG8_BAR __builtin_amdgcn_s_barrier()
; #define PG8_SCHED __builtin_amdgcn_sched_barrier(0)
; template <class Epi, class Sched, bool ALIGN_EPI = false, bool SP2 = false>
; __device__ __forceinline__ void gemm_phase(PG8_LAS unsigned char* lds, const Gemm g, const Sched& S, const Epi& E) {
;     ...
;             PG8_WAIT_V(8); PG8_WAIT_L(0); PG8_BAR; PG8_MMA(0, 0, At, B0); PG8_MMA(0, 1, At, B1); PG8_BAR; PG8_SCHED;
;             PG8_LDA(At, 0, 1); PG8_STAGE(PG8_SB(0, 0), b2, voffB); PG8_STAGE(PG8_SB(0, 1), b2 + hstep, voffB); PG8_STAGE(PG8_SA(0, 0), a2, voffA);
;             PG8_WAIT_V(8); PG8_WAIT_L(0); PG8_BAR; PG8_MMA(1, 0, At, B0); PG8_MMA(1, 1, At, B1); PG8_BAR; PG8_SCHED;
	s_setprio 0
	s_waitcnt lgkmcnt(0)
	v_mfma_f32_16x16x32_bf16 v[136:139], v[100:103], v[192:195], v[136:139]
	v_mfma_f32_16x16x32_bf16 v[132:135], v[140:143], v[192:195], v[132:135]
	v_mfma_f32_16x16x32_bf16 v[128:131], v[100:103], v[200:203], v[128:131]
	v_mfma_f32_16x16x32_bf16 v[124:127], v[140:143], v[200:203], v[124:127]
	v_mfma_f32_16x16x32_bf16 v[120:123], v[100:103], v[208:211], v[120:123]
	v_mfma_f32_16x16x32_bf16 v[116:119], v[140:143], v[208:211], v[116:119]
	v_mfma_f32_16x16x32_bf16 v[112:115], v[100:103], v[216:219], v[112:115]
	v_mfma_f32_16x16x32_bf16 v[108:111], v[140:143], v[216:219], v[108:111]
	v_mfma_f32_16x16x32_bf16 v[136:139], v[104:107], v[196:199], v[136:139]
	v_mfma_f32_16x16x32_bf16 v[132:135], v[144:147], v[196:199], v[132:135]
	v_mfma_f32_16x16x32_bf16 v[128:131], v[104:107], v[204:207], v[128:131]
	v_mfma_f32_16x16x32_bf16 v[124:127], v[144:147], v[204:207], v[124:127]
	v_mfma_f32_16x16x32_bf16 v[120:123], v[104:107], v[212:215], v[120:123]
	v_mfma_f32_16x16x32_bf16 v[116:119], v[144:147], v[212:215], v[116:119]
	v_mfma_f32_16x16x32_bf16 v[112:115], v[104:107], v[220:223], v[112:115]
	v_mfma_f32_16x16x32_bf16 v[108:111], v[144:147], v[220:223], v[108:111]
	v_mfma_f32_16x16x32_bf16 v[64:67], v[158:161], v[192:195], v[64:67]
	v_mfma_f32_16x16x32_bf16 v[60:63], v[166:169], v[192:195], v[60:63]
	v_mfma_f32_16x16x32_bf16 v[56:59], v[158:161], v[200:203], v[56:59]
	v_mfma_f32_16x16x32_bf16 v[52:55], v[166:169], v[200:203], v[52:55]
	v_mfma_f32_16x16x32_bf16 v[48:51], v[158:161], v[208:211], v[48:51]
	v_mfma_f32_16x16x32_bf16 v[44:47], v[166:169], v[208:211], v[44:47]
	v_mfma_f32_16x16x32_bf16 v[40:43], v[158:161], v[216:219], v[40:43]
	v_mfma_f32_16x16x32_bf16 v[36:39], v[166:169], v[216:219], v[36:39]
	v_mfma_f32_16x16x32_bf16 v[64:67], v[162:165], v[196:199], v[64:67]
	v_mfma_f32_16x16x32_bf16 v[60:63], v[184:187], v[196:199], v[60:63]
	v_mfma_f32_16x16x32_bf16 v[56:59], v[162:165], v[204:207], v[56:59]
	v_mfma_f32_16x16x32_bf16 v[52:55], v[184:187], v[204:207], v[52:55]
	v_mfma_f32_16x16x32_bf16 v[48:51], v[162:165], v[212:215], v[48:51]
	v_mfma_f32_16x16x32_bf16 v[44:47], v[184:187], v[212:215], v[44:47]
	v_mfma_f32_16x16x32_bf16 v[40:43], v[162:165], v[220:223], v[40:43]
	v_mfma_f32_16x16x32_bf16 v[36:39], v[184:187], v[220:223], v[36:39]
	s_barrier
	s_setprio 1
	s_add_i32 s61, s61, s28
	v_lshl_add_u64 v[170:171], s[14:15], 0, v[174:175]
	s_mov_b32 m0, s61
	ds_read_b128 v[192:195], v190 offset:16384
	ds_read_b128 v[196:199], v190 offset:17408
	ds_read_b128 v[200:203], v190 offset:18432
	ds_read_b128 v[204:207], v190 offset:19456
	ds_read_b128 v[208:211], v190 offset:20480
	ds_read_b128 v[212:215], v190 offset:21504
	ds_read_b128 v[216:219], v190 offset:22528
	ds_read_b128 v[220:223], v190 offset:23552
	global_load_lds_dwordx4 v[170:171], off
	s_add_i32 m0, s61, 0x2000
	s_add_u32 s62, s14, 0x100000
	v_lshl_add_u64 v[224:225], s[14:15], 0, v[148:149]
	s_addc_u32 s63, s15, 0
	s_add_i32 s61, s64, s28
	global_load_lds_dwordx4 v[224:225], off
	v_lshl_add_u64 v[226:227], s[62:63], 0, v[174:175]
	s_mov_b32 m0, s61
	v_lshl_add_u64 v[228:229], s[16:17], 0, v[150:151]
	global_load_lds_dwordx4 v[226:227], off
	v_lshl_add_u64 v[226:227], s[62:63], 0, v[148:149]
	s_add_i32 m0, s61, 0x2000
	s_nop 0
	global_load_lds_dwordx4 v[226:227], off
	v_lshl_add_u64 v[226:227], s[16:17], 0, v[152:153]
	s_mov_b32 m0, s29
	s_nop 0
	global_load_lds_dwordx4 v[226:227], off
	s_mov_b32 m0, s30
	s_nop 0
	global_load_lds_dwordx4 v[228:229], off
	s_waitcnt vmcnt(8)
	s_waitcnt lgkmcnt(0)
	s_barrier
	s_setprio 0
	s_waitcnt lgkmcnt(0)
	v_mfma_f32_16x16x32_bf16 v[96:99], v[100:103], v[192:195], v[96:99]
	v_mfma_f32_16x16x32_bf16 v[92:95], v[140:143], v[192:195], v[92:95]
	v_mfma_f32_16x16x32_bf16 v[88:91], v[100:103], v[200:203], v[88:91]
	v_mfma_f32_16x16x32_bf16 v[84:87], v[140:143], v[200:203], v[84:87]
	v_mfma_f32_16x16x32_bf16 v[80:83], v[100:103], v[208:211], v[80:83]
	v_mfma_f32_16x16x32_bf16 v[76:79], v[140:143], v[208:211], v[76:79]
	v_mfma_f32_16x16x32_bf16 v[72:75], v[100:103], v[216:219], v[72:75]
	v_mfma_f32_16x16x32_bf16 v[68:71], v[140:143], v[216:219], v[68:71]
	v_mfma_f32_16x16x32_bf16 v[96:99], v[104:107], v[196:199], v[96:99]
	v_mfma_f32_16x16x32_bf16 v[92:95], v[144:147], v[196:199], v[92:95]
	v_mfma_f32_16x16x32_bf16 v[88:91], v[104:107], v[204:207], v[88:91]
	v_mfma_f32_16x16x32_bf16 v[84:87], v[144:147], v[204:207], v[84:87]
	v_mfma_f32_16x16x32_bf16 v[80:83], v[104:107], v[212:215], v[80:83]
	v_mfma_f32_16x16x32_bf16 v[76:79], v[144:147], v[212:215], v[76:79]
	v_mfma_f32_16x16x32_bf16 v[72:75], v[104:107], v[220:223], v[72:75]
	v_mfma_f32_16x16x32_bf16 v[68:71], v[144:147], v[220:223], v[68:71]
	v_mfma_f32_16x16x32_bf16 v[32:35], v[158:161], v[192:195], v[32:35]
	v_mfma_f32_16x16x32_bf16 v[28:31], v[166:169], v[192:195], v[28:31]
	v_mfma_f32_16x16x32_bf16 v[24:27], v[158:161], v[200:203], v[24:27]
	v_mfma_f32_16x16x32_bf16 v[20:23], v[166:169], v[200:203], v[20:23]
	v_mfma_f32_16x16x32_bf16 v[16:19], v[158:161], v[208:211], v[16:19]
	v_mfma_f32_16x16x32_bf16 v[12:15], v[166:169], v[208:211], v[12:15]
	v_mfma_f32_16x16x32_bf16 v[8:11], v[158:161], v[216:219], v[8:11]
	v_mfma_f32_16x16x32_bf16 v[4:7], v[166:169], v[216:219], v[4:7]
	v_mfma_f32_16x16x32_bf16 v[32:35], v[162:165], v[196:199], v[32:35]
	v_mfma_f32_16x16x32_bf16 v[28:31], v[184:187], v[196:199], v[28:31]
	v_mfma_f32_16x16x32_bf16 v[24:27], v[162:165], v[204:207], v[24:27]
	v_mfma_f32_16x16x32_bf16 v[20:23], v[184:187], v[204:207], v[20:23]
	v_mfma_f32_16x16x32_bf16 v[16:19], v[162:165], v[212:215], v[16:19]
	v_mfma_f32_16x16x32_bf16 v[12:15], v[184:187], v[212:215], v[12:15]
	v_mfma_f32_16x16x32_bf16 v[8:11], v[162:165], v[220:223], v[8:11]
	v_mfma_f32_16x16x32_bf16 v[4:7], v[184:187], v[220:223], v[4:7]
	s_barrier
; #define PG8_STAGE(bufoff, gbase, voff) do { _Pragma("unroll") for (int _i = 0; _i < 2; ++_i) \
;         __builtin_amdgcn_global_load_lds((const unsigned*)((const char*)(gbase) + (voff)[_i]), (PG8_LAS unsigned*)(lds + (bufoff) + ldsw + _i * 8192), 16, 0, 0); } while (0)
; #define PG8_LDA(dst, b, h) do { _Pragma("unroll") for (int m = 0; m < 4; ++m) _Pragma("unroll") for (int k = 0; k < 2; ++k) dst[m][k] = *(const PG8_LAS bf16x8*)(lds + PG8_SA(b, h) + aoff + m * 2048 + k * 1024); } while (0)
; #define PG8_LDB(dst, b, h) do { _Pragma("unroll") for (int n = 0; n < 2; ++n) _Pragma("unroll") for (int k = 0; k < 2; ++k) dst[n][k] = *(const PG8_LAS bf16x8*)(lds + PG8_SB(b, h) + boff + n * 2048 + k * 1024); } while (0)
; #define PG8_MMA(ai, bj, At, Bt) do { __builtin_amdgcn_s_setprio(1); _Pragma("unroll") for (int m = 0; m < 4; ++m) _Pragma("unroll") for (int n = 0; n < 2; ++n) _Pragma("unroll") for (int k = 0; k < 2; ++k) \
;         acc[ai][bj][m][n] = __builtin_amdgcn_mfma_f32_16x16x32_bf16(Bt[n][k], At[m][k], acc[ai][bj][m][n], 0, 0, 0); __builtin_amdgcn_s_setprio(0); } while (0)
; #define PG8_WAIT_V(n) asm volatile("s_waitcnt vmcnt(" #n ")" ::: "memory")
; #define PG8_WAIT_L(n) asm volatile("s_waitcnt lgkmcnt(" #n ")" ::: "memory")
; #define PG8_BAR __builtin_amdgcn_s_barrier()
; #define PG8_SCHED __builtin_amdgcn_sched_barrier(0)
; template <class Epi, class Sched, bool ALIGN_EPI = false, bool SP2 = false>
; __device__ __forceinline__ void gemm_phase(PG8_LAS unsigned char* lds, const Gemm g, const Sched& S, const Epi& E) {
;     ...
;             PG8_WAIT_V(8); PG8_WAIT_L(0); PG8_BAR; PG8_MMA(1, 0, At, B0); PG8_MMA(1, 1, At, B1); PG8_BAR; PG8_SCHED;
;             PG8_LDB(B0, 1, 0); PG8_LDB(B1, 1, 1); PG8_SCHED; PG8_LDA(At, 1, 0); PG8_STAGE(PG8_SA(0, 1), a2 + hstep, voffA);
;             PG8_WAIT_V(8); PG8_WAIT_L(0); PG8_BAR; PG8_MMA(0, 0, At, B0); PG8_MMA(0, 1, At, B1); PG8_BAR; PG8_SCHED;
	s_setprio 1
	s_add_i32 s61, 0, 0x18000
	s_add_i32 s62, 0, 0x1c000
	v_add_u32_e32 v144, s61, v188
	v_add_u32_e32 v184, s62, v188
	ds_read_b128 v[100:103], v144
	ds_read_b128 v[104:107], v144 offset:1024
	ds_read_b128 v[140:143], v144 offset:2048
	ds_read_b128 v[144:147], v144 offset:3072
	ds_read_b128 v[158:161], v184
	ds_read_b128 v[162:165], v184 offset:1024
	ds_read_b128 v[166:169], v184 offset:2048
	ds_read_b128 v[184:187], v184 offset:3072
	s_add_u32 s16, s16, 0x100000
	s_addc_u32 s17, s17, 0
	s_mov_b32 m0, s31
	v_lshl_add_u64 v[230:231], s[16:17], 0, v[152:153]
	ds_read_b128 v[192:195], v190 offset:32768
	ds_read_b128 v[196:199], v190 offset:33792
	ds_read_b128 v[200:203], v190 offset:34816
	ds_read_b128 v[204:207], v190 offset:35840
	ds_read_b128 v[208:211], v190 offset:36864
	ds_read_b128 v[212:215], v190 offset:37888
	ds_read_b128 v[216:219], v190 offset:38912
	ds_read_b128 v[220:223], v190 offset:39936
	global_load_lds_dwordx4 v[230:231], off
	v_lshl_add_u64 v[230:231], s[16:17], 0, v[150:151]
	s_mov_b32 m0, s34
	s_nop 0
	global_load_lds_dwordx4 v[230:231], off
	s_waitcnt vmcnt(8)
	s_waitcnt lgkmcnt(0)
	s_barrier
	s_setprio 0
	s_waitcnt lgkmcnt(0)
	v_mfma_f32_16x16x32_bf16 v[136:139], v[100:103], v[192:195], v[136:139]
	v_mfma_f32_16x16x32_bf16 v[132:135], v[140:143], v[192:195], v[132:135]
	v_mfma_f32_16x16x32_bf16 v[128:131], v[100:103], v[200:203], v[128:131]
	v_mfma_f32_16x16x32_bf16 v[124:127], v[140:143], v[200:203], v[124:127]
	v_mfma_f32_16x16x32_bf16 v[120:123], v[100:103], v[208:211], v[120:123]
	v_mfma_f32_16x16x32_bf16 v[116:119], v[140:143], v[208:211], v[116:119]
	v_mfma_f32_16x16x32_bf16 v[112:115], v[100:103], v[216:219], v[112:115]
	v_mfma_f32_16x16x32_bf16 v[108:111], v[140:143], v[216:219], v[108:111]
	v_mfma_f32_16x16x32_bf16 v[136:139], v[104:107], v[196:199], v[136:139]
	v_mfma_f32_16x16x32_bf16 v[132:135], v[144:147], v[196:199], v[132:135]
	v_mfma_f32_16x16x32_bf16 v[128:131], v[104:107], v[204:207], v[128:131]
	v_mfma_f32_16x16x32_bf16 v[124:127], v[144:147], v[204:207], v[124:127]
	v_mfma_f32_16x16x32_bf16 v[120:123], v[104:107], v[212:215], v[120:123]
	v_mfma_f32_16x16x32_bf16 v[116:119], v[144:147], v[212:215], v[116:119]
	v_mfma_f32_16x16x32_bf16 v[112:115], v[104:107], v[220:223], v[112:115]
	v_mfma_f32_16x16x32_bf16 v[108:111], v[144:147], v[220:223], v[108:111]
	v_mfma_f32_16x16x32_bf16 v[64:67], v[158:161], v[192:195], v[64:67]
	v_mfma_f32_16x16x32_bf16 v[60:63], v[166:169], v[192:195], v[60:63]
	v_mfma_f32_16x16x32_bf16 v[56:59], v[158:161], v[200:203], v[56:59]
	v_mfma_f32_16x16x32_bf16 v[52:55], v[166:169], v[200:203], v[52:55]
	v_mfma_f32_16x16x32_bf16 v[48:51], v[158:161], v[208:211], v[48:51]
	v_mfma_f32_16x16x32_bf16 v[44:47], v[166:169], v[208:211], v[44:47]
	v_mfma_f32_16x16x32_bf16 v[40:43], v[158:161], v[216:219], v[40:43]
	v_mfma_f32_16x16x32_bf16 v[36:39], v[166:169], v[216:219], v[36:39]
	v_mfma_f32_16x16x32_bf16 v[64:67], v[162:165], v[196:199], v[64:67]
	v_mfma_f32_16x16x32_bf16 v[60:63], v[184:187], v[196:199], v[60:63]
	v_mfma_f32_16x16x32_bf16 v[56:59], v[162:165], v[204:207], v[56:59]
	v_mfma_f32_16x16x32_bf16 v[52:55], v[184:187], v[204:207], v[52:55]
	v_mfma_f32_16x16x32_bf16 v[48:51], v[162:165], v[212:215], v[48:51]
	v_mfma_f32_16x16x32_bf16 v[44:47], v[184:187], v[212:215], v[44:47]
	v_mfma_f32_16x16x32_bf16 v[40:43], v[162:165], v[220:223], v[40:43]
	v_mfma_f32_16x16x32_bf16 v[36:39], v[184:187], v[220:223], v[36:39]
	s_barrier
; #define PG8_STAGE(bufoff, gbase, voff) do { _Pragma("unroll") for (int _i = 0; _i < 2; ++_i) \
;         __builtin_amdgcn_global_load_lds((const unsigned*)((const char*)(gbase) + (voff)[_i]), (PG8_LAS unsigned*)(lds + (bufoff) + ldsw + _i * 8192), 16, 0, 0); } while (0)
; #define PG8_LDA(dst, b, h) do { _Pragma("unroll") for (int m = 0; m < 4; ++m) _Pragma("unroll") for (int k = 0; k < 2; ++k) dst[m][k] = *(const PG8_LAS bf16x8*)(lds + PG8_SA(b, h) + aoff + m * 2048 + k * 1024); } while (0)
; #define PG8_MMA(ai, bj, At, Bt) do { __builtin_amdgcn_s_setprio(1); _Pragma("unroll") for (int m = 0; m < 4; ++m) _Pragma("unroll") for (int n = 0; n < 2; ++n) _Pragma("unroll") for (int k = 0; k < 2; ++k) \
;         acc[ai][bj][m][n] = __builtin_amdgcn_mfma_f32_16x16x32_bf16(Bt[n][k], At[m][k], acc[ai][bj][m][n], 0, 0, 0); __builtin_amdgcn_s_setprio(0); } while (0)
; #define PG8_WAIT_V(n) asm volatile("s_waitcnt vmcnt(" #n ")" ::: "memory")
; #define PG8_WAIT_L(n) asm volatile("s_waitcnt lgkmcnt(" #n ")" ::: "memory")
; #define PG8_BAR __builtin_amdgcn_s_barrier()
; #define PG8_SCHED __builtin_amdgcn_sched_barrier(0)
; template <class Epi, class Sched, bool ALIGN_EPI = false, bool SP2 = false>
; __device__ __forceinline__ void gemm_phase(PG8_LAS unsigned char* lds, const Gemm g, const Sched& S, const Epi& E) {
;     ...
;         for (int t = 0; t < nt; t += 2) {
;             const bool last = (t == nt - 2);
;             const char* a1 = cA + (size_t)(t + 1) * kstep;
;             const char* a2 = last ? nA : cA + (size_t)(t + 2) * kstep; const char* b2 = last ? nB : cB + (size_t)(t + 2) * kstep;
;             const char* a3 = a2 + kstep; const char* b3 = b2 + kstep;
;     ...
;             PG8_WAIT_V(8); PG8_WAIT_L(0); PG8_BAR; PG8_MMA(0, 0, At, B0); PG8_MMA(0, 1, At, B1); PG8_BAR; PG8_SCHED;
;             PG8_LDA(At, 1, 1); PG8_STAGE(PG8_SB(1, 0), b3, voffB); PG8_STAGE(PG8_SB(1, 1), b3 + hstep, voffB); PG8_STAGE(PG8_SA(1, 0), a3, voffA);
;             PG8_WAIT_V(8); PG8_WAIT_L(0); PG8_BAR; PG8_MMA(1, 0, At, B0); PG8_MMA(1, 1, At, B1); PG8_BAR; PG8_SCHED;
	s_setprio 1
	s_add_i32 s16, s61, s28
	v_lshl_add_u64 v[170:171], v[170:171], 0, s[10:11]
	s_mov_b32 m0, s16
	ds_read_b128 v[192:195], v190 offset:49152
	ds_read_b128 v[196:199], v190 offset:50176
	ds_read_b128 v[200:203], v190 offset:51200
	ds_read_b128 v[204:207], v190 offset:52224
	ds_read_b128 v[208:211], v190 offset:53248
	ds_read_b128 v[212:215], v190 offset:54272
	ds_read_b128 v[216:219], v190 offset:55296
	ds_read_b128 v[220:223], v190 offset:56320
	global_load_lds_dwordx4 v[170:171], off
	s_add_i32 m0, s16, 0x2000
	s_add_u32 s14, s14, 0x100080
	v_lshl_add_u64 v[170:171], v[224:225], 0, s[10:11]
	s_addc_u32 s15, s15, 0
	s_add_i32 s16, s62, s28
	global_load_lds_dwordx4 v[170:171], off
	v_lshl_add_u64 v[170:171], s[14:15], 0, v[174:175]
	s_mov_b32 m0, s16
	s_nop 0
	global_load_lds_dwordx4 v[170:171], off
	v_lshl_add_u64 v[170:171], s[14:15], 0, v[148:149]
	s_add_i32 m0, s16, 0x2000
	s_nop 0
	global_load_lds_dwordx4 v[170:171], off
	v_lshl_add_u64 v[170:171], v[226:227], 0, s[10:11]
	s_mov_b32 m0, s35
	s_nop 0
	global_load_lds_dwordx4 v[170:171], off
	v_lshl_add_u64 v[170:171], v[228:229], 0, s[10:11]
	s_mov_b32 m0, s38
	s_nop 0
	global_load_lds_dwordx4 v[170:171], off
	s_waitcnt vmcnt(8)
	s_waitcnt lgkmcnt(0)
	s_barrier
	s_setprio 0
	s_waitcnt lgkmcnt(0)
	v_mfma_f32_16x16x32_bf16 v[96:99], v[100:103], v[192:195], v[96:99]
	v_mfma_f32_16x16x32_bf16 v[92:95], v[140:143], v[192:195], v[92:95]
	v_mfma_f32_16x16x32_bf16 v[88:91], v[100:103], v[200:203], v[88:91]
	v_mfma_f32_16x16x32_bf16 v[84:87], v[140:143], v[200:203], v[84:87]
	v_mfma_f32_16x16x32_bf16 v[80:83], v[100:103], v[208:211], v[80:83]
	v_mfma_f32_16x16x32_bf16 v[76:79], v[140:143], v[208:211], v[76:79]
	v_mfma_f32_16x16x32_bf16 v[72:75], v[100:103], v[216:219], v[72:75]
	v_mfma_f32_16x16x32_bf16 v[68:71], v[140:143], v[216:219], v[68:71]
	v_mfma_f32_16x16x32_bf16 v[96:99], v[104:107], v[196:199], v[96:99]
	v_mfma_f32_16x16x32_bf16 v[92:95], v[144:147], v[196:199], v[92:95]
	v_mfma_f32_16x16x32_bf16 v[88:91], v[104:107], v[204:207], v[88:91]
	v_mfma_f32_16x16x32_bf16 v[84:87], v[144:147], v[204:207], v[84:87]
	v_mfma_f32_16x16x32_bf16 v[80:83], v[104:107], v[212:215], v[80:83]
	v_mfma_f32_16x16x32_bf16 v[76:79], v[144:147], v[212:215], v[76:79]
	v_mfma_f32_16x16x32_bf16 v[72:75], v[104:107], v[220:223], v[72:75]
	v_mfma_f32_16x16x32_bf16 v[68:71], v[144:147], v[220:223], v[68:71]
	v_mfma_f32_16x16x32_bf16 v[32:35], v[158:161], v[192:195], v[32:35]
	v_mfma_f32_16x16x32_bf16 v[28:31], v[166:169], v[192:195], v[28:31]
	v_mfma_f32_16x16x32_bf16 v[24:27], v[158:161], v[200:203], v[24:27]
	v_mfma_f32_16x16x32_bf16 v[20:23], v[166:169], v[200:203], v[20:23]
	v_mfma_f32_16x16x32_bf16 v[16:19], v[158:161], v[208:211], v[16:19]
	v_mfma_f32_16x16x32_bf16 v[12:15], v[166:169], v[208:211], v[12:15]
	v_mfma_f32_16x16x32_bf16 v[8:11], v[158:161], v[216:219], v[8:11]
	v_mfma_f32_16x16x32_bf16 v[4:7], v[166:169], v[216:219], v[4:7]
	v_mfma_f32_16x16x32_bf16 v[32:35], v[162:165], v[196:199], v[32:35]
	v_mfma_f32_16x16x32_bf16 v[28:31], v[184:187], v[196:199], v[28:31]
	v_mfma_f32_16x16x32_bf16 v[24:27], v[162:165], v[204:207], v[24:27]
	v_mfma_f32_16x16x32_bf16 v[20:23], v[184:187], v[204:207], v[20:23]
	v_mfma_f32_16x16x32_bf16 v[16:19], v[162:165], v[212:215], v[16:19]
	v_mfma_f32_16x16x32_bf16 v[12:15], v[184:187], v[212:215], v[12:15]
	v_mfma_f32_16x16x32_bf16 v[8:11], v[162:165], v[220:223], v[8:11]
	v_mfma_f32_16x16x32_bf16 v[4:7], v[184:187], v[220:223], v[4:7]
	s_barrier
	s_setprio 1
	s_add_i32 s60, s60, 2
	s_add_u32 s53, s53, 0x100
	s_addc_u32 s59, s59, 0
	s_add_u32 s0, s0, 0x100
	s_addc_u32 s1, s1, 0
	s_cmp_gt_u32 s60, 61
	s_cbranch_scc0 .LBB0_485
	s_and_b64 vcc, exec, s[48:49]
	s_cbranch_vccz .LBB0_488
	s_barrier

; #define PG8_STAGE(bufoff, gbase, voff) do { _Pragma("unroll") for (int _i = 0; _i < 2; ++_i) \
;         __builtin_amdgcn_global_load_lds((const unsigned*)((const char*)(gbase) + (voff)[_i]), (PG8_LAS unsigned*)(lds + (bufoff) + ldsw + _i * 8192), 16, 0, 0); } while (0)
; #define PG8_LDA(dst, b, h) do { _Pragma("unroll") for (int m = 0; m < 4; ++m) _Pragma("unroll") for (int k = 0; k < 2; ++k) dst[m][k] = *(const PG8_LAS bf16x8*)(lds + PG8_SA(b, h) + aoff + m * 2048 + k * 1024); } while (0)
; #define PG8_LDB(dst, b, h) do { _Pragma("unroll") for (int n = 0; n < 2; ++n) _Pragma("unroll") for (int k = 0; k < 2; ++k) dst[n][k] = *(const PG8_LAS bf16x8*)(lds + PG8_SB(b, h) + boff + n * 2048 + k * 1024); } while (0)
; #define PG8_WAIT_V(n) asm volatile("s_waitcnt vmcnt(" #n ")" ::: "memory")
; #define PG8_WAIT_L(n) asm volatile("s_waitcnt lgkmcnt(" #n ")" ::: "memory")
; #define PG8_BAR __builtin_amdgcn_s_barrier()
; template <class Epi, class Sched, bool ALIGN_EPI = false, bool SP2 = false>
; __device__ __forceinline__ void gemm_phase(PG8_LAS unsigned char* lds, const Gemm g, const Sched& S, const Epi& E) {
;     ...
;         const bool has_next = S.next(ui + 1, nxt);
;         const char* nA = has_next ? (const char*)g.A + (size_t)nxt.pm * tstep : cA; const char* nB = has_next ? (const char*)g.Bt + (size_t)nxt.pn * tstep : cB;
;         for (int t = 0; t < nt; t += 2) {
;             const bool last = (t == nt - 2);
;             const char* a1 = cA + (size_t)(t + 1) * kstep;
;             const char* a2 = last ? nA : cA + (size_t)(t + 2) * kstep; const char* b2 = last ? nB : cB + (size_t)(t + 2) * kstep;
;             const char* a3 = a2 + kstep; const char* b3 = b2 + kstep;
;             if (last && has_next) S.a_ready(nxt);
;             if constexpr (SP2) {
;             PG8_LDB(B0, 0, 0); PG8_LDB(B1, 0, 1); PG8_SCHED; PG8_LDA(At, 0, 0); PG8_STAGE(PG8_SA(1, 1), a1 + hstep, voffA);
;             PG8_WAIT_V(8); PG8_WAIT_L(0); PG8_BAR; PG8_MMA(0, 0, At, B0); PG8_MMA(0, 1, At, B1); PG8_BAR; PG8_SCHED;
;     ...
; #pragma unroll
;         for (int a = 0; a < 2; ++a)
; #pragma unroll
;             for (int b = 0; b < 2; ++b)
; #pragma unroll
;                 for (int m = 0; m < 4; ++m)
; #pragma unroll
;                     for (int n = 0; n < 2; ++n) acc[a][b][m][n] = (f32x4){0.f, 0.f, 0.f, 0.f};
;         cur = nxt; cA = nA; cB = nB; ++ui;
.LBB0_562:
	s_ashr_i32 s39, s38, 31
	s_lshl_b64 s[26:27], s[38:39], 20
	s_add_u32 s44, s22, s26
	s_addc_u32 s45, s23, s27
	s_and_b64 s[26:27], s[42:43], exec
	s_cselect_b32 s39, s45, s19
	s_cselect_b32 s59, s44, s18
	s_ashr_i32 s37, s36, 31
	s_lshl_b64 s[26:27], s[36:37], 20
	s_add_u32 s46, s24, s26
	s_addc_u32 s47, s25, s27
	s_and_b64 s[26:27], s[42:43], exec
	s_cselect_b32 s37, s47, s1
	s_cselect_b32 s60, s46, s0
	s_add_u32 s61, s0, 0x100
	s_addc_u32 s62, s1, 0
	s_add_u32 s0, s18, 0x80080
	v_mov_b32_e32 v4, 0
	s_addc_u32 s1, s19, 0
	s_mov_b32 s63, -2
	s_waitcnt lgkmcnt(0)
	v_mov_b32_e32 v5, v4
	v_mov_b32_e32 v6, v4
	v_mov_b32_e32 v7, v4
	v_mov_b32_e32 v8, v4
	v_mov_b32_e32 v9, v4
	v_mov_b32_e32 v10, v4
	v_mov_b32_e32 v11, v4
	v_mov_b32_e32 v20, v4
	v_mov_b32_e32 v21, v4
	v_mov_b32_e32 v22, v4
	v_mov_b32_e32 v23, v4
	v_mov_b32_e32 v24, v4
	v_mov_b32_e32 v25, v4
	v_mov_b32_e32 v26, v4
	v_mov_b32_e32 v27, v4
	s_waitcnt vmcnt(0)
	v_mov_b32_e32 v36, v4
	v_mov_b32_e32 v37, v4
	v_mov_b32_e32 v38, v4
	v_mov_b32_e32 v39, v4
	v_mov_b32_e32 v40, v4
	v_mov_b32_e32 v41, v4
	v_mov_b32_e32 v42, v4
	v_mov_b32_e32 v43, v4
	v_mov_b32_e32 v52, v4
	v_mov_b32_e32 v53, v4
	v_mov_b32_e32 v54, v4
	v_mov_b32_e32 v55, v4
	v_mov_b32_e32 v56, v4
	v_mov_b32_e32 v57, v4
	v_mov_b32_e32 v58, v4
	v_mov_b32_e32 v59, v4
	v_mov_b32_e32 v12, v4
	v_mov_b32_e32 v13, v4
	v_mov_b32_e32 v14, v4
	v_mov_b32_e32 v15, v4
	v_mov_b32_e32 v16, v4
	v_mov_b32_e32 v17, v4
	v_mov_b32_e32 v18, v4
	v_mov_b32_e32 v19, v4
	v_mov_b32_e32 v28, v4
	v_mov_b32_e32 v29, v4
	v_mov_b32_e32 v30, v4
	v_mov_b32_e32 v31, v4
	v_mov_b32_e32 v32, v4
	v_mov_b32_e32 v33, v4
	v_mov_b32_e32 v34, v4
	v_mov_b32_e32 v35, v4
	v_mov_b32_e32 v44, v4
	v_mov_b32_e32 v45, v4
	v_mov_b32_e32 v46, v4
	v_mov_b32_e32 v47, v4
	v_mov_b32_e32 v48, v4
	v_mov_b32_e32 v49, v4
	v_mov_b32_e32 v50, v4
	v_mov_b32_e32 v51, v4
	v_mov_b32_e32 v60, v4
	v_mov_b32_e32 v61, v4
	v_mov_b32_e32 v62, v4
	v_mov_b32_e32 v63, v4
	v_mov_b32_e32 v64, v4
	v_mov_b32_e32 v65, v4
	v_mov_b32_e32 v66, v4
	v_mov_b32_e32 v67, v4
	v_mov_b32_e32 v68, v4
	v_mov_b32_e32 v69, v4
	v_mov_b32_e32 v70, v4
	v_mov_b32_e32 v71, v4
	v_mov_b32_e32 v72, v4
	v_mov_b32_e32 v73, v4
	v_mov_b32_e32 v74, v4
	v_mov_b32_e32 v75, v4
	v_mov_b32_e32 v84, v4
	v_mov_b32_e32 v85, v4
	v_mov_b32_e32 v86, v4
	v_mov_b32_e32 v87, v4
	v_mov_b32_e32 v88, v4
	v_mov_b32_e32 v89, v4
	v_mov_b32_e32 v90, v4
	v_mov_b32_e32 v91, v4
	v_mov_b32_e32 v100, v4
	v_mov_b32_e32 v101, v4
	v_mov_b32_e32 v102, v4
	v_mov_b32_e32 v103, v4
	v_mov_b32_e32 v104, v4
	v_mov_b32_e32 v105, v4
	v_mov_b32_e32 v106, v4
	v_mov_b32_e32 v107, v4
	v_mov_b32_e32 v116, v4
	v_mov_b32_e32 v117, v4
	v_mov_b32_e32 v118, v4
	v_mov_b32_e32 v119, v4
	v_mov_b32_e32 v120, v4
	v_mov_b32_e32 v121, v4
	v_mov_b32_e32 v122, v4
	v_mov_b32_e32 v123, v4
	v_mov_b32_e32 v76, v4
	v_mov_b32_e32 v77, v4
	v_mov_b32_e32 v78, v4
	v_mov_b32_e32 v79, v4
	v_mov_b32_e32 v80, v4
	v_mov_b32_e32 v81, v4
	v_mov_b32_e32 v82, v4
	v_mov_b32_e32 v83, v4
	v_mov_b32_e32 v92, v4
	v_mov_b32_e32 v93, v4
	v_mov_b32_e32 v94, v4
	v_mov_b32_e32 v95, v4
	v_mov_b32_e32 v96, v4
	v_mov_b32_e32 v97, v4
	v_mov_b32_e32 v98, v4
	v_mov_b32_e32 v99, v4
	v_mov_b32_e32 v108, v4
	v_mov_b32_e32 v109, v4
	v_mov_b32_e32 v110, v4
	v_mov_b32_e32 v111, v4
	v_mov_b32_e32 v112, v4
	v_mov_b32_e32 v113, v4
	v_mov_b32_e32 v114, v4
	v_mov_b32_e32 v115, v4
	v_mov_b32_e32 v124, v4
	v_mov_b32_e32 v125, v4
	v_mov_b32_e32 v126, v4
	v_mov_b32_e32 v127, v4
	v_mov_b32_e32 v128, v4
	v_mov_b32_e32 v129, v4
	v_mov_b32_e32 v130, v4
	v_mov_b32_e32 v131, v4
	s_setprio 1
.LBB0_563:
	s_add_u32 s18, s0, 0xfff80080
	s_addc_u32 s19, s1, -1
	s_add_i32 s64, 0, 0x10000
	s_cmp_eq_u32 s63, 28
	s_cselect_b32 s27, s39, s19
	s_cselect_b32 s26, s59, s18
	s_cselect_b32 s19, s37, s62
	s_cselect_b32 s18, s60, s61
	s_add_i32 s66, 0, 0x14000
	v_add_u32_e32 v144, s64, v167
	v_add_u32_e32 v170, s66, v167
	ds_read_b128 v[132:135], v144
	ds_read_b128 v[136:139], v144 offset:1024
	ds_read_b128 v[140:143], v144 offset:2048
	ds_read_b128 v[144:147], v144 offset:3072
	ds_read_b128 v[158:161], v170
	ds_read_b128 v[162:165], v170 offset:1024
	ds_read_b128 v[184:187], v170 offset:2048
	ds_read_b128 v[188:191], v170 offset:3072
	v_lshl_add_u64 v[170:171], s[0:1], 0, v[156:157]
	s_add_i32 m0, s49, 0xc000
	ds_read_b128 v[192:195], v169
	ds_read_b128 v[196:199], v169 offset:1024
	ds_read_b128 v[200:203], v169 offset:2048
	ds_read_b128 v[204:207], v169 offset:3072
	ds_read_b128 v[208:211], v169 offset:4096
	ds_read_b128 v[212:215], v169 offset:5120
	ds_read_b128 v[216:219], v169 offset:6144
	ds_read_b128 v[220:223], v169 offset:7168
	global_load_lds_dwordx4 v[170:171], off
	v_lshl_add_u64 v[170:171], s[0:1], 0, v[154:155]
	s_add_i32 m0, s49, 0xe000
	s_nop 0
	global_load_lds_dwordx4 v[170:171], off
	s_waitcnt vmcnt(8)
	s_waitcnt lgkmcnt(0)
	s_barrier
; #define PG8_STAGE(bufoff, gbase, voff) do { _Pragma("unroll") for (int _i = 0; _i < 2; ++_i) \
;         __builtin_amdgcn_global_load_lds((const unsigned*)((const char*)(gbase) + (voff)[_i]), (PG8_LAS unsigned*)(lds + (bufoff) + ldsw + _i * 8192), 16, 0, 0); } while (0)
; #define PG8_LDA(dst, b, h) do { _Pragma("unroll") for (int m = 0; m < 4; ++m) _Pragma("unroll") for (int k = 0; k < 2; ++k) dst[m][k] = *(const PG8_LAS bf16x8*)(lds + PG8_SA(b, h) + aoff + m * 2048 + k * 1024); } while (0)
; #define PG8_MMA(ai, bj, At, Bt) do { __builtin_amdgcn_s_setprio(1); _Pragma("unroll") for (int m = 0; m < 4; ++m) _Pragma("unroll") for (int n = 0; n < 2; ++n) _Pragma("unroll") for (int k = 0; k < 2; ++k) \
;         acc[ai][bj][m][n] = __builtin_amdgcn_mfma_f32_16x16x32_bf16(Bt[n][k], At[m][k], acc[ai][bj][m][n], 0, 0, 0); __builtin_amdgcn_s_setprio(0); } while (0)
; #define PG8_WAIT_V(n) asm volatile("s_waitcnt vmcnt(" #n ")" ::: "memory")
; #define PG8_WAIT_L(n) asm volatile("s_waitcnt lgkmcnt(" #n ")" ::: "memory")
; #define PG8_BAR __builtin_amdgcn_s_barrier()
; #define PG8_SCHED __builtin_amdgcn_sched_barrier(0)
; template <class Epi, class Sched, bool ALIGN_EPI = false, bool SP2 = false>
; __device__ __forceinline__ void gemm_phase(PG8_LAS unsigned char* lds, const Gemm g, const Sched& S, const Epi& E) {
;     ...
;             PG8_WAIT_V(8); PG8_WAIT_L(0); PG8_BAR; PG8_MMA(0, 0, At, B0); PG8_MMA(0, 1, At, B1); PG8_BAR; PG8_SCHED;
;             PG8_LDA(At, 0, 1); PG8_STAGE(PG8_SB(0, 0), b2, voffB); PG8_STAGE(PG8_SB(0, 1), b2 + hstep, voffB); PG8_STAGE(PG8_SA(0, 0), a2, voffA);
;             PG8_WAIT_V(8); PG8_WAIT_L(0); PG8_BAR; PG8_MMA(1, 0, At, B0); PG8_MMA(1, 1, At, B1); PG8_BAR; PG8_SCHED;
	s_setprio 0
	s_waitcnt lgkmcnt(0)
	v_mfma_f32_16x16x32_bf16 v[128:131], v[132:135], v[192:195], v[128:131]
	v_mfma_f32_16x16x32_bf16 v[124:127], v[140:143], v[192:195], v[124:127]
	v_mfma_f32_16x16x32_bf16 v[112:115], v[132:135], v[200:203], v[112:115]
	v_mfma_f32_16x16x32_bf16 v[108:111], v[140:143], v[200:203], v[108:111]
	v_mfma_f32_16x16x32_bf16 v[96:99], v[132:135], v[208:211], v[96:99]
	v_mfma_f32_16x16x32_bf16 v[92:95], v[140:143], v[208:211], v[92:95]
	v_mfma_f32_16x16x32_bf16 v[80:83], v[132:135], v[216:219], v[80:83]
	v_mfma_f32_16x16x32_bf16 v[76:79], v[140:143], v[216:219], v[76:79]
	v_mfma_f32_16x16x32_bf16 v[128:131], v[136:139], v[196:199], v[128:131]
	v_mfma_f32_16x16x32_bf16 v[124:127], v[144:147], v[196:199], v[124:127]
	v_mfma_f32_16x16x32_bf16 v[112:115], v[136:139], v[204:207], v[112:115]
	v_mfma_f32_16x16x32_bf16 v[108:111], v[144:147], v[204:207], v[108:111]
	v_mfma_f32_16x16x32_bf16 v[96:99], v[136:139], v[212:215], v[96:99]
	v_mfma_f32_16x16x32_bf16 v[92:95], v[144:147], v[212:215], v[92:95]
	v_mfma_f32_16x16x32_bf16 v[80:83], v[136:139], v[220:223], v[80:83]
	v_mfma_f32_16x16x32_bf16 v[76:79], v[144:147], v[220:223], v[76:79]
	v_mfma_f32_16x16x32_bf16 v[120:123], v[158:161], v[192:195], v[120:123]
	v_mfma_f32_16x16x32_bf16 v[116:119], v[184:187], v[192:195], v[116:119]
	v_mfma_f32_16x16x32_bf16 v[104:107], v[158:161], v[200:203], v[104:107]
	v_mfma_f32_16x16x32_bf16 v[100:103], v[184:187], v[200:203], v[100:103]
	v_mfma_f32_16x16x32_bf16 v[88:91], v[158:161], v[208:211], v[88:91]
	v_mfma_f32_16x16x32_bf16 v[84:87], v[184:187], v[208:211], v[84:87]
	v_mfma_f32_16x16x32_bf16 v[72:75], v[158:161], v[216:219], v[72:75]
	v_mfma_f32_16x16x32_bf16 v[68:71], v[184:187], v[216:219], v[68:71]
	v_mfma_f32_16x16x32_bf16 v[120:123], v[162:165], v[196:199], v[120:123]
	v_mfma_f32_16x16x32_bf16 v[116:119], v[188:191], v[196:199], v[116:119]
	v_mfma_f32_16x16x32_bf16 v[104:107], v[162:165], v[204:207], v[104:107]
	v_mfma_f32_16x16x32_bf16 v[100:103], v[188:191], v[204:207], v[100:103]
	v_mfma_f32_16x16x32_bf16 v[88:91], v[162:165], v[212:215], v[88:91]
	v_mfma_f32_16x16x32_bf16 v[84:87], v[188:191], v[212:215], v[84:87]
	v_mfma_f32_16x16x32_bf16 v[72:75], v[162:165], v[220:223], v[72:75]
	v_mfma_f32_16x16x32_bf16 v[68:71], v[188:191], v[220:223], v[68:71]
	s_barrier
	s_setprio 1
	s_add_i32 s64, s64, s48
	v_lshl_add_u64 v[170:171], s[18:19], 0, v[174:175]
	s_mov_b32 m0, s64
	ds_read_b128 v[192:195], v169 offset:16384
	ds_read_b128 v[196:199], v169 offset:17408
	ds_read_b128 v[200:203], v169 offset:18432
	ds_read_b128 v[204:207], v169 offset:19456
	ds_read_b128 v[208:211], v169 offset:20480
	ds_read_b128 v[212:215], v169 offset:21504
	ds_read_b128 v[216:219], v169 offset:22528
	ds_read_b128 v[220:223], v169 offset:23552
	global_load_lds_dwordx4 v[170:171], off
	s_add_i32 m0, s64, 0x2000
	s_add_u32 s64, s18, 0x80000
	v_lshl_add_u64 v[224:225], s[18:19], 0, v[148:149]
	s_addc_u32 s65, s19, 0
	s_add_i32 s66, s66, s48
	global_load_lds_dwordx4 v[224:225], off
	v_lshl_add_u64 v[226:227], s[64:65], 0, v[174:175]
	s_mov_b32 m0, s66
	v_lshl_add_u64 v[228:229], s[26:27], 0, v[150:151]
	global_load_lds_dwordx4 v[226:227], off
	v_lshl_add_u64 v[226:227], s[64:65], 0, v[148:149]
	s_add_i32 m0, s66, 0x2000
	s_nop 0
	global_load_lds_dwordx4 v[226:227], off
	v_lshl_add_u64 v[226:227], s[26:27], 0, v[152:153]
	s_mov_b32 m0, s49
	s_nop 0
	global_load_lds_dwordx4 v[226:227], off
	s_mov_b32 m0, s50
	s_nop 0
	global_load_lds_dwordx4 v[228:229], off
	s_waitcnt vmcnt(8)
	s_waitcnt lgkmcnt(0)
	s_barrier
	s_setprio 0
	s_waitcnt lgkmcnt(0)
	v_mfma_f32_16x16x32_bf16 v[64:67], v[132:135], v[192:195], v[64:67]
	v_mfma_f32_16x16x32_bf16 v[60:63], v[140:143], v[192:195], v[60:63]
	v_mfma_f32_16x16x32_bf16 v[48:51], v[132:135], v[200:203], v[48:51]
	v_mfma_f32_16x16x32_bf16 v[44:47], v[140:143], v[200:203], v[44:47]
	v_mfma_f32_16x16x32_bf16 v[32:35], v[132:135], v[208:211], v[32:35]
	v_mfma_f32_16x16x32_bf16 v[28:31], v[140:143], v[208:211], v[28:31]
	v_mfma_f32_16x16x32_bf16 v[16:19], v[132:135], v[216:219], v[16:19]
	v_mfma_f32_16x16x32_bf16 v[12:15], v[140:143], v[216:219], v[12:15]
	v_mfma_f32_16x16x32_bf16 v[64:67], v[136:139], v[196:199], v[64:67]
	v_mfma_f32_16x16x32_bf16 v[60:63], v[144:147], v[196:199], v[60:63]
	v_mfma_f32_16x16x32_bf16 v[48:51], v[136:139], v[204:207], v[48:51]
	v_mfma_f32_16x16x32_bf16 v[44:47], v[144:147], v[204:207], v[44:47]
	v_mfma_f32_16x16x32_bf16 v[32:35], v[136:139], v[212:215], v[32:35]
	v_mfma_f32_16x16x32_bf16 v[28:31], v[144:147], v[212:215], v[28:31]
	v_mfma_f32_16x16x32_bf16 v[16:19], v[136:139], v[220:223], v[16:19]
	v_mfma_f32_16x16x32_bf16 v[12:15], v[144:147], v[220:223], v[12:15]
	v_mfma_f32_16x16x32_bf16 v[56:59], v[158:161], v[192:195], v[56:59]
	v_mfma_f32_16x16x32_bf16 v[52:55], v[184:187], v[192:195], v[52:55]
	v_mfma_f32_16x16x32_bf16 v[40:43], v[158:161], v[200:203], v[40:43]
	v_mfma_f32_16x16x32_bf16 v[36:39], v[184:187], v[200:203], v[36:39]
	v_mfma_f32_16x16x32_bf16 v[24:27], v[158:161], v[208:211], v[24:27]
	v_mfma_f32_16x16x32_bf16 v[20:23], v[184:187], v[208:211], v[20:23]
	v_mfma_f32_16x16x32_bf16 v[8:11], v[158:161], v[216:219], v[8:11]
	v_mfma_f32_16x16x32_bf16 v[4:7], v[184:187], v[216:219], v[4:7]
	v_mfma_f32_16x16x32_bf16 v[56:59], v[162:165], v[196:199], v[56:59]
	v_mfma_f32_16x16x32_bf16 v[52:55], v[188:191], v[196:199], v[52:55]
	v_mfma_f32_16x16x32_bf16 v[40:43], v[162:165], v[204:207], v[40:43]
	v_mfma_f32_16x16x32_bf16 v[36:39], v[188:191], v[204:207], v[36:39]
	v_mfma_f32_16x16x32_bf16 v[24:27], v[162:165], v[212:215], v[24:27]
	v_mfma_f32_16x16x32_bf16 v[20:23], v[188:191], v[212:215], v[20:23]
	v_mfma_f32_16x16x32_bf16 v[8:11], v[162:165], v[220:223], v[8:11]
	v_mfma_f32_16x16x32_bf16 v[4:7], v[188:191], v[220:223], v[4:7]
	s_barrier
; #define PG8_STAGE(bufoff, gbase, voff) do { _Pragma("unroll") for (int _i = 0; _i < 2; ++_i) \
;         __builtin_amdgcn_global_load_lds((const unsigned*)((const char*)(gbase) + (voff)[_i]), (PG8_LAS unsigned*)(lds + (bufoff) + ldsw + _i * 8192), 16, 0, 0); } while (0)
; #define PG8_LDA(dst, b, h) do { _Pragma("unroll") for (int m = 0; m < 4; ++m) _Pragma("unroll") for (int k = 0; k < 2; ++k) dst[m][k] = *(const PG8_LAS bf16x8*)(lds + PG8_SA(b, h) + aoff + m * 2048 + k * 1024); } while (0)
; #define PG8_LDB(dst, b, h) do { _Pragma("unroll") for (int n = 0; n < 2; ++n) _Pragma("unroll") for (int k = 0; k < 2; ++k) dst[n][k] = *(const PG8_LAS bf16x8*)(lds + PG8_SB(b, h) + boff + n * 2048 + k * 1024); } while (0)
; #define PG8_MMA(ai, bj, At, Bt) do { __builtin_amdgcn_s_setprio(1); _Pragma("unroll") for (int m = 0; m < 4; ++m) _Pragma("unroll") for (int n = 0; n < 2; ++n) _Pragma("unroll") for (int k = 0; k < 2; ++k) \
;         acc[ai][bj][m][n] = __builtin_amdgcn_mfma_f32_16x16x32_bf16(Bt[n][k], At[m][k], acc[ai][bj][m][n], 0, 0, 0); __builtin_amdgcn_s_setprio(0); } while (0)
; #define PG8_WAIT_V(n) asm volatile("s_waitcnt vmcnt(" #n ")" ::: "memory")
; #define PG8_WAIT_L(n) asm volatile("s_waitcnt lgkmcnt(" #n ")" ::: "memory")
; #define PG8_BAR __builtin_amdgcn_s_barrier()
; #define PG8_SCHED __builtin_amdgcn_sched_barrier(0)
; template <class Epi, class Sched, bool ALIGN_EPI = false, bool SP2 = false>
; __device__ __forceinline__ void gemm_phase(PG8_LAS unsigned char* lds, const Gemm g, const Sched& S, const Epi& E) {
;     ...
;             PG8_WAIT_V(8); PG8_WAIT_L(0); PG8_BAR; PG8_MMA(1, 0, At, B0); PG8_MMA(1, 1, At, B1); PG8_BAR; PG8_SCHED;
;             PG8_LDB(B0, 1, 0); PG8_LDB(B1, 1, 1); PG8_SCHED; PG8_LDA(At, 1, 0); PG8_STAGE(PG8_SA(0, 1), a2 + hstep, voffA);
;             PG8_WAIT_V(8); PG8_WAIT_L(0); PG8_BAR; PG8_MMA(0, 0, At, B0); PG8_MMA(0, 1, At, B1); PG8_BAR; PG8_SCHED;
	s_setprio 1
	s_add_i32 s64, 0, 0x18000
	s_add_i32 s65, 0, 0x1c000
	v_add_u32_e32 v144, s64, v167
	v_add_u32_e32 v179, s65, v167
	ds_read_b128 v[132:135], v144
	ds_read_b128 v[136:139], v144 offset:1024
	ds_read_b128 v[140:143], v144 offset:2048
	ds_read_b128 v[144:147], v144 offset:3072
	ds_read_b128 v[158:161], v179
	ds_read_b128 v[162:165], v179 offset:1024
	ds_read_b128 v[184:187], v179 offset:2048
	ds_read_b128 v[188:191], v179 offset:3072
	s_add_u32 s26, s26, 0x80000
	s_addc_u32 s27, s27, 0
	s_mov_b32 m0, s51
	v_lshl_add_u64 v[230:231], s[26:27], 0, v[152:153]
	ds_read_b128 v[192:195], v169 offset:32768
	ds_read_b128 v[196:199], v169 offset:33792
	ds_read_b128 v[200:203], v169 offset:34816
	ds_read_b128 v[204:207], v169 offset:35840
	ds_read_b128 v[208:211], v169 offset:36864
	ds_read_b128 v[212:215], v169 offset:37888
	ds_read_b128 v[216:219], v169 offset:38912
	ds_read_b128 v[220:223], v169 offset:39936
	global_load_lds_dwordx4 v[230:231], off
	v_lshl_add_u64 v[230:231], s[26:27], 0, v[150:151]
	s_mov_b32 m0, s52
	s_nop 0
	global_load_lds_dwordx4 v[230:231], off
	s_waitcnt vmcnt(8)
	s_waitcnt lgkmcnt(0)
	s_barrier
	s_setprio 0
	s_waitcnt lgkmcnt(0)
	v_mfma_f32_16x16x32_bf16 v[128:131], v[132:135], v[192:195], v[128:131]
	v_mfma_f32_16x16x32_bf16 v[124:127], v[140:143], v[192:195], v[124:127]
	v_mfma_f32_16x16x32_bf16 v[112:115], v[132:135], v[200:203], v[112:115]
	v_mfma_f32_16x16x32_bf16 v[108:111], v[140:143], v[200:203], v[108:111]
	v_mfma_f32_16x16x32_bf16 v[96:99], v[132:135], v[208:211], v[96:99]
	v_mfma_f32_16x16x32_bf16 v[92:95], v[140:143], v[208:211], v[92:95]
	v_mfma_f32_16x16x32_bf16 v[80:83], v[132:135], v[216:219], v[80:83]
	v_mfma_f32_16x16x32_bf16 v[76:79], v[140:143], v[216:219], v[76:79]
	v_mfma_f32_16x16x32_bf16 v[128:131], v[136:139], v[196:199], v[128:131]
	v_mfma_f32_16x16x32_bf16 v[124:127], v[144:147], v[196:199], v[124:127]
	v_mfma_f32_16x16x32_bf16 v[112:115], v[136:139], v[204:207], v[112:115]
	v_mfma_f32_16x16x32_bf16 v[108:111], v[144:147], v[204:207], v[108:111]
	v_mfma_f32_16x16x32_bf16 v[96:99], v[136:139], v[212:215], v[96:99]
	v_mfma_f32_16x16x32_bf16 v[92:95], v[144:147], v[212:215], v[92:95]
	v_mfma_f32_16x16x32_bf16 v[80:83], v[136:139], v[220:223], v[80:83]
	v_mfma_f32_16x16x32_bf16 v[76:79], v[144:147], v[220:223], v[76:79]
	v_mfma_f32_16x16x32_bf16 v[120:123], v[158:161], v[192:195], v[120:123]
	v_mfma_f32_16x16x32_bf16 v[116:119], v[184:187], v[192:195], v[116:119]
	v_mfma_f32_16x16x32_bf16 v[104:107], v[158:161], v[200:203], v[104:107]
	v_mfma_f32_16x16x32_bf16 v[100:103], v[184:187], v[200:203], v[100:103]
	v_mfma_f32_16x16x32_bf16 v[88:91], v[158:161], v[208:211], v[88:91]
	v_mfma_f32_16x16x32_bf16 v[84:87], v[184:187], v[208:211], v[84:87]
	v_mfma_f32_16x16x32_bf16 v[72:75], v[158:161], v[216:219], v[72:75]
	v_mfma_f32_16x16x32_bf16 v[68:71], v[184:187], v[216:219], v[68:71]
	v_mfma_f32_16x16x32_bf16 v[120:123], v[162:165], v[196:199], v[120:123]
	v_mfma_f32_16x16x32_bf16 v[116:119], v[188:191], v[196:199], v[116:119]
	v_mfma_f32_16x16x32_bf16 v[104:107], v[162:165], v[204:207], v[104:107]
	v_mfma_f32_16x16x32_bf16 v[100:103], v[188:191], v[204:207], v[100:103]
	v_mfma_f32_16x16x32_bf16 v[88:91], v[162:165], v[212:215], v[88:91]
	v_mfma_f32_16x16x32_bf16 v[84:87], v[188:191], v[212:215], v[84:87]
	v_mfma_f32_16x16x32_bf16 v[72:75], v[162:165], v[220:223], v[72:75]
	v_mfma_f32_16x16x32_bf16 v[68:71], v[188:191], v[220:223], v[68:71]
	s_barrier
; #define PG8_STAGE(bufoff, gbase, voff) do { _Pragma("unroll") for (int _i = 0; _i < 2; ++_i) \
;         __builtin_amdgcn_global_load_lds((const unsigned*)((const char*)(gbase) + (voff)[_i]), (PG8_LAS unsigned*)(lds + (bufoff) + ldsw + _i * 8192), 16, 0, 0); } while (0)
; #define PG8_LDA(dst, b, h) do { _Pragma("unroll") for (int m = 0; m < 4; ++m) _Pragma("unroll") for (int k = 0; k < 2; ++k) dst[m][k] = *(const PG8_LAS bf16x8*)(lds + PG8_SA(b, h) + aoff + m * 2048 + k * 1024); } while (0)
; #define PG8_MMA(ai, bj, At, Bt) do { __builtin_amdgcn_s_setprio(1); _Pragma("unroll") for (int m = 0; m < 4; ++m) _Pragma("unroll") for (int n = 0; n < 2; ++n) _Pragma("unroll") for (int k = 0; k < 2; ++k) \
;         acc[ai][bj][m][n] = __builtin_amdgcn_mfma_f32_16x16x32_bf16(Bt[n][k], At[m][k], acc[ai][bj][m][n], 0, 0, 0); __builtin_amdgcn_s_setprio(0); } while (0)
; #define PG8_WAIT_V(n) asm volatile("s_waitcnt vmcnt(" #n ")" ::: "memory")
; #define PG8_WAIT_L(n) asm volatile("s_waitcnt lgkmcnt(" #n ")" ::: "memory")
; #define PG8_BAR __builtin_amdgcn_s_barrier()
; #define PG8_SCHED __builtin_amdgcn_sched_barrier(0)
; template <class Epi, class Sched, bool ALIGN_EPI = false, bool SP2 = false>
; __device__ __forceinline__ void gemm_phase(PG8_LAS unsigned char* lds, const Gemm g, const Sched& S, const Epi& E) {
;     ...
;         for (int t = 0; t < nt; t += 2) {
;             const bool last = (t == nt - 2);
;             const char* a1 = cA + (size_t)(t + 1) * kstep;
;             const char* a2 = last ? nA : cA + (size_t)(t + 2) * kstep; const char* b2 = last ? nB : cB + (size_t)(t + 2) * kstep;
;             const char* a3 = a2 + kstep; const char* b3 = b2 + kstep;
;     ...
;             PG8_WAIT_V(8); PG8_WAIT_L(0); PG8_BAR; PG8_MMA(0, 0, At, B0); PG8_MMA(0, 1, At, B1); PG8_BAR; PG8_SCHED;
;             PG8_LDA(At, 1, 1); PG8_STAGE(PG8_SB(1, 0), b3, voffB); PG8_STAGE(PG8_SB(1, 1), b3 + hstep, voffB); PG8_STAGE(PG8_SA(1, 0), a3, voffA);
;             PG8_WAIT_V(8); PG8_WAIT_L(0); PG8_BAR; PG8_MMA(1, 0, At, B0); PG8_MMA(1, 1, At, B1); PG8_BAR; PG8_SCHED;
	s_setprio 1
	s_add_i32 s26, s64, s48
	v_lshl_add_u64 v[170:171], v[170:171], 0, s[10:11]
	s_mov_b32 m0, s26
	ds_read_b128 v[192:195], v169 offset:49152
	ds_read_b128 v[196:199], v169 offset:50176
	ds_read_b128 v[200:203], v169 offset:51200
	ds_read_b128 v[204:207], v169 offset:52224
	ds_read_b128 v[208:211], v169 offset:53248
	ds_read_b128 v[212:215], v169 offset:54272
	ds_read_b128 v[216:219], v169 offset:55296
	ds_read_b128 v[220:223], v169 offset:56320
	global_load_lds_dwordx4 v[170:171], off
	s_add_i32 m0, s26, 0x2000
	s_add_u32 s18, s18, 0x80080
	v_lshl_add_u64 v[170:171], v[224:225], 0, s[10:11]
	s_addc_u32 s19, s19, 0
	s_add_i32 s26, s65, s48
	global_load_lds_dwordx4 v[170:171], off
	v_lshl_add_u64 v[170:171], s[18:19], 0, v[174:175]
	s_mov_b32 m0, s26
	s_nop 0
	global_load_lds_dwordx4 v[170:171], off
	v_lshl_add_u64 v[170:171], s[18:19], 0, v[148:149]
	s_add_i32 m0, s26, 0x2000
	s_nop 0
	global_load_lds_dwordx4 v[170:171], off
	v_lshl_add_u64 v[170:171], v[226:227], 0, s[10:11]
	s_mov_b32 m0, s54
	s_nop 0
	global_load_lds_dwordx4 v[170:171], off
	v_lshl_add_u64 v[170:171], v[228:229], 0, s[10:11]
	s_mov_b32 m0, s55
	s_nop 0
	global_load_lds_dwordx4 v[170:171], off
	s_waitcnt vmcnt(8)
	s_waitcnt lgkmcnt(0)
	s_barrier
	s_setprio 0
	s_waitcnt lgkmcnt(0)
	v_mfma_f32_16x16x32_bf16 v[64:67], v[132:135], v[192:195], v[64:67]
	v_mfma_f32_16x16x32_bf16 v[60:63], v[140:143], v[192:195], v[60:63]
	v_mfma_f32_16x16x32_bf16 v[48:51], v[132:135], v[200:203], v[48:51]
	v_mfma_f32_16x16x32_bf16 v[44:47], v[140:143], v[200:203], v[44:47]
	v_mfma_f32_16x16x32_bf16 v[32:35], v[132:135], v[208:211], v[32:35]
	v_mfma_f32_16x16x32_bf16 v[28:31], v[140:143], v[208:211], v[28:31]
	v_mfma_f32_16x16x32_bf16 v[16:19], v[132:135], v[216:219], v[16:19]
	v_mfma_f32_16x16x32_bf16 v[12:15], v[140:143], v[216:219], v[12:15]
	v_mfma_f32_16x16x32_bf16 v[64:67], v[136:139], v[196:199], v[64:67]
	v_mfma_f32_16x16x32_bf16 v[60:63], v[144:147], v[196:199], v[60:63]
	v_mfma_f32_16x16x32_bf16 v[48:51], v[136:139], v[204:207], v[48:51]
	v_mfma_f32_16x16x32_bf16 v[44:47], v[144:147], v[204:207], v[44:47]
	v_mfma_f32_16x16x32_bf16 v[32:35], v[136:139], v[212:215], v[32:35]
	v_mfma_f32_16x16x32_bf16 v[28:31], v[144:147], v[212:215], v[28:31]
	v_mfma_f32_16x16x32_bf16 v[16:19], v[136:139], v[220:223], v[16:19]
	v_mfma_f32_16x16x32_bf16 v[12:15], v[144:147], v[220:223], v[12:15]
	v_mfma_f32_16x16x32_bf16 v[56:59], v[158:161], v[192:195], v[56:59]
	v_mfma_f32_16x16x32_bf16 v[52:55], v[184:187], v[192:195], v[52:55]
	v_mfma_f32_16x16x32_bf16 v[40:43], v[158:161], v[200:203], v[40:43]
	v_mfma_f32_16x16x32_bf16 v[36:39], v[184:187], v[200:203], v[36:39]
	v_mfma_f32_16x16x32_bf16 v[24:27], v[158:161], v[208:211], v[24:27]
	v_mfma_f32_16x16x32_bf16 v[20:23], v[184:187], v[208:211], v[20:23]
	v_mfma_f32_16x16x32_bf16 v[8:11], v[158:161], v[216:219], v[8:11]
	v_mfma_f32_16x16x32_bf16 v[4:7], v[184:187], v[216:219], v[4:7]
	v_mfma_f32_16x16x32_bf16 v[56:59], v[162:165], v[196:199], v[56:59]
	v_mfma_f32_16x16x32_bf16 v[52:55], v[188:191], v[196:199], v[52:55]
	v_mfma_f32_16x16x32_bf16 v[40:43], v[162:165], v[204:207], v[40:43]
	v_mfma_f32_16x16x32_bf16 v[36:39], v[188:191], v[204:207], v[36:39]
	v_mfma_f32_16x16x32_bf16 v[24:27], v[162:165], v[212:215], v[24:27]
	v_mfma_f32_16x16x32_bf16 v[20:23], v[188:191], v[212:215], v[20:23]
	v_mfma_f32_16x16x32_bf16 v[8:11], v[162:165], v[220:223], v[8:11]
	v_mfma_f32_16x16x32_bf16 v[4:7], v[188:191], v[220:223], v[4:7]
	s_barrier
	s_setprio 1
	s_add_i32 s63, s63, 2
	s_add_u32 s61, s61, 0x100
	s_addc_u32 s62, s62, 0
	s_add_u32 s0, s0, 0x100
	s_addc_u32 s1, s1, 0
	s_cmp_gt_u32 s63, 29
	s_cbranch_scc0 .LBB0_563
	s_and_b64 vcc, exec, s[34:35]
	s_cbranch_vccz .LBB0_566
	s_barrier

; #define PG8_STAGE(bufoff, gbase, voff) do { _Pragma("unroll") for (int _i = 0; _i < 2; ++_i) \
;         __builtin_amdgcn_global_load_lds((const unsigned*)((const char*)(gbase) + (voff)[_i]), (PG8_LAS unsigned*)(lds + (bufoff) + ldsw + _i * 8192), 16, 0, 0); } while (0)
; #define PG8_LDA(dst, b, h) do { _Pragma("unroll") for (int m = 0; m < 4; ++m) _Pragma("unroll") for (int k = 0; k < 2; ++k) dst[m][k] = *(const PG8_LAS bf16x8*)(lds + PG8_SA(b, h) + aoff + m * 2048 + k * 1024); } while (0)
; #define PG8_LDB(dst, b, h) do { _Pragma("unroll") for (int n = 0; n < 2; ++n) _Pragma("unroll") for (int k = 0; k < 2; ++k) dst[n][k] = *(const PG8_LAS bf16x8*)(lds + PG8_SB(b, h) + boff + n * 2048 + k * 1024); } while (0)
; #define PG8_WAIT_V(n) asm volatile("s_waitcnt vmcnt(" #n ")" ::: "memory")
; #define PG8_WAIT_L(n) asm volatile("s_waitcnt lgkmcnt(" #n ")" ::: "memory")
; #define PG8_BAR __builtin_amdgcn_s_barrier()
; template <class Epi, class Sched, bool ALIGN_EPI = false, bool SP2 = false>
; __device__ __forceinline__ void gemm_phase(PG8_LAS unsigned char* lds, const Gemm g, const Sched& S, const Epi& E) {
;     ...
;         const bool has_next = S.next(ui + 1, nxt);
;         const char* nA = has_next ? (const char*)g.A + (size_t)nxt.pm * tstep : cA; const char* nB = has_next ? (const char*)g.Bt + (size_t)nxt.pn * tstep : cB;
;         for (int t = 0; t < nt; t += 2) {
;             const bool last = (t == nt - 2);
;             const char* a1 = cA + (size_t)(t + 1) * kstep;
;             const char* a2 = last ? nA : cA + (size_t)(t + 2) * kstep; const char* b2 = last ? nB : cB + (size_t)(t + 2) * kstep;
;             const char* a3 = a2 + kstep; const char* b3 = b2 + kstep;
;             if (last && has_next) S.a_ready(nxt);
;             if constexpr (SP2) {
;             PG8_LDB(B0, 0, 0); PG8_LDB(B1, 0, 1); PG8_SCHED; PG8_LDA(At, 0, 0); PG8_STAGE(PG8_SA(1, 1), a1 + hstep, voffA);
;             PG8_WAIT_V(8); PG8_WAIT_L(0); PG8_BAR; PG8_MMA(0, 0, At, B0); PG8_MMA(0, 1, At, B1); PG8_BAR; PG8_SCHED;
;     ...
; #pragma unroll
;         for (int a = 0; a < 2; ++a)
; #pragma unroll
;             for (int b = 0; b < 2; ++b)
; #pragma unroll
;                 for (int m = 0; m < 4; ++m)
; #pragma unroll
;                     for (int n = 0; n < 2; ++n) acc[a][b][m][n] = (f32x4){0.f, 0.f, 0.f, 0.f};
;         cur = nxt; cA = nA; cB = nB; ++ui;
.LBB0_659:
	s_ashr_i32 s65, s64, 31
	s_lshl_b64 s[16:17], s[64:65], 20
	s_add_u32 s66, s19, s16
	s_addc_u32 s67, s20, s17
	s_and_b64 s[16:17], s[40:41], exec
	s_cselect_b32 s23, s67, s15
	s_cselect_b32 s24, s66, s14
	s_ashr_i32 s63, s62, 31
	s_lshl_b64 s[16:17], s[62:63], 20
	s_add_u32 s68, s26, s16
	s_addc_u32 s69, s27, s17
	s_and_b64 s[16:17], s[40:41], exec
	s_cselect_b32 s25, s69, s1
	s_cselect_b32 s42, s68, s0
	s_add_u32 s43, s0, 0x100
	s_addc_u32 s44, s1, 0
	s_add_u32 s0, s14, 0x80080
	v_mov_b32_e32 v4, 0
	s_addc_u32 s1, s15, 0
	s_mov_b32 s45, -2
	v_mov_b32_e32 v5, v4
	v_mov_b32_e32 v6, v4
	v_mov_b32_e32 v7, v4
	v_mov_b32_e32 v8, v4
	v_mov_b32_e32 v9, v4
	v_mov_b32_e32 v10, v4
	v_mov_b32_e32 v11, v4
	v_mov_b32_e32 v12, v4
	v_mov_b32_e32 v13, v4
	v_mov_b32_e32 v14, v4
	v_mov_b32_e32 v15, v4
	v_mov_b32_e32 v16, v4
	v_mov_b32_e32 v17, v4
	v_mov_b32_e32 v18, v4
	v_mov_b32_e32 v19, v4
	v_mov_b32_e32 v20, v4
	v_mov_b32_e32 v21, v4
	v_mov_b32_e32 v22, v4
	v_mov_b32_e32 v23, v4
	v_mov_b32_e32 v24, v4
	v_mov_b32_e32 v25, v4
	v_mov_b32_e32 v26, v4
	v_mov_b32_e32 v27, v4
	s_waitcnt vmcnt(0)
	v_mov_b32_e32 v28, v4
	v_mov_b32_e32 v29, v4
	v_mov_b32_e32 v30, v4
	v_mov_b32_e32 v31, v4
	v_mov_b32_e32 v32, v4
	v_mov_b32_e32 v33, v4
	v_mov_b32_e32 v34, v4
	v_mov_b32_e32 v35, v4
	v_mov_b32_e32 v88, v4
	v_mov_b32_e32 v89, v4
	v_mov_b32_e32 v90, v4
	v_mov_b32_e32 v91, v4
	v_mov_b32_e32 v92, v4
	v_mov_b32_e32 v93, v4
	v_mov_b32_e32 v94, v4
	v_mov_b32_e32 v95, v4
	v_mov_b32_e32 v52, v4
	v_mov_b32_e32 v53, v4
	v_mov_b32_e32 v54, v4
	v_mov_b32_e32 v55, v4
	v_mov_b32_e32 v56, v4
	v_mov_b32_e32 v57, v4
	v_mov_b32_e32 v58, v4
	v_mov_b32_e32 v59, v4
	v_mov_b32_e32 v60, v4
	v_mov_b32_e32 v61, v4
	v_mov_b32_e32 v62, v4
	v_mov_b32_e32 v63, v4
	v_mov_b32_e32 v64, v4
	v_mov_b32_e32 v65, v4
	v_mov_b32_e32 v66, v4
	v_mov_b32_e32 v67, v4
	v_mov_b32_e32 v68, v4
	v_mov_b32_e32 v69, v4
	v_mov_b32_e32 v70, v4
	v_mov_b32_e32 v71, v4
	v_mov_b32_e32 v72, v4
	v_mov_b32_e32 v73, v4
	v_mov_b32_e32 v74, v4
	v_mov_b32_e32 v75, v4
	v_mov_b32_e32 v100, v4
	v_mov_b32_e32 v101, v4
	v_mov_b32_e32 v102, v4
	v_mov_b32_e32 v103, v4
	v_mov_b32_e32 v104, v4
	v_mov_b32_e32 v105, v4
	v_mov_b32_e32 v106, v4
	v_mov_b32_e32 v107, v4
	v_mov_b32_e32 v108, v4
	v_mov_b32_e32 v109, v4
	v_mov_b32_e32 v110, v4
	v_mov_b32_e32 v111, v4
	v_mov_b32_e32 v112, v4
	v_mov_b32_e32 v113, v4
	v_mov_b32_e32 v114, v4
	v_mov_b32_e32 v115, v4
	v_mov_b32_e32 v116, v4
	v_mov_b32_e32 v117, v4
	v_mov_b32_e32 v118, v4
	v_mov_b32_e32 v119, v4
	v_mov_b32_e32 v120, v4
	v_mov_b32_e32 v121, v4
	v_mov_b32_e32 v122, v4
	v_mov_b32_e32 v123, v4
	v_mov_b32_e32 v140, v4
	v_mov_b32_e32 v141, v4
	v_mov_b32_e32 v142, v4
	v_mov_b32_e32 v143, v4
	v_mov_b32_e32 v144, v4
	v_mov_b32_e32 v145, v4
	v_mov_b32_e32 v146, v4
	v_mov_b32_e32 v147, v4
	v_mov_b32_e32 v156, v4
	v_mov_b32_e32 v157, v4
	v_mov_b32_e32 v158, v4
	v_mov_b32_e32 v159, v4
	v_mov_b32_e32 v160, v4
	v_mov_b32_e32 v161, v4
	v_mov_b32_e32 v162, v4
	v_mov_b32_e32 v163, v4
	v_mov_b32_e32 v124, v4
	v_mov_b32_e32 v125, v4
	v_mov_b32_e32 v126, v4
	v_mov_b32_e32 v127, v4
	v_mov_b32_e32 v128, v4
	v_mov_b32_e32 v129, v4
	v_mov_b32_e32 v130, v4
	v_mov_b32_e32 v131, v4
	v_mov_b32_e32 v132, v4
	v_mov_b32_e32 v133, v4
	v_mov_b32_e32 v134, v4
	v_mov_b32_e32 v135, v4
	v_mov_b32_e32 v136, v4
	v_mov_b32_e32 v137, v4
	v_mov_b32_e32 v138, v4
	v_mov_b32_e32 v139, v4
	v_mov_b32_e32 v148, v4
	v_mov_b32_e32 v149, v4
	v_mov_b32_e32 v150, v4
	v_mov_b32_e32 v151, v4
	v_mov_b32_e32 v152, v4
	v_mov_b32_e32 v153, v4
	v_mov_b32_e32 v154, v4
	v_mov_b32_e32 v155, v4
	s_setprio 1
.LBB0_660:
	s_add_u32 s14, s0, 0xfff80080
	s_addc_u32 s15, s1, -1
	s_add_i32 s46, 0, 0x10000
	s_cmp_eq_u32 s45, 28
	s_cselect_b32 s17, s23, s15
	s_cselect_b32 s16, s24, s14
	s_cselect_b32 s15, s25, s44
	s_cselect_b32 s14, s42, s43
	s_add_i32 s63, 0, 0x14000
	v_add_u32_e32 v48, s46, v243
	v_add_u32_e32 v96, s63, v243
	ds_read_b128 v[36:39], v48
	ds_read_b128 v[40:43], v48 offset:1024
	ds_read_b128 v[44:47], v48 offset:2048
	ds_read_b128 v[48:51], v48 offset:3072
	ds_read_b128 v[76:79], v96
	ds_read_b128 v[80:83], v96 offset:1024
	ds_read_b128 v[84:87], v96 offset:2048
	ds_read_b128 v[96:99], v96 offset:3072
	v_lshl_add_u64 v[224:225], s[0:1], 0, v[198:199]
	s_add_i32 m0, s29, 0xc000
	ds_read_b128 v[164:167], v249
	ds_read_b128 v[168:171], v249 offset:1024
	ds_read_b128 v[200:203], v249 offset:2048
	ds_read_b128 v[204:207], v249 offset:3072
	ds_read_b128 v[208:211], v249 offset:4096
	ds_read_b128 v[212:215], v249 offset:5120
	ds_read_b128 v[216:219], v249 offset:6144
	ds_read_b128 v[220:223], v249 offset:7168
	global_load_lds_dwordx4 v[224:225], off
	v_lshl_add_u64 v[224:225], s[0:1], 0, v[196:197]
	s_add_i32 m0, s29, 0xe000
	s_nop 0
	global_load_lds_dwordx4 v[224:225], off
	s_waitcnt vmcnt(8)
	s_waitcnt lgkmcnt(0)
	s_barrier
; #define PG8_STAGE(bufoff, gbase, voff) do { _Pragma("unroll") for (int _i = 0; _i < 2; ++_i) \
;         __builtin_amdgcn_global_load_lds((const unsigned*)((const char*)(gbase) + (voff)[_i]), (PG8_LAS unsigned*)(lds + (bufoff) + ldsw + _i * 8192), 16, 0, 0); } while (0)
; #define PG8_LDA(dst, b, h) do { _Pragma("unroll") for (int m = 0; m < 4; ++m) _Pragma("unroll") for (int k = 0; k < 2; ++k) dst[m][k] = *(const PG8_LAS bf16x8*)(lds + PG8_SA(b, h) + aoff + m * 2048 + k * 1024); } while (0)
; #define PG8_MMA(ai, bj, At, Bt) do { __builtin_amdgcn_s_setprio(1); _Pragma("unroll") for (int m = 0; m < 4; ++m) _Pragma("unroll") for (int n = 0; n < 2; ++n) _Pragma("unroll") for (int k = 0; k < 2; ++k) \
;         acc[ai][bj][m][n] = __builtin_amdgcn_mfma_f32_16x16x32_bf16(Bt[n][k], At[m][k], acc[ai][bj][m][n], 0, 0, 0); __builtin_amdgcn_s_setprio(0); } while (0)
; #define PG8_WAIT_V(n) asm volatile("s_waitcnt vmcnt(" #n ")" ::: "memory")
; #define PG8_WAIT_L(n) asm volatile("s_waitcnt lgkmcnt(" #n ")" ::: "memory")
; #define PG8_BAR __builtin_amdgcn_s_barrier()
; #define PG8_SCHED __builtin_amdgcn_sched_barrier(0)
; template <class Epi, class Sched, bool ALIGN_EPI = false, bool SP2 = false>
; __device__ __forceinline__ void gemm_phase(PG8_LAS unsigned char* lds, const Gemm g, const Sched& S, const Epi& E) {
;     ...
;             PG8_WAIT_V(8); PG8_WAIT_L(0); PG8_BAR; PG8_MMA(0, 0, At, B0); PG8_MMA(0, 1, At, B1); PG8_BAR; PG8_SCHED;
;             PG8_LDA(At, 0, 1); PG8_STAGE(PG8_SB(0, 0), b2, voffB); PG8_STAGE(PG8_SB(0, 1), b2 + hstep, voffB); PG8_STAGE(PG8_SA(0, 0), a2, voffA);
;             PG8_WAIT_V(8); PG8_WAIT_L(0); PG8_BAR; PG8_MMA(1, 0, At, B0); PG8_MMA(1, 1, At, B1); PG8_BAR; PG8_SCHED;
	s_setprio 0
	s_waitcnt lgkmcnt(0)
	v_mfma_f32_16x16x32_bf16 v[152:155], v[36:39], v[164:167], v[152:155]
	v_mfma_f32_16x16x32_bf16 v[148:151], v[44:47], v[164:167], v[148:151]
	v_mfma_f32_16x16x32_bf16 v[136:139], v[36:39], v[200:203], v[136:139]
	v_mfma_f32_16x16x32_bf16 v[132:135], v[44:47], v[200:203], v[132:135]
	v_mfma_f32_16x16x32_bf16 v[128:131], v[36:39], v[208:211], v[128:131]
	v_mfma_f32_16x16x32_bf16 v[124:127], v[44:47], v[208:211], v[124:127]
	v_mfma_f32_16x16x32_bf16 v[160:163], v[36:39], v[216:219], v[160:163]
	v_mfma_f32_16x16x32_bf16 v[156:159], v[44:47], v[216:219], v[156:159]
	v_mfma_f32_16x16x32_bf16 v[152:155], v[40:43], v[168:171], v[152:155]
	v_mfma_f32_16x16x32_bf16 v[148:151], v[48:51], v[168:171], v[148:151]
	v_mfma_f32_16x16x32_bf16 v[136:139], v[40:43], v[204:207], v[136:139]
	v_mfma_f32_16x16x32_bf16 v[132:135], v[48:51], v[204:207], v[132:135]
	v_mfma_f32_16x16x32_bf16 v[128:131], v[40:43], v[212:215], v[128:131]
	v_mfma_f32_16x16x32_bf16 v[124:127], v[48:51], v[212:215], v[124:127]
	v_mfma_f32_16x16x32_bf16 v[160:163], v[40:43], v[220:223], v[160:163]
	v_mfma_f32_16x16x32_bf16 v[156:159], v[48:51], v[220:223], v[156:159]
	v_mfma_f32_16x16x32_bf16 v[144:147], v[76:79], v[164:167], v[144:147]
	v_mfma_f32_16x16x32_bf16 v[140:143], v[84:87], v[164:167], v[140:143]
	v_mfma_f32_16x16x32_bf16 v[120:123], v[76:79], v[200:203], v[120:123]
	v_mfma_f32_16x16x32_bf16 v[116:119], v[84:87], v[200:203], v[116:119]
	v_mfma_f32_16x16x32_bf16 v[112:115], v[76:79], v[208:211], v[112:115]
	v_mfma_f32_16x16x32_bf16 v[108:111], v[84:87], v[208:211], v[108:111]
	v_mfma_f32_16x16x32_bf16 v[104:107], v[76:79], v[216:219], v[104:107]
	v_mfma_f32_16x16x32_bf16 v[100:103], v[84:87], v[216:219], v[100:103]
	v_mfma_f32_16x16x32_bf16 v[144:147], v[80:83], v[168:171], v[144:147]
	v_mfma_f32_16x16x32_bf16 v[140:143], v[96:99], v[168:171], v[140:143]
	v_mfma_f32_16x16x32_bf16 v[120:123], v[80:83], v[204:207], v[120:123]
	v_mfma_f32_16x16x32_bf16 v[116:119], v[96:99], v[204:207], v[116:119]
	v_mfma_f32_16x16x32_bf16 v[112:115], v[80:83], v[212:215], v[112:115]
	v_mfma_f32_16x16x32_bf16 v[108:111], v[96:99], v[212:215], v[108:111]
	v_mfma_f32_16x16x32_bf16 v[104:107], v[80:83], v[220:223], v[104:107]
	v_mfma_f32_16x16x32_bf16 v[100:103], v[96:99], v[220:223], v[100:103]
	s_barrier
	s_setprio 1
	s_add_i32 s46, s46, s28
	v_lshl_add_u64 v[232:233], s[14:15], 0, v[188:189]
	s_mov_b32 m0, s46
	ds_read_b128 v[164:167], v249 offset:16384
	ds_read_b128 v[168:171], v249 offset:17408
	ds_read_b128 v[200:203], v249 offset:18432
	ds_read_b128 v[204:207], v249 offset:19456
	ds_read_b128 v[208:211], v249 offset:20480
	ds_read_b128 v[212:215], v249 offset:21504
	ds_read_b128 v[216:219], v249 offset:22528
	ds_read_b128 v[220:223], v249 offset:23552
	global_load_lds_dwordx4 v[232:233], off
	s_add_i32 m0, s46, 0x2000
	s_add_u32 s46, s14, 0x80000
	v_lshl_add_u64 v[234:235], s[14:15], 0, v[184:185]
	s_addc_u32 s47, s15, 0
	s_add_i32 s63, s63, s28
	global_load_lds_dwordx4 v[234:235], off
	v_lshl_add_u64 v[224:225], s[46:47], 0, v[188:189]
	s_mov_b32 m0, s63
	v_lshl_add_u64 v[236:237], s[16:17], 0, v[190:191]
	global_load_lds_dwordx4 v[224:225], off
	v_lshl_add_u64 v[224:225], s[46:47], 0, v[184:185]
	s_add_i32 m0, s63, 0x2000
	v_lshl_add_u64 v[250:251], s[16:17], 0, v[186:187]
	global_load_lds_dwordx4 v[224:225], off
	s_mov_b32 m0, s29
	s_nop 0
	global_load_lds_dwordx4 v[236:237], off
	s_mov_b32 m0, s30
	s_nop 0
	global_load_lds_dwordx4 v[250:251], off
	s_waitcnt vmcnt(8)
	s_waitcnt lgkmcnt(0)
	s_barrier
	s_setprio 0
	s_waitcnt lgkmcnt(0)
	v_mfma_f32_16x16x32_bf16 v[72:75], v[36:39], v[164:167], v[72:75]
	v_mfma_f32_16x16x32_bf16 v[68:71], v[44:47], v[164:167], v[68:71]
	v_mfma_f32_16x16x32_bf16 v[64:67], v[36:39], v[200:203], v[64:67]
	v_mfma_f32_16x16x32_bf16 v[60:63], v[44:47], v[200:203], v[60:63]
	v_mfma_f32_16x16x32_bf16 v[56:59], v[36:39], v[208:211], v[56:59]
	v_mfma_f32_16x16x32_bf16 v[52:55], v[44:47], v[208:211], v[52:55]
	v_mfma_f32_16x16x32_bf16 v[36:39], v[36:39], v[216:219], v[92:95]
	v_mfma_f32_16x16x32_bf16 v[72:75], v[40:43], v[168:171], v[72:75]
	v_mfma_f32_16x16x32_bf16 v[68:71], v[48:51], v[168:171], v[68:71]
	v_mfma_f32_16x16x32_bf16 v[64:67], v[40:43], v[204:207], v[64:67]
	v_mfma_f32_16x16x32_bf16 v[60:63], v[48:51], v[204:207], v[60:63]
	v_mfma_f32_16x16x32_bf16 v[56:59], v[40:43], v[212:215], v[56:59]
	v_mfma_f32_16x16x32_bf16 v[52:55], v[48:51], v[212:215], v[52:55]
	v_mfma_f32_16x16x32_bf16 v[36:39], v[40:43], v[220:223], v[36:39]
	v_mfma_f32_16x16x32_bf16 v[40:43], v[44:47], v[216:219], v[88:91]
	v_mfma_f32_16x16x32_bf16 v[40:43], v[48:51], v[220:223], v[40:43]
	v_mfma_f32_16x16x32_bf16 v[32:35], v[76:79], v[164:167], v[32:35]
	v_mfma_f32_16x16x32_bf16 v[28:31], v[84:87], v[164:167], v[28:31]
	v_mfma_f32_16x16x32_bf16 v[24:27], v[76:79], v[200:203], v[24:27]
	v_mfma_f32_16x16x32_bf16 v[20:23], v[84:87], v[200:203], v[20:23]
	v_mfma_f32_16x16x32_bf16 v[16:19], v[76:79], v[208:211], v[16:19]
	v_mfma_f32_16x16x32_bf16 v[12:15], v[84:87], v[208:211], v[12:15]
	v_mfma_f32_16x16x32_bf16 v[8:11], v[76:79], v[216:219], v[8:11]
	v_mfma_f32_16x16x32_bf16 v[4:7], v[84:87], v[216:219], v[4:7]
	v_mfma_f32_16x16x32_bf16 v[32:35], v[80:83], v[168:171], v[32:35]
	v_mfma_f32_16x16x32_bf16 v[28:31], v[96:99], v[168:171], v[28:31]
	v_mfma_f32_16x16x32_bf16 v[24:27], v[80:83], v[204:207], v[24:27]
	v_mfma_f32_16x16x32_bf16 v[20:23], v[96:99], v[204:207], v[20:23]
	v_mfma_f32_16x16x32_bf16 v[16:19], v[80:83], v[212:215], v[16:19]
	v_mfma_f32_16x16x32_bf16 v[12:15], v[96:99], v[212:215], v[12:15]
	v_mfma_f32_16x16x32_bf16 v[8:11], v[80:83], v[220:223], v[8:11]
	v_mfma_f32_16x16x32_bf16 v[4:7], v[96:99], v[220:223], v[4:7]
	s_barrier
; #define PG8_STAGE(bufoff, gbase, voff) do { _Pragma("unroll") for (int _i = 0; _i < 2; ++_i) \
;         __builtin_amdgcn_global_load_lds((const unsigned*)((const char*)(gbase) + (voff)[_i]), (PG8_LAS unsigned*)(lds + (bufoff) + ldsw + _i * 8192), 16, 0, 0); } while (0)
; #define PG8_LDA(dst, b, h) do { _Pragma("unroll") for (int m = 0; m < 4; ++m) _Pragma("unroll") for (int k = 0; k < 2; ++k) dst[m][k] = *(const PG8_LAS bf16x8*)(lds + PG8_SA(b, h) + aoff + m * 2048 + k * 1024); } while (0)
; #define PG8_LDB(dst, b, h) do { _Pragma("unroll") for (int n = 0; n < 2; ++n) _Pragma("unroll") for (int k = 0; k < 2; ++k) dst[n][k] = *(const PG8_LAS bf16x8*)(lds + PG8_SB(b, h) + boff + n * 2048 + k * 1024); } while (0)
; #define PG8_MMA(ai, bj, At, Bt) do { __builtin_amdgcn_s_setprio(1); _Pragma("unroll") for (int m = 0; m < 4; ++m) _Pragma("unroll") for (int n = 0; n < 2; ++n) _Pragma("unroll") for (int k = 0; k < 2; ++k) \
;         acc[ai][bj][m][n] = __builtin_amdgcn_mfma_f32_16x16x32_bf16(Bt[n][k], At[m][k], acc[ai][bj][m][n], 0, 0, 0); __builtin_amdgcn_s_setprio(0); } while (0)
; #define PG8_WAIT_V(n) asm volatile("s_waitcnt vmcnt(" #n ")" ::: "memory")
; #define PG8_WAIT_L(n) asm volatile("s_waitcnt lgkmcnt(" #n ")" ::: "memory")
; #define PG8_BAR __builtin_amdgcn_s_barrier()
; #define PG8_SCHED __builtin_amdgcn_sched_barrier(0)
; template <class Epi, class Sched, bool ALIGN_EPI = false, bool SP2 = false>
; __device__ __forceinline__ void gemm_phase(PG8_LAS unsigned char* lds, const Gemm g, const Sched& S, const Epi& E) {
;     ...
;             PG8_WAIT_V(8); PG8_WAIT_L(0); PG8_BAR; PG8_MMA(1, 0, At, B0); PG8_MMA(1, 1, At, B1); PG8_BAR; PG8_SCHED;
;             PG8_LDB(B0, 1, 0); PG8_LDB(B1, 1, 1); PG8_SCHED; PG8_LDA(At, 1, 0); PG8_STAGE(PG8_SA(0, 1), a2 + hstep, voffA);
;             PG8_WAIT_V(8); PG8_WAIT_L(0); PG8_BAR; PG8_MMA(0, 0, At, B0); PG8_MMA(0, 1, At, B1); PG8_BAR; PG8_SCHED;
	s_setprio 1
	s_add_i32 s46, 0, 0x18000
	s_add_i32 s47, 0, 0x1c000
	v_add_u32_e32 v80, s46, v243
	v_add_u32_e32 v88, s47, v243
	ds_read_b128 v[44:47], v80
	ds_read_b128 v[48:51], v80 offset:1024
	ds_read_b128 v[76:79], v80 offset:2048
	ds_read_b128 v[80:83], v80 offset:3072
	ds_read_b128 v[84:87], v88
	ds_read_b128 v[96:99], v88 offset:1024
	ds_read_b128 v[164:167], v88 offset:2048
	ds_read_b128 v[168:171], v88 offset:3072
	s_add_u32 s16, s16, 0x80000
	s_addc_u32 s17, s17, 0
	s_mov_b32 m0, s31
	v_lshl_add_u64 v[224:225], s[16:17], 0, v[190:191]
	ds_read_b128 v[88:91], v249 offset:32768
	ds_read_b128 v[92:95], v249 offset:33792
	ds_read_b128 v[200:203], v249 offset:34816
	ds_read_b128 v[204:207], v249 offset:35840
	ds_read_b128 v[208:211], v249 offset:36864
	ds_read_b128 v[212:215], v249 offset:37888
	ds_read_b128 v[216:219], v249 offset:38912
	ds_read_b128 v[220:223], v249 offset:39936
	global_load_lds_dwordx4 v[224:225], off
	v_lshl_add_u64 v[224:225], s[16:17], 0, v[186:187]
	s_mov_b32 m0, s34
	s_nop 0
	global_load_lds_dwordx4 v[224:225], off
	s_waitcnt vmcnt(8)
	s_waitcnt lgkmcnt(0)
	s_barrier
	s_setprio 0
	s_waitcnt lgkmcnt(0)
	v_mfma_f32_16x16x32_bf16 v[152:155], v[44:47], v[88:91], v[152:155]
	v_mfma_f32_16x16x32_bf16 v[148:151], v[76:79], v[88:91], v[148:151]
	v_mfma_f32_16x16x32_bf16 v[136:139], v[44:47], v[200:203], v[136:139]
	v_mfma_f32_16x16x32_bf16 v[132:135], v[76:79], v[200:203], v[132:135]
	v_mfma_f32_16x16x32_bf16 v[128:131], v[44:47], v[208:211], v[128:131]
	v_mfma_f32_16x16x32_bf16 v[124:127], v[76:79], v[208:211], v[124:127]
	v_mfma_f32_16x16x32_bf16 v[160:163], v[44:47], v[216:219], v[160:163]
	v_mfma_f32_16x16x32_bf16 v[156:159], v[76:79], v[216:219], v[156:159]
	v_mfma_f32_16x16x32_bf16 v[152:155], v[48:51], v[92:95], v[152:155]
	v_mfma_f32_16x16x32_bf16 v[148:151], v[80:83], v[92:95], v[148:151]
	v_mfma_f32_16x16x32_bf16 v[136:139], v[48:51], v[204:207], v[136:139]
	v_mfma_f32_16x16x32_bf16 v[132:135], v[80:83], v[204:207], v[132:135]
	v_mfma_f32_16x16x32_bf16 v[128:131], v[48:51], v[212:215], v[128:131]
	v_mfma_f32_16x16x32_bf16 v[124:127], v[80:83], v[212:215], v[124:127]
	v_mfma_f32_16x16x32_bf16 v[160:163], v[48:51], v[220:223], v[160:163]
	v_mfma_f32_16x16x32_bf16 v[156:159], v[80:83], v[220:223], v[156:159]
	v_mfma_f32_16x16x32_bf16 v[144:147], v[84:87], v[88:91], v[144:147]
	v_mfma_f32_16x16x32_bf16 v[88:91], v[164:167], v[88:91], v[140:143]
	v_mfma_f32_16x16x32_bf16 v[140:143], v[168:171], v[92:95], v[88:91]
	v_mfma_f32_16x16x32_bf16 v[88:91], v[84:87], v[200:203], v[120:123]
	v_mfma_f32_16x16x32_bf16 v[120:123], v[96:99], v[204:207], v[88:91]
	v_mfma_f32_16x16x32_bf16 v[88:91], v[164:167], v[200:203], v[116:119]
	v_mfma_f32_16x16x32_bf16 v[116:119], v[168:171], v[204:207], v[88:91]
	v_mfma_f32_16x16x32_bf16 v[88:91], v[84:87], v[208:211], v[112:115]
	v_mfma_f32_16x16x32_bf16 v[112:115], v[96:99], v[212:215], v[88:91]
	v_mfma_f32_16x16x32_bf16 v[88:91], v[164:167], v[208:211], v[108:111]
	v_mfma_f32_16x16x32_bf16 v[108:111], v[168:171], v[212:215], v[88:91]
	v_mfma_f32_16x16x32_bf16 v[88:91], v[84:87], v[216:219], v[104:107]
	v_mfma_f32_16x16x32_bf16 v[104:107], v[96:99], v[220:223], v[88:91]
	v_mfma_f32_16x16x32_bf16 v[88:91], v[164:167], v[216:219], v[100:103]
	v_mfma_f32_16x16x32_bf16 v[144:147], v[96:99], v[92:95], v[144:147]
	v_mfma_f32_16x16x32_bf16 v[100:103], v[168:171], v[220:223], v[88:91]
	s_barrier
; #define PG8_STAGE(bufoff, gbase, voff) do { _Pragma("unroll") for (int _i = 0; _i < 2; ++_i) \
;         __builtin_amdgcn_global_load_lds((const unsigned*)((const char*)(gbase) + (voff)[_i]), (PG8_LAS unsigned*)(lds + (bufoff) + ldsw + _i * 8192), 16, 0, 0); } while (0)
; #define PG8_LDA(dst, b, h) do { _Pragma("unroll") for (int m = 0; m < 4; ++m) _Pragma("unroll") for (int k = 0; k < 2; ++k) dst[m][k] = *(const PG8_LAS bf16x8*)(lds + PG8_SA(b, h) + aoff + m * 2048 + k * 1024); } while (0)
; #define PG8_MMA(ai, bj, At, Bt) do { __builtin_amdgcn_s_setprio(1); _Pragma("unroll") for (int m = 0; m < 4; ++m) _Pragma("unroll") for (int n = 0; n < 2; ++n) _Pragma("unroll") for (int k = 0; k < 2; ++k) \
;         acc[ai][bj][m][n] = __builtin_amdgcn_mfma_f32_16x16x32_bf16(Bt[n][k], At[m][k], acc[ai][bj][m][n], 0, 0, 0); __builtin_amdgcn_s_setprio(0); } while (0)
; #define PG8_WAIT_V(n) asm volatile("s_waitcnt vmcnt(" #n ")" ::: "memory")
; #define PG8_WAIT_L(n) asm volatile("s_waitcnt lgkmcnt(" #n ")" ::: "memory")
; #define PG8_BAR __builtin_amdgcn_s_barrier()
; #define PG8_SCHED __builtin_amdgcn_sched_barrier(0)
; template <class Epi, class Sched, bool ALIGN_EPI = false, bool SP2 = false>
; __device__ __forceinline__ void gemm_phase(PG8_LAS unsigned char* lds, const Gemm g, const Sched& S, const Epi& E) {
;     ...
;         for (int t = 0; t < nt; t += 2) {
;             const bool last = (t == nt - 2);
;             const char* a1 = cA + (size_t)(t + 1) * kstep;
;             const char* a2 = last ? nA : cA + (size_t)(t + 2) * kstep; const char* b2 = last ? nB : cB + (size_t)(t + 2) * kstep;
;             const char* a3 = a2 + kstep; const char* b3 = b2 + kstep;
;     ...
;             PG8_WAIT_V(8); PG8_WAIT_L(0); PG8_BAR; PG8_MMA(0, 0, At, B0); PG8_MMA(0, 1, At, B1); PG8_BAR; PG8_SCHED;
;             PG8_LDA(At, 1, 1); PG8_STAGE(PG8_SB(1, 0), b3, voffB); PG8_STAGE(PG8_SB(1, 1), b3 + hstep, voffB); PG8_STAGE(PG8_SA(1, 0), a3, voffA);
;             PG8_WAIT_V(8); PG8_WAIT_L(0); PG8_BAR; PG8_MMA(1, 0, At, B0); PG8_MMA(1, 1, At, B1); PG8_BAR; PG8_SCHED;
	s_setprio 1
	s_add_i32 s16, s46, s28
	s_nop 2
	v_lshl_add_u64 v[88:89], v[232:233], 0, s[10:11]
	s_mov_b32 m0, s16
	ds_read_b128 v[200:203], v249 offset:49152
	ds_read_b128 v[204:207], v249 offset:50176
	ds_read_b128 v[208:211], v249 offset:51200
	ds_read_b128 v[212:215], v249 offset:52224
	ds_read_b128 v[216:219], v249 offset:53248
	ds_read_b128 v[220:223], v249 offset:54272
	ds_read_b128 v[224:227], v249 offset:55296
	ds_read_b128 v[228:231], v249 offset:56320
	global_load_lds_dwordx4 v[88:89], off
	s_add_i32 m0, s16, 0x2000
	s_add_u32 s14, s14, 0x80080
	v_lshl_add_u64 v[88:89], v[234:235], 0, s[10:11]
	s_addc_u32 s15, s15, 0
	s_add_i32 s16, s47, s28
	global_load_lds_dwordx4 v[88:89], off
	v_lshl_add_u64 v[88:89], s[14:15], 0, v[188:189]
	s_mov_b32 m0, s16
	s_nop 0
	global_load_lds_dwordx4 v[88:89], off
	v_lshl_add_u64 v[88:89], s[14:15], 0, v[184:185]
	s_add_i32 m0, s16, 0x2000
	s_nop 0
	global_load_lds_dwordx4 v[88:89], off
	v_lshl_add_u64 v[88:89], v[236:237], 0, s[10:11]
	s_mov_b32 m0, s72
	s_nop 0
	global_load_lds_dwordx4 v[88:89], off
	v_lshl_add_u64 v[88:89], v[250:251], 0, s[10:11]
	s_mov_b32 m0, s73
	s_nop 0
	global_load_lds_dwordx4 v[88:89], off
	s_waitcnt vmcnt(8)
	s_waitcnt lgkmcnt(0)
	s_barrier
	s_setprio 0
	s_waitcnt lgkmcnt(0)
	v_mfma_f32_16x16x32_bf16 v[36:39], v[44:47], v[224:227], v[36:39]
	v_mfma_f32_16x16x32_bf16 v[72:75], v[44:47], v[200:203], v[72:75]
	v_mfma_f32_16x16x32_bf16 v[68:71], v[76:79], v[200:203], v[68:71]
	v_mfma_f32_16x16x32_bf16 v[64:67], v[44:47], v[208:211], v[64:67]
	v_mfma_f32_16x16x32_bf16 v[60:63], v[76:79], v[208:211], v[60:63]
	v_mfma_f32_16x16x32_bf16 v[56:59], v[44:47], v[216:219], v[56:59]
	v_mfma_f32_16x16x32_bf16 v[52:55], v[76:79], v[216:219], v[52:55]
	v_mfma_f32_16x16x32_bf16 v[92:95], v[48:51], v[228:231], v[36:39]
	v_mfma_f32_16x16x32_bf16 v[36:39], v[76:79], v[224:227], v[40:43]
	v_mfma_f32_16x16x32_bf16 v[72:75], v[48:51], v[204:207], v[72:75]
	v_mfma_f32_16x16x32_bf16 v[68:71], v[80:83], v[204:207], v[68:71]
	v_mfma_f32_16x16x32_bf16 v[64:67], v[48:51], v[212:215], v[64:67]
	v_mfma_f32_16x16x32_bf16 v[60:63], v[80:83], v[212:215], v[60:63]
	v_mfma_f32_16x16x32_bf16 v[56:59], v[48:51], v[220:223], v[56:59]
	v_mfma_f32_16x16x32_bf16 v[52:55], v[80:83], v[220:223], v[52:55]
	v_mfma_f32_16x16x32_bf16 v[88:91], v[80:83], v[228:231], v[36:39]
	v_mfma_f32_16x16x32_bf16 v[32:35], v[84:87], v[200:203], v[32:35]
	v_mfma_f32_16x16x32_bf16 v[28:31], v[164:167], v[200:203], v[28:31]
	v_mfma_f32_16x16x32_bf16 v[24:27], v[84:87], v[208:211], v[24:27]
	v_mfma_f32_16x16x32_bf16 v[20:23], v[164:167], v[208:211], v[20:23]
	v_mfma_f32_16x16x32_bf16 v[16:19], v[84:87], v[216:219], v[16:19]
	v_mfma_f32_16x16x32_bf16 v[12:15], v[164:167], v[216:219], v[12:15]
	v_mfma_f32_16x16x32_bf16 v[8:11], v[84:87], v[224:227], v[8:11]
	v_mfma_f32_16x16x32_bf16 v[4:7], v[164:167], v[224:227], v[4:7]
	v_mfma_f32_16x16x32_bf16 v[32:35], v[96:99], v[204:207], v[32:35]
	v_mfma_f32_16x16x32_bf16 v[28:31], v[168:171], v[204:207], v[28:31]
	v_mfma_f32_16x16x32_bf16 v[24:27], v[96:99], v[212:215], v[24:27]
	v_mfma_f32_16x16x32_bf16 v[20:23], v[168:171], v[212:215], v[20:23]
	v_mfma_f32_16x16x32_bf16 v[16:19], v[96:99], v[220:223], v[16:19]
	v_mfma_f32_16x16x32_bf16 v[12:15], v[168:171], v[220:223], v[12:15]
	v_mfma_f32_16x16x32_bf16 v[8:11], v[96:99], v[228:231], v[8:11]
	v_mfma_f32_16x16x32_bf16 v[4:7], v[168:171], v[228:231], v[4:7]
	s_barrier
	s_setprio 1
	s_add_i32 s45, s45, 2
	s_add_u32 s43, s43, 0x100
	s_addc_u32 s44, s44, 0
	s_add_u32 s0, s0, 0x100
	s_addc_u32 s1, s1, 0
	s_cmp_gt_u32 s45, 29
	s_cbranch_scc0 .LBB0_660
	s_and_b64 vcc, exec, s[52:53]
	s_cbranch_vccz .LBB0_663
	s_barrier

; #define PG8_STAGE(bufoff, gbase, voff) do { _Pragma("unroll") for (int _i = 0; _i < 2; ++_i) \
;         __builtin_amdgcn_global_load_lds((const unsigned*)((const char*)(gbase) + (voff)[_i]), (PG8_LAS unsigned*)(lds + (bufoff) + ldsw + _i * 8192), 16, 0, 0); } while (0)
; #define PG8_LDA(dst, b, h) do { _Pragma("unroll") for (int m = 0; m < 4; ++m) _Pragma("unroll") for (int k = 0; k < 2; ++k) dst[m][k] = *(const PG8_LAS bf16x8*)(lds + PG8_SA(b, h) + aoff + m * 2048 + k * 1024); } while (0)
; #define PG8_LDB(dst, b, h) do { _Pragma("unroll") for (int n = 0; n < 2; ++n) _Pragma("unroll") for (int k = 0; k < 2; ++k) dst[n][k] = *(const PG8_LAS bf16x8*)(lds + PG8_SB(b, h) + boff + n * 2048 + k * 1024); } while (0)
; #define PG8_MMA(ai, bj, At, Bt) do { __builtin_amdgcn_s_setprio(1); _Pragma("unroll") for (int m = 0; m < 4; ++m) _Pragma("unroll") for (int n = 0; n < 2; ++n) _Pragma("unroll") for (int k = 0; k < 2; ++k) \
;         acc[ai][bj][m][n] = __builtin_amdgcn_mfma_f32_16x16x32_bf16(Bt[n][k], At[m][k], acc[ai][bj][m][n], 0, 0, 0); __builtin_amdgcn_s_setprio(0); } while (0)
; #define PG8_WAIT_V(n) asm volatile("s_waitcnt vmcnt(" #n ")" ::: "memory")
; #define PG8_BAR __builtin_amdgcn_s_barrier()
; template <class Epi, class Sched, bool ALIGN_EPI = false, bool SP2 = false>
; __device__ __forceinline__ void gemm_phase(PG8_LAS unsigned char* lds, const Gemm g, const Sched& S, const Epi& E) {
;     ...
;         for (int t = 0; t < nt; t += 2) {
;             const bool last = (t == nt - 2);
;             const char* a1 = cA + (size_t)(t + 1) * kstep;
;             const char* a2 = last ? nA : cA + (size_t)(t + 2) * kstep; const char* b2 = last ? nB : cB + (size_t)(t + 2) * kstep;
;             const char* a3 = a2 + kstep; const char* b3 = b2 + kstep;
;             if (last && has_next) S.a_ready(nxt);
;             if constexpr (SP2) {
;             PG8_LDB(B0, 0, 0); PG8_LDB(B1, 0, 1); PG8_SCHED; PG8_LDA(At, 0, 0); PG8_STAGE(PG8_SA(1, 1), a1 + hstep, voffA);
;             PG8_WAIT_V(8); PG8_WAIT_L(0); PG8_BAR; PG8_MMA(0, 0, At, B0); PG8_MMA(0, 1, At, B1); PG8_BAR; PG8_SCHED;
;     ...
; #pragma unroll
;         for (int a = 0; a < 2; ++a)
; #pragma unroll
;             for (int b = 0; b < 2; ++b)
; #pragma unroll
;                 for (int m = 0; m < 4; ++m)
; #pragma unroll
;                     for (int n = 0; n < 2; ++n) acc[a][b][m][n] = (f32x4){0.f, 0.f, 0.f, 0.f};
.LBB0_821:
	s_add_u32 s23, s14, 0x100
	v_mov_b32_e32 v4, 0
	s_addc_u32 s24, s15, 0
	s_mov_b32 s25, -2
	s_waitcnt lgkmcnt(0)
	v_mov_b32_e32 v5, v4
	v_mov_b32_e32 v6, v4
	v_mov_b32_e32 v7, v4
	v_mov_b32_e32 v8, v4
	v_mov_b32_e32 v9, v4
	v_mov_b32_e32 v10, v4
	v_mov_b32_e32 v11, v4
	v_mov_b32_e32 v20, v4
	v_mov_b32_e32 v21, v4
	v_mov_b32_e32 v22, v4
	v_mov_b32_e32 v23, v4
	v_mov_b32_e32 v24, v4
	v_mov_b32_e32 v25, v4
	v_mov_b32_e32 v26, v4
	v_mov_b32_e32 v27, v4
	s_waitcnt vmcnt(0)
	v_mov_b32_e32 v36, v4
	v_mov_b32_e32 v37, v4
	v_mov_b32_e32 v38, v4
	v_mov_b32_e32 v39, v4
	v_mov_b32_e32 v40, v4
	v_mov_b32_e32 v41, v4
	v_mov_b32_e32 v42, v4
	v_mov_b32_e32 v43, v4
	v_mov_b32_e32 v52, v4
	v_mov_b32_e32 v53, v4
	v_mov_b32_e32 v54, v4
	v_mov_b32_e32 v55, v4
	v_mov_b32_e32 v56, v4
	v_mov_b32_e32 v57, v4
	v_mov_b32_e32 v58, v4
	v_mov_b32_e32 v59, v4
	v_mov_b32_e32 v12, v4
	v_mov_b32_e32 v13, v4
	v_mov_b32_e32 v14, v4
	v_mov_b32_e32 v15, v4
	v_mov_b32_e32 v16, v4
	v_mov_b32_e32 v17, v4
	v_mov_b32_e32 v18, v4
	v_mov_b32_e32 v19, v4
	v_mov_b32_e32 v28, v4
	v_mov_b32_e32 v29, v4
	v_mov_b32_e32 v30, v4
	v_mov_b32_e32 v31, v4
	v_mov_b32_e32 v32, v4
	v_mov_b32_e32 v33, v4
	v_mov_b32_e32 v34, v4
	v_mov_b32_e32 v35, v4
	v_mov_b32_e32 v44, v4
	v_mov_b32_e32 v45, v4
	v_mov_b32_e32 v46, v4
	v_mov_b32_e32 v47, v4
	v_mov_b32_e32 v48, v4
	v_mov_b32_e32 v49, v4
	v_mov_b32_e32 v50, v4
	v_mov_b32_e32 v51, v4
	v_mov_b32_e32 v60, v4
	v_mov_b32_e32 v61, v4
	v_mov_b32_e32 v62, v4
	v_mov_b32_e32 v63, v4
	v_mov_b32_e32 v64, v4
	v_mov_b32_e32 v65, v4
	v_mov_b32_e32 v66, v4
	v_mov_b32_e32 v67, v4
	v_mov_b32_e32 v68, v4
	v_mov_b32_e32 v69, v4
	v_mov_b32_e32 v70, v4
	v_mov_b32_e32 v71, v4
	v_mov_b32_e32 v72, v4
	v_mov_b32_e32 v73, v4
	v_mov_b32_e32 v74, v4
	v_mov_b32_e32 v75, v4
	v_mov_b32_e32 v84, v4
	v_mov_b32_e32 v85, v4
	v_mov_b32_e32 v86, v4
	v_mov_b32_e32 v87, v4
	v_mov_b32_e32 v88, v4
	v_mov_b32_e32 v89, v4
	v_mov_b32_e32 v90, v4
	v_mov_b32_e32 v91, v4
	v_mov_b32_e32 v100, v4
	v_mov_b32_e32 v101, v4
	v_mov_b32_e32 v102, v4
	v_mov_b32_e32 v103, v4
	v_mov_b32_e32 v104, v4
	v_mov_b32_e32 v105, v4
	v_mov_b32_e32 v106, v4
	v_mov_b32_e32 v107, v4
	v_mov_b32_e32 v124, v4
	v_mov_b32_e32 v125, v4
	v_mov_b32_e32 v126, v4
	v_mov_b32_e32 v127, v4
	v_mov_b32_e32 v128, v4
	v_mov_b32_e32 v129, v4
	v_mov_b32_e32 v130, v4
	v_mov_b32_e32 v131, v4
	v_mov_b32_e32 v76, v4
	v_mov_b32_e32 v77, v4
	v_mov_b32_e32 v78, v4
	v_mov_b32_e32 v79, v4
	v_mov_b32_e32 v80, v4
	v_mov_b32_e32 v81, v4
	v_mov_b32_e32 v82, v4
	v_mov_b32_e32 v83, v4
	v_mov_b32_e32 v92, v4
	v_mov_b32_e32 v93, v4
	v_mov_b32_e32 v94, v4
	v_mov_b32_e32 v95, v4
	v_mov_b32_e32 v96, v4
	v_mov_b32_e32 v97, v4
	v_mov_b32_e32 v98, v4
	v_mov_b32_e32 v99, v4
	v_mov_b32_e32 v108, v4
	v_mov_b32_e32 v109, v4
	v_mov_b32_e32 v110, v4
	v_mov_b32_e32 v111, v4
	v_mov_b32_e32 v112, v4
	v_mov_b32_e32 v113, v4
	v_mov_b32_e32 v114, v4
	v_mov_b32_e32 v115, v4
	v_mov_b32_e32 v132, v4
	v_mov_b32_e32 v133, v4
	v_mov_b32_e32 v134, v4
	v_mov_b32_e32 v135, v4
	v_mov_b32_e32 v136, v4
	v_mov_b32_e32 v137, v4
	v_mov_b32_e32 v138, v4
	v_mov_b32_e32 v139, v4
	s_setprio 1
.LBB0_822:
	s_add_u32 s14, s0, 0x100
	s_addc_u32 s15, s1, 0
	s_add_i32 s60, 0, 0x10000
	s_cmpk_eq_i32 s25, 0x52
	s_cselect_b32 s19, s41, s15
	s_cselect_b32 s18, s40, s14
	s_cselect_b32 s17, s51, s24
	s_cselect_b32 s16, s50, s23
	s_add_i32 s61, 0, 0x14000
	v_add_u32_e32 v154, s60, v159
	v_add_u32_e32 v170, s61, v159
	ds_read_b128 v[116:119], v154
	ds_read_b128 v[120:123], v154 offset:1024
	ds_read_b128 v[150:153], v154 offset:2048
	ds_read_b128 v[154:157], v154 offset:3072
	ds_read_b128 v[162:165], v170
	ds_read_b128 v[166:169], v170 offset:1024
	ds_read_b128 v[184:187], v170 offset:2048
	ds_read_b128 v[188:191], v170 offset:3072
	v_lshl_add_u64 v[170:171], s[0:1], 0, v[148:149]
	s_add_i32 m0, s31, 0xc000
	ds_read_b128 v[192:195], v161
	ds_read_b128 v[196:199], v161 offset:1024
	ds_read_b128 v[200:203], v161 offset:2048
	ds_read_b128 v[204:207], v161 offset:3072
	ds_read_b128 v[208:211], v161 offset:4096
	ds_read_b128 v[212:215], v161 offset:5120
	ds_read_b128 v[216:219], v161 offset:6144
	ds_read_b128 v[220:223], v161 offset:7168
	global_load_lds_dwordx4 v[170:171], off
	v_lshl_add_u64 v[170:171], s[0:1], 0, v[146:147]
	s_add_i32 m0, s31, 0xe000
	s_nop 0
	global_load_lds_dwordx4 v[170:171], off
	s_waitcnt vmcnt(8)
	s_waitcnt lgkmcnt(0)
	s_barrier
	s_setprio 0
	s_waitcnt lgkmcnt(0)
	v_mfma_f32_16x16x32_bf16 v[136:139], v[116:119], v[192:195], v[136:139]
	v_mfma_f32_16x16x32_bf16 v[132:135], v[150:153], v[192:195], v[132:135]
	v_mfma_f32_16x16x32_bf16 v[112:115], v[116:119], v[200:203], v[112:115]
	v_mfma_f32_16x16x32_bf16 v[108:111], v[150:153], v[200:203], v[108:111]
	v_mfma_f32_16x16x32_bf16 v[96:99], v[116:119], v[208:211], v[96:99]
	v_mfma_f32_16x16x32_bf16 v[92:95], v[150:153], v[208:211], v[92:95]
	v_mfma_f32_16x16x32_bf16 v[80:83], v[116:119], v[216:219], v[80:83]
	v_mfma_f32_16x16x32_bf16 v[76:79], v[150:153], v[216:219], v[76:79]
	v_mfma_f32_16x16x32_bf16 v[136:139], v[120:123], v[196:199], v[136:139]
	v_mfma_f32_16x16x32_bf16 v[132:135], v[154:157], v[196:199], v[132:135]
	v_mfma_f32_16x16x32_bf16 v[112:115], v[120:123], v[204:207], v[112:115]
	v_mfma_f32_16x16x32_bf16 v[108:111], v[154:157], v[204:207], v[108:111]
	v_mfma_f32_16x16x32_bf16 v[96:99], v[120:123], v[212:215], v[96:99]
	v_mfma_f32_16x16x32_bf16 v[92:95], v[154:157], v[212:215], v[92:95]
	v_mfma_f32_16x16x32_bf16 v[80:83], v[120:123], v[220:223], v[80:83]
	v_mfma_f32_16x16x32_bf16 v[76:79], v[154:157], v[220:223], v[76:79]
	v_mfma_f32_16x16x32_bf16 v[128:131], v[162:165], v[192:195], v[128:131]
	v_mfma_f32_16x16x32_bf16 v[124:127], v[184:187], v[192:195], v[124:127]
	v_mfma_f32_16x16x32_bf16 v[104:107], v[162:165], v[200:203], v[104:107]
	v_mfma_f32_16x16x32_bf16 v[100:103], v[184:187], v[200:203], v[100:103]
	v_mfma_f32_16x16x32_bf16 v[88:91], v[162:165], v[208:211], v[88:91]
	v_mfma_f32_16x16x32_bf16 v[84:87], v[184:187], v[208:211], v[84:87]
	v_mfma_f32_16x16x32_bf16 v[72:75], v[162:165], v[216:219], v[72:75]
	v_mfma_f32_16x16x32_bf16 v[68:71], v[184:187], v[216:219], v[68:71]
	v_mfma_f32_16x16x32_bf16 v[128:131], v[166:169], v[196:199], v[128:131]
	v_mfma_f32_16x16x32_bf16 v[124:127], v[188:191], v[196:199], v[124:127]
	v_mfma_f32_16x16x32_bf16 v[104:107], v[166:169], v[204:207], v[104:107]
	v_mfma_f32_16x16x32_bf16 v[100:103], v[188:191], v[204:207], v[100:103]
	v_mfma_f32_16x16x32_bf16 v[88:91], v[166:169], v[212:215], v[88:91]
	v_mfma_f32_16x16x32_bf16 v[84:87], v[188:191], v[212:215], v[84:87]
	v_mfma_f32_16x16x32_bf16 v[72:75], v[166:169], v[220:223], v[72:75]
	v_mfma_f32_16x16x32_bf16 v[68:71], v[188:191], v[220:223], v[68:71]
	s_barrier
; #define PG8_STAGE(bufoff, gbase, voff) do { _Pragma("unroll") for (int _i = 0; _i < 2; ++_i) \
;         __builtin_amdgcn_global_load_lds((const unsigned*)((const char*)(gbase) + (voff)[_i]), (PG8_LAS unsigned*)(lds + (bufoff) + ldsw + _i * 8192), 16, 0, 0); } while (0)
; #define PG8_LDA(dst, b, h) do { _Pragma("unroll") for (int m = 0; m < 4; ++m) _Pragma("unroll") for (int k = 0; k < 2; ++k) dst[m][k] = *(const PG8_LAS bf16x8*)(lds + PG8_SA(b, h) + aoff + m * 2048 + k * 1024); } while (0)
; #define PG8_LDB(dst, b, h) do { _Pragma("unroll") for (int n = 0; n < 2; ++n) _Pragma("unroll") for (int k = 0; k < 2; ++k) dst[n][k] = *(const PG8_LAS bf16x8*)(lds + PG8_SB(b, h) + boff + n * 2048 + k * 1024); } while (0)
; #define PG8_MMA(ai, bj, At, Bt) do { __builtin_amdgcn_s_setprio(1); _Pragma("unroll") for (int m = 0; m < 4; ++m) _Pragma("unroll") for (int n = 0; n < 2; ++n) _Pragma("unroll") for (int k = 0; k < 2; ++k) \
;         acc[ai][bj][m][n] = __builtin_amdgcn_mfma_f32_16x16x32_bf16(Bt[n][k], At[m][k], acc[ai][bj][m][n], 0, 0, 0); __builtin_amdgcn_s_setprio(0); } while (0)
; #define PG8_WAIT_V(n) asm volatile("s_waitcnt vmcnt(" #n ")" ::: "memory")
; #define PG8_WAIT_L(n) asm volatile("s_waitcnt lgkmcnt(" #n ")" ::: "memory")
; #define PG8_BAR __builtin_amdgcn_s_barrier()
; #define PG8_SCHED __builtin_amdgcn_sched_barrier(0)
; template <class Epi, class Sched, bool ALIGN_EPI = false, bool SP2 = false>
; __device__ __forceinline__ void gemm_phase(PG8_LAS unsigned char* lds, const Gemm g, const Sched& S, const Epi& E) {
;     ...
;             PG8_WAIT_V(8); PG8_WAIT_L(0); PG8_BAR; PG8_MMA(0, 0, At, B0); PG8_MMA(0, 1, At, B1); PG8_BAR; PG8_SCHED;
;             PG8_LDA(At, 0, 1); PG8_STAGE(PG8_SB(0, 0), b2, voffB); PG8_STAGE(PG8_SB(0, 1), b2 + hstep, voffB); PG8_STAGE(PG8_SA(0, 0), a2, voffA);
;             PG8_WAIT_V(8); PG8_WAIT_L(0); PG8_BAR; PG8_MMA(1, 0, At, B0); PG8_MMA(1, 1, At, B1); PG8_BAR; PG8_SCHED;
;             PG8_LDB(B0, 1, 0); PG8_LDB(B1, 1, 1); PG8_SCHED; PG8_LDA(At, 1, 0); PG8_STAGE(PG8_SA(0, 1), a2 + hstep, voffA);
;             PG8_WAIT_V(8); PG8_WAIT_L(0); PG8_BAR; PG8_MMA(0, 0, At, B0); PG8_MMA(0, 1, At, B1); PG8_BAR; PG8_SCHED;
	s_setprio 1
	s_add_i32 s0, s60, s30
	v_lshl_add_u64 v[170:171], s[16:17], 0, v[174:175]
	s_mov_b32 m0, s0
	ds_read_b128 v[192:195], v161 offset:16384
	ds_read_b128 v[196:199], v161 offset:17408
	ds_read_b128 v[200:203], v161 offset:18432
	ds_read_b128 v[204:207], v161 offset:19456
	ds_read_b128 v[208:211], v161 offset:20480
	ds_read_b128 v[212:215], v161 offset:21504
	ds_read_b128 v[216:219], v161 offset:22528
	ds_read_b128 v[220:223], v161 offset:23552
	global_load_lds_dwordx4 v[170:171], off
	s_add_i32 m0, s0, 0x2000
	s_add_u32 s0, s16, 0x158000
	v_lshl_add_u64 v[224:225], s[16:17], 0, v[140:141]
	s_addc_u32 s1, s17, 0
	s_add_i32 s60, s61, s30
	global_load_lds_dwordx4 v[224:225], off
	v_lshl_add_u64 v[226:227], s[0:1], 0, v[174:175]
	s_mov_b32 m0, s60
	v_lshl_add_u64 v[228:229], s[18:19], 0, v[142:143]
	global_load_lds_dwordx4 v[226:227], off
	v_lshl_add_u64 v[226:227], s[0:1], 0, v[140:141]
	s_add_i32 m0, s60, 0x2000
	s_nop 0
	global_load_lds_dwordx4 v[226:227], off
	v_lshl_add_u64 v[226:227], s[18:19], 0, v[144:145]
	s_mov_b32 m0, s31
	s_nop 0
	global_load_lds_dwordx4 v[226:227], off
	s_mov_b32 m0, s34
	s_nop 0
	global_load_lds_dwordx4 v[228:229], off
	s_waitcnt vmcnt(8)
	s_waitcnt lgkmcnt(0)
	s_barrier
	s_setprio 0
	s_waitcnt lgkmcnt(0)
	v_mfma_f32_16x16x32_bf16 v[64:67], v[116:119], v[192:195], v[64:67]
	v_mfma_f32_16x16x32_bf16 v[60:63], v[150:153], v[192:195], v[60:63]
	v_mfma_f32_16x16x32_bf16 v[48:51], v[116:119], v[200:203], v[48:51]
	v_mfma_f32_16x16x32_bf16 v[44:47], v[150:153], v[200:203], v[44:47]
	v_mfma_f32_16x16x32_bf16 v[32:35], v[116:119], v[208:211], v[32:35]
	v_mfma_f32_16x16x32_bf16 v[28:31], v[150:153], v[208:211], v[28:31]
	v_mfma_f32_16x16x32_bf16 v[16:19], v[116:119], v[216:219], v[16:19]
	v_mfma_f32_16x16x32_bf16 v[12:15], v[150:153], v[216:219], v[12:15]
	v_mfma_f32_16x16x32_bf16 v[64:67], v[120:123], v[196:199], v[64:67]
	v_mfma_f32_16x16x32_bf16 v[60:63], v[154:157], v[196:199], v[60:63]
	v_mfma_f32_16x16x32_bf16 v[48:51], v[120:123], v[204:207], v[48:51]
	v_mfma_f32_16x16x32_bf16 v[44:47], v[154:157], v[204:207], v[44:47]
	v_mfma_f32_16x16x32_bf16 v[32:35], v[120:123], v[212:215], v[32:35]
	v_mfma_f32_16x16x32_bf16 v[28:31], v[154:157], v[212:215], v[28:31]
	v_mfma_f32_16x16x32_bf16 v[16:19], v[120:123], v[220:223], v[16:19]
	v_mfma_f32_16x16x32_bf16 v[12:15], v[154:157], v[220:223], v[12:15]
	v_mfma_f32_16x16x32_bf16 v[56:59], v[162:165], v[192:195], v[56:59]
	v_mfma_f32_16x16x32_bf16 v[52:55], v[184:187], v[192:195], v[52:55]
	v_mfma_f32_16x16x32_bf16 v[40:43], v[162:165], v[200:203], v[40:43]
	v_mfma_f32_16x16x32_bf16 v[36:39], v[184:187], v[200:203], v[36:39]
	v_mfma_f32_16x16x32_bf16 v[24:27], v[162:165], v[208:211], v[24:27]
	v_mfma_f32_16x16x32_bf16 v[20:23], v[184:187], v[208:211], v[20:23]
	v_mfma_f32_16x16x32_bf16 v[8:11], v[162:165], v[216:219], v[8:11]
	v_mfma_f32_16x16x32_bf16 v[4:7], v[184:187], v[216:219], v[4:7]
	v_mfma_f32_16x16x32_bf16 v[56:59], v[166:169], v[196:199], v[56:59]
	v_mfma_f32_16x16x32_bf16 v[52:55], v[188:191], v[196:199], v[52:55]
	v_mfma_f32_16x16x32_bf16 v[40:43], v[166:169], v[204:207], v[40:43]
	v_mfma_f32_16x16x32_bf16 v[36:39], v[188:191], v[204:207], v[36:39]
	v_mfma_f32_16x16x32_bf16 v[24:27], v[166:169], v[212:215], v[24:27]
	v_mfma_f32_16x16x32_bf16 v[20:23], v[188:191], v[212:215], v[20:23]
	v_mfma_f32_16x16x32_bf16 v[8:11], v[166:169], v[220:223], v[8:11]
	v_mfma_f32_16x16x32_bf16 v[4:7], v[188:191], v[220:223], v[4:7]
	s_barrier
	s_setprio 1
	s_add_i32 s60, 0, 0x18000
	s_add_i32 s61, 0, 0x1c000
	v_add_u32_e32 v154, s60, v159
	v_add_u32_e32 v179, s61, v159
	ds_read_b128 v[116:119], v154
	ds_read_b128 v[120:123], v154 offset:1024
	ds_read_b128 v[150:153], v154 offset:2048
	ds_read_b128 v[154:157], v154 offset:3072
	ds_read_b128 v[162:165], v179
	ds_read_b128 v[166:169], v179 offset:1024
	ds_read_b128 v[184:187], v179 offset:2048
	ds_read_b128 v[188:191], v179 offset:3072
	s_add_u32 s0, s18, 0x158000
	s_addc_u32 s1, s19, 0
	s_mov_b32 m0, s35
	v_lshl_add_u64 v[230:231], s[0:1], 0, v[144:145]
	ds_read_b128 v[192:195], v161 offset:32768
	ds_read_b128 v[196:199], v161 offset:33792
	ds_read_b128 v[200:203], v161 offset:34816
	ds_read_b128 v[204:207], v161 offset:35840
	ds_read_b128 v[208:211], v161 offset:36864
	ds_read_b128 v[212:215], v161 offset:37888
	ds_read_b128 v[216:219], v161 offset:38912
	ds_read_b128 v[220:223], v161 offset:39936
	global_load_lds_dwordx4 v[230:231], off
	v_lshl_add_u64 v[230:231], s[0:1], 0, v[142:143]
	s_mov_b32 m0, s52
	s_nop 0
	global_load_lds_dwordx4 v[230:231], off
	s_waitcnt vmcnt(8)
	s_waitcnt lgkmcnt(0)
	s_barrier
; #define PG8_STAGE(bufoff, gbase, voff) do { _Pragma("unroll") for (int _i = 0; _i < 2; ++_i) \
;         __builtin_amdgcn_global_load_lds((const unsigned*)((const char*)(gbase) + (voff)[_i]), (PG8_LAS unsigned*)(lds + (bufoff) + ldsw + _i * 8192), 16, 0, 0); } while (0)
; #define PG8_LDA(dst, b, h) do { _Pragma("unroll") for (int m = 0; m < 4; ++m) _Pragma("unroll") for (int k = 0; k < 2; ++k) dst[m][k] = *(const PG8_LAS bf16x8*)(lds + PG8_SA(b, h) + aoff + m * 2048 + k * 1024); } while (0)
; #define PG8_MMA(ai, bj, At, Bt) do { __builtin_amdgcn_s_setprio(1); _Pragma("unroll") for (int m = 0; m < 4; ++m) _Pragma("unroll") for (int n = 0; n < 2; ++n) _Pragma("unroll") for (int k = 0; k < 2; ++k) \
;         acc[ai][bj][m][n] = __builtin_amdgcn_mfma_f32_16x16x32_bf16(Bt[n][k], At[m][k], acc[ai][bj][m][n], 0, 0, 0); __builtin_amdgcn_s_setprio(0); } while (0)
; #define PG8_WAIT_V(n) asm volatile("s_waitcnt vmcnt(" #n ")" ::: "memory")
; #define PG8_WAIT_L(n) asm volatile("s_waitcnt lgkmcnt(" #n ")" ::: "memory")
; #define PG8_BAR __builtin_amdgcn_s_barrier()
; #define PG8_SCHED __builtin_amdgcn_sched_barrier(0)
; template <class Epi, class Sched, bool ALIGN_EPI = false, bool SP2 = false>
; __device__ __forceinline__ void gemm_phase(PG8_LAS unsigned char* lds, const Gemm g, const Sched& S, const Epi& E) {
;     ...
;             PG8_WAIT_V(8); PG8_WAIT_L(0); PG8_BAR; PG8_MMA(0, 0, At, B0); PG8_MMA(0, 1, At, B1); PG8_BAR; PG8_SCHED;
;             PG8_LDA(At, 1, 1); PG8_STAGE(PG8_SB(1, 0), b3, voffB); PG8_STAGE(PG8_SB(1, 1), b3 + hstep, voffB); PG8_STAGE(PG8_SA(1, 0), a3, voffA);
;             PG8_WAIT_V(8); PG8_WAIT_L(0); PG8_BAR; PG8_MMA(1, 0, At, B0); PG8_MMA(1, 1, At, B1); PG8_BAR; PG8_SCHED;
	s_setprio 0
	s_waitcnt lgkmcnt(0)
	v_mfma_f32_16x16x32_bf16 v[136:139], v[116:119], v[192:195], v[136:139]
	v_mfma_f32_16x16x32_bf16 v[132:135], v[150:153], v[192:195], v[132:135]
	v_mfma_f32_16x16x32_bf16 v[112:115], v[116:119], v[200:203], v[112:115]
	v_mfma_f32_16x16x32_bf16 v[108:111], v[150:153], v[200:203], v[108:111]
	v_mfma_f32_16x16x32_bf16 v[96:99], v[116:119], v[208:211], v[96:99]
	v_mfma_f32_16x16x32_bf16 v[92:95], v[150:153], v[208:211], v[92:95]
	v_mfma_f32_16x16x32_bf16 v[80:83], v[116:119], v[216:219], v[80:83]
	v_mfma_f32_16x16x32_bf16 v[76:79], v[150:153], v[216:219], v[76:79]
	v_mfma_f32_16x16x32_bf16 v[136:139], v[120:123], v[196:199], v[136:139]
	v_mfma_f32_16x16x32_bf16 v[132:135], v[154:157], v[196:199], v[132:135]
	v_mfma_f32_16x16x32_bf16 v[112:115], v[120:123], v[204:207], v[112:115]
	v_mfma_f32_16x16x32_bf16 v[108:111], v[154:157], v[204:207], v[108:111]
	v_mfma_f32_16x16x32_bf16 v[96:99], v[120:123], v[212:215], v[96:99]
	v_mfma_f32_16x16x32_bf16 v[92:95], v[154:157], v[212:215], v[92:95]
	v_mfma_f32_16x16x32_bf16 v[80:83], v[120:123], v[220:223], v[80:83]
	v_mfma_f32_16x16x32_bf16 v[76:79], v[154:157], v[220:223], v[76:79]
	v_mfma_f32_16x16x32_bf16 v[128:131], v[162:165], v[192:195], v[128:131]
	v_mfma_f32_16x16x32_bf16 v[124:127], v[184:187], v[192:195], v[124:127]
	v_mfma_f32_16x16x32_bf16 v[104:107], v[162:165], v[200:203], v[104:107]
	v_mfma_f32_16x16x32_bf16 v[100:103], v[184:187], v[200:203], v[100:103]
	v_mfma_f32_16x16x32_bf16 v[88:91], v[162:165], v[208:211], v[88:91]
	v_mfma_f32_16x16x32_bf16 v[84:87], v[184:187], v[208:211], v[84:87]
	v_mfma_f32_16x16x32_bf16 v[72:75], v[162:165], v[216:219], v[72:75]
	v_mfma_f32_16x16x32_bf16 v[68:71], v[184:187], v[216:219], v[68:71]
	v_mfma_f32_16x16x32_bf16 v[128:131], v[166:169], v[196:199], v[128:131]
	v_mfma_f32_16x16x32_bf16 v[124:127], v[188:191], v[196:199], v[124:127]
	v_mfma_f32_16x16x32_bf16 v[104:107], v[166:169], v[204:207], v[104:107]
	v_mfma_f32_16x16x32_bf16 v[100:103], v[188:191], v[204:207], v[100:103]
	v_mfma_f32_16x16x32_bf16 v[88:91], v[166:169], v[212:215], v[88:91]
	v_mfma_f32_16x16x32_bf16 v[84:87], v[188:191], v[212:215], v[84:87]
	v_mfma_f32_16x16x32_bf16 v[72:75], v[166:169], v[220:223], v[72:75]
	v_mfma_f32_16x16x32_bf16 v[68:71], v[188:191], v[220:223], v[68:71]
	s_barrier
	s_setprio 1
	s_add_i32 s0, s60, s30
	v_lshl_add_u64 v[170:171], v[170:171], 0, s[10:11]
	s_mov_b32 m0, s0
	ds_read_b128 v[192:195], v161 offset:49152
	ds_read_b128 v[196:199], v161 offset:50176
	ds_read_b128 v[200:203], v161 offset:51200
	ds_read_b128 v[204:207], v161 offset:52224
	ds_read_b128 v[208:211], v161 offset:53248
	ds_read_b128 v[212:215], v161 offset:54272
	ds_read_b128 v[216:219], v161 offset:55296
	ds_read_b128 v[220:223], v161 offset:56320
	global_load_lds_dwordx4 v[170:171], off
	s_add_i32 m0, s0, 0x2000
	s_add_u32 s0, s16, 0x158080
	v_lshl_add_u64 v[170:171], v[224:225], 0, s[10:11]
	s_addc_u32 s1, s17, 0
	s_add_i32 s16, s61, s30
	global_load_lds_dwordx4 v[170:171], off
	v_lshl_add_u64 v[170:171], s[0:1], 0, v[174:175]
	s_mov_b32 m0, s16
	s_nop 0
	global_load_lds_dwordx4 v[170:171], off
	v_lshl_add_u64 v[170:171], s[0:1], 0, v[140:141]
	s_add_i32 m0, s16, 0x2000
	s_nop 0
	global_load_lds_dwordx4 v[170:171], off
	v_lshl_add_u64 v[170:171], v[226:227], 0, s[10:11]
	s_mov_b32 m0, s54
	s_nop 0
	global_load_lds_dwordx4 v[170:171], off
	v_lshl_add_u64 v[170:171], v[228:229], 0, s[10:11]
	s_mov_b32 m0, s55
	s_nop 0
	global_load_lds_dwordx4 v[170:171], off
	s_waitcnt vmcnt(8)
	s_waitcnt lgkmcnt(0)
	s_barrier
	s_setprio 0
	s_waitcnt lgkmcnt(0)
	v_mfma_f32_16x16x32_bf16 v[64:67], v[116:119], v[192:195], v[64:67]
	v_mfma_f32_16x16x32_bf16 v[60:63], v[150:153], v[192:195], v[60:63]
	v_mfma_f32_16x16x32_bf16 v[48:51], v[116:119], v[200:203], v[48:51]
	v_mfma_f32_16x16x32_bf16 v[44:47], v[150:153], v[200:203], v[44:47]
	v_mfma_f32_16x16x32_bf16 v[32:35], v[116:119], v[208:211], v[32:35]
	v_mfma_f32_16x16x32_bf16 v[28:31], v[150:153], v[208:211], v[28:31]
	v_mfma_f32_16x16x32_bf16 v[16:19], v[116:119], v[216:219], v[16:19]
	v_mfma_f32_16x16x32_bf16 v[12:15], v[150:153], v[216:219], v[12:15]
	v_mfma_f32_16x16x32_bf16 v[64:67], v[120:123], v[196:199], v[64:67]
	v_mfma_f32_16x16x32_bf16 v[60:63], v[154:157], v[196:199], v[60:63]
	v_mfma_f32_16x16x32_bf16 v[48:51], v[120:123], v[204:207], v[48:51]
	v_mfma_f32_16x16x32_bf16 v[44:47], v[154:157], v[204:207], v[44:47]
	v_mfma_f32_16x16x32_bf16 v[32:35], v[120:123], v[212:215], v[32:35]
	v_mfma_f32_16x16x32_bf16 v[28:31], v[154:157], v[212:215], v[28:31]
	v_mfma_f32_16x16x32_bf16 v[16:19], v[120:123], v[220:223], v[16:19]
	v_mfma_f32_16x16x32_bf16 v[12:15], v[154:157], v[220:223], v[12:15]
	v_mfma_f32_16x16x32_bf16 v[56:59], v[162:165], v[192:195], v[56:59]
	v_mfma_f32_16x16x32_bf16 v[52:55], v[184:187], v[192:195], v[52:55]
	v_mfma_f32_16x16x32_bf16 v[40:43], v[162:165], v[200:203], v[40:43]
	v_mfma_f32_16x16x32_bf16 v[36:39], v[184:187], v[200:203], v[36:39]
	v_mfma_f32_16x16x32_bf16 v[24:27], v[162:165], v[208:211], v[24:27]
	v_mfma_f32_16x16x32_bf16 v[20:23], v[184:187], v[208:211], v[20:23]
	v_mfma_f32_16x16x32_bf16 v[8:11], v[162:165], v[216:219], v[8:11]
	v_mfma_f32_16x16x32_bf16 v[4:7], v[184:187], v[216:219], v[4:7]
	v_mfma_f32_16x16x32_bf16 v[56:59], v[166:169], v[196:199], v[56:59]
	v_mfma_f32_16x16x32_bf16 v[52:55], v[188:191], v[196:199], v[52:55]
	v_mfma_f32_16x16x32_bf16 v[40:43], v[166:169], v[204:207], v[40:43]
	v_mfma_f32_16x16x32_bf16 v[36:39], v[188:191], v[204:207], v[36:39]
	v_mfma_f32_16x16x32_bf16 v[24:27], v[166:169], v[212:215], v[24:27]
	v_mfma_f32_16x16x32_bf16 v[20:23], v[188:191], v[212:215], v[20:23]
	v_mfma_f32_16x16x32_bf16 v[8:11], v[166:169], v[220:223], v[8:11]
	v_mfma_f32_16x16x32_bf16 v[4:7], v[188:191], v[220:223], v[4:7]
	s_barrier
	s_setprio 1
	s_add_i32 s25, s25, 2
	s_add_u32 s23, s23, 0x100
	s_addc_u32 s24, s24, 0
	s_cmpk_gt_u32 s25, 0x53
	s_mov_b64 s[0:1], s[14:15]
	s_cbranch_scc0 .LBB0_822
	s_and_b64 vcc, exec, s[48:49]
	s_cbranch_vccz .LBB0_825
	s_barrier
